# adds: redundant post-barrier lgkmcnt(0) removed, s_setprio raise moved before the pre-MFMA barrier and the drop after the post-MFMA barrier
# speedup vs baseline: 1.0203x; 1.0003x over previous
;     __device__ __forceinline__ bool next(int i, Unit& u) const { const int off = i * H + (r >> 1); if (off >= 8 * nN) return false; u.pm = 16 * g + 8 * (r & 1) + (off & 7); u.pn = off >> 3; return true; }
; #define PG8_STAGE(bufoff, gbase, unused) do { _Pragma("unroll") for (int _i = 0; _i < 2; ++_i) \
;         __builtin_amdgcn_global_load_lds((const unsigned*)((const char*)(gbase) + voff + _i * 8192), (LAS unsigned*)(lds + (bufoff) + ldsw + _i * 8192), 16, 0, 0); } while (0)
; #define PG8_LDA(dst, b, h) do { _Pragma("unroll") for (int m = 0; m < 4; ++m) _Pragma("unroll") for (int k = 0; k < 2; ++k) dst[m][k] = *(const LAS bf16x8*)(lds + PG8_SA(b, h) + aoff + m * 2048 + (FP8 ? k * 16 : k * 1024)); } while (0)
; #define PG8_LDB(dst, b, h) do { _Pragma("unroll") for (int n = 0; n < 2; ++n) _Pragma("unroll") for (int k = 0; k < 2; ++k) dst[n][k] = *(const LAS bf16x8*)(lds + PG8_SB(b, h) + boff + n * 2048 + (FP8 ? k * 16 : k * 1024)); } while (0)
; #define PG8_BAR __builtin_amdgcn_s_barrier()
; template <class Epi, class Sched, bool ALIGN_EPI, bool SP2, int MODE  >
; __device__ __forceinline__ void gemm_phase(LAS unsigned char* lds, const Gemm g, const Sched S, const Epi E, unsigned long long& probe_acc, int epi_id, int wv) {
;     ...
;         const bool has_next = S.next(ui + 1, nxt);
;         const char* nA = has_next ? (const char*)g.A + (size_t)nxt.pm * tA + (g.gt ? (size_t)(nxt.pn / g.gt) * gK2 : 0) : cA; const char* nB = has_next ? (const char*)g.Bt + (size_t)nxt.pn * tB : cB;
;         for (int t = 0; t < nt; t += 2) {
;             const bool last = (t == nt - 2);
;             const char* a1 = cA + (size_t)(t + 1) * kstep;
;             const char* a2 = last ? nA : cA + (size_t)(t + 2) * kstep; const char* b2 = last ? nB : cB + (size_t)(t + 2) * kstep;
;             const char* a3 = a2 + kstep; const char* b3 = b2 + kstep;
;             if constexpr (SP2) {
;             PG8_LDB(B0, 0, 0); PG8_LDB(B1, 0, 1); PG8_SCHED; PG8_LDA(At, 0, 0); PG8_STAGE(PG8_SA(1, 1), a1 + hA, voffA);
;             PG8_WAIT_V(8); PG8_WAIT_L(0); PG8_BAR; PG8_MMA(0, 0, At, B0); PG8_MMA(0, 1, At, B1); PG8_BAR; PG8_SCHED;
;             PG8_LDA(At, 0, 1); PG8_STAGE(PG8_SB(0, 0), b2, voffB); PG8_STAGE(PG8_SB(0, 1), b2 + hB, voffB); PG8_STAGE(PG8_SA(0, 0), a2, voffA);
;             PG8_WAIT_V(8); PG8_WAIT_L(0); PG8_BAR; PG8_MMA(1, 0, At, B0); PG8_MMA(1, 1, At, B1); PG8_BAR; PG8_SCHED;
.LBB0_325:
	s_mov_b64 s[28:29], s[10:11]
	s_mov_b32 s11, s1
	s_mov_b32 s26, s1
	s_add_i32 s40, s40, 1
	v_readlane_b32 s1, v254, 6
	s_mov_b64 s[14:15], s[4:5]
	s_mul_i32 s1, s40, s1
	v_readlane_b32 s4, v254, 35
	s_add_i32 s1, s1, s4
	s_cmpk_lt_i32 s1, 0x160
	s_cselect_b64 s[24:25], -1, 0
	s_and_b32 s4, s1, 7
	v_readlane_b32 s5, v254, 18
	s_mov_b32 s10, s69
	s_mov_b32 s8, s69
	s_or_b32 s69, s4, s5
	s_ashr_i32 s1, s1, 3
	s_and_b64 s[4:5], s[24:25], exec
	s_cselect_b32 s10, s69, s10
	s_cselect_b32 s4, s1, s11
	s_ashr_i32 s11, s10, 31
	s_lshl_b64 s[10:11], s[10:11], 19
	s_add_u32 s10, s34, s10
	s_addc_u32 s11, s35, s11
	s_and_b64 s[16:17], s[24:25], exec
	s_cselect_b32 s27, s11, s29
	s_cselect_b32 s46, s10, s28
	s_ashr_i32 s5, s4, 31
	s_lshl_b64 s[4:5], s[4:5], 19
	s_add_u32 s4, s36, s4
	s_addc_u32 s5, s37, s5
	s_and_b64 s[16:17], s[24:25], exec
	s_cselect_b32 vcc_lo, s5, s15
	s_cselect_b32 vcc_hi, s4, s14
	s_add_u32 s16, s14, 0x8000
	s_addc_u32 s17, s15, 0
	s_mov_b32 s14, -2
	s_waitcnt lgkmcnt(0)
	v_add_u32_e32 v0, s39, v212
	ds_read_b128 v[132:135], v0
	ds_read_b128 v[136:139], v0 offset:1024
	ds_read_b128 v[140:143], v0 offset:2048
	ds_read_b128 v[144:147], v0 offset:3072
	v_add_u32_e32 v0, s65, v212
	ds_read_b128 v[148:151], v0
	ds_read_b128 v[152:155], v0 offset:1024
	ds_read_b128 v[156:159], v0 offset:2048
	ds_read_b128 v[160:163], v0 offset:3072
	s_add_u32 s30, s28, 0x8000
	s_addc_u32 s31, s29, 0
	s_cmp_eq_u32 s14, 12
	s_cselect_b32 s23, s27, s31
	s_cselect_b32 s22, s46, s30
	s_cselect_b32 s21, vcc_lo, s17
	s_cselect_b32 s20, vcc_hi, s16
	v_lshl_add_u64 v[184:185], s[28:29], 0, v[130:131]
	v_lshl_add_u64 v[204:205], v[184:185], 0, s[80:81]
	s_add_i32 m0, s85, 0xc000
	ds_read_b128 v[164:167], v213
	ds_read_b128 v[168:171], v213 offset:1024
	ds_read_b128 v[172:175], v213 offset:2048
	ds_read_b128 v[176:179], v213 offset:3072
	ds_read_b128 v[180:183], v213 offset:4096
	ds_read_b128 v[190:193], v213 offset:5120
	ds_read_b128 v[196:199], v213 offset:6144
	ds_read_b128 v[200:203], v213 offset:7168
	global_load_lds_dwordx4 v[204:205], off
	v_lshl_add_u64 v[184:185], v[184:185], 0, s[82:83]
	s_add_i32 m0, s85, 0xe000
	s_nop 0
	global_load_lds_dwordx4 v[184:185], off
	s_waitcnt vmcnt(8)
	s_waitcnt lgkmcnt(0)
	s_setprio 1
	s_barrier
	v_mfma_i32_16x16x64_i8 v[126:129], v[132:135], v[164:167], 0
	v_mfma_i32_16x16x64_i8 v[102:105], v[140:143], v[164:167], 0
	v_mfma_i32_16x16x64_i8 v[122:125], v[132:135], v[172:175], 0
	v_mfma_i32_16x16x64_i8 v[94:97], v[140:143], v[172:175], 0
	v_mfma_i32_16x16x64_i8 v[118:121], v[132:135], v[180:183], 0
	v_mfma_i32_16x16x64_i8 v[46:49], v[140:143], v[180:183], 0
	v_mfma_i32_16x16x64_i8 v[110:113], v[132:135], v[196:199], 0
	v_mfma_i32_16x16x64_i8 v[38:41], v[140:143], v[196:199], 0
	v_mfma_i32_16x16x64_i8 v[126:129], v[136:139], v[168:171], v[126:129]
	v_mfma_i32_16x16x64_i8 v[102:105], v[144:147], v[168:171], v[102:105]
	v_mfma_i32_16x16x64_i8 v[122:125], v[136:139], v[176:179], v[122:125]
	v_mfma_i32_16x16x64_i8 v[94:97], v[144:147], v[176:179], v[94:97]
	v_mfma_i32_16x16x64_i8 v[118:121], v[136:139], v[190:193], v[118:121]
	v_mfma_i32_16x16x64_i8 v[46:49], v[144:147], v[190:193], v[46:49]
	v_mfma_i32_16x16x64_i8 v[110:113], v[136:139], v[200:203], v[110:113]
	v_mfma_i32_16x16x64_i8 v[38:41], v[144:147], v[200:203], v[38:41]
	v_mfma_i32_16x16x64_i8 v[114:117], v[148:151], v[164:167], 0
	v_mfma_i32_16x16x64_i8 v[82:85], v[156:159], v[164:167], 0
	v_mfma_i32_16x16x64_i8 v[106:109], v[148:151], v[172:175], 0
	v_mfma_i32_16x16x64_i8 v[74:77], v[156:159], v[172:175], 0
	v_mfma_i32_16x16x64_i8 v[98:101], v[148:151], v[180:183], 0
	v_mfma_i32_16x16x64_i8 v[42:45], v[156:159], v[180:183], 0
	v_mfma_i32_16x16x64_i8 v[90:93], v[148:151], v[196:199], 0
	v_mfma_i32_16x16x64_i8 v[34:37], v[156:159], v[196:199], 0
	v_mfma_i32_16x16x64_i8 v[114:117], v[152:155], v[168:171], v[114:117]
	v_mfma_i32_16x16x64_i8 v[82:85], v[160:163], v[168:171], v[82:85]
	v_mfma_i32_16x16x64_i8 v[106:109], v[152:155], v[176:179], v[106:109]
	v_mfma_i32_16x16x64_i8 v[74:77], v[160:163], v[176:179], v[74:77]
	v_mfma_i32_16x16x64_i8 v[98:101], v[152:155], v[190:193], v[98:101]
	v_mfma_i32_16x16x64_i8 v[42:45], v[160:163], v[190:193], v[42:45]
	v_mfma_i32_16x16x64_i8 v[90:93], v[152:155], v[200:203], v[90:93]
	v_mfma_i32_16x16x64_i8 v[34:37], v[160:163], v[200:203], v[34:37]
	s_barrier
	s_setprio 0
	s_mov_b32 m0, s41
	v_lshl_add_u64 v[184:185], s[20:21], 0, v[130:131]
	ds_read_b128 v[164:167], v213 offset:16384
	ds_read_b128 v[168:171], v213 offset:17408
	ds_read_b128 v[172:175], v213 offset:18432
	ds_read_b128 v[176:179], v213 offset:19456
	ds_read_b128 v[180:183], v213 offset:20480
	ds_read_b128 v[190:193], v213 offset:21504
	ds_read_b128 v[196:199], v213 offset:22528
	ds_read_b128 v[200:203], v213 offset:23552
	global_load_lds_dwordx4 v[184:185], off
	v_lshl_add_u64 v[204:205], v[184:185], 0, s[70:71]
	s_mov_b32 m0, s64
	s_nop 0
	global_load_lds_dwordx4 v[204:205], off
	v_lshl_add_u64 v[204:205], v[184:185], 0, s[72:73]
	s_mov_b32 m0, s68
	s_nop 0
	global_load_lds_dwordx4 v[204:205], off
	v_lshl_add_u64 v[204:205], v[184:185], 0, s[74:75]
	s_mov_b32 m0, s84
	s_nop 0
	global_load_lds_dwordx4 v[204:205], off
	v_lshl_add_u64 v[204:205], s[22:23], 0, v[130:131]
	s_mov_b32 m0, s85
	v_lshl_add_u64 v[206:207], v[204:205], 0, s[70:71]
	global_load_lds_dwordx4 v[204:205], off
	s_mov_b32 m0, s86
	s_nop 0
	global_load_lds_dwordx4 v[206:207], off
	s_waitcnt vmcnt(8)
	s_waitcnt lgkmcnt(0)
	s_setprio 1
	s_barrier
; #define PG8_STAGE(bufoff, gbase, unused) do { _Pragma("unroll") for (int _i = 0; _i < 2; ++_i) \
;         __builtin_amdgcn_global_load_lds((const unsigned*)((const char*)(gbase) + voff + _i * 8192), (LAS unsigned*)(lds + (bufoff) + ldsw + _i * 8192), 16, 0, 0); } while (0)
; #define PG8_LDA(dst, b, h) do { _Pragma("unroll") for (int m = 0; m < 4; ++m) _Pragma("unroll") for (int k = 0; k < 2; ++k) dst[m][k] = *(const LAS bf16x8*)(lds + PG8_SA(b, h) + aoff + m * 2048 + (FP8 ? k * 16 : k * 1024)); } while (0)
; #define PG8_LDB(dst, b, h) do { _Pragma("unroll") for (int n = 0; n < 2; ++n) _Pragma("unroll") for (int k = 0; k < 2; ++k) dst[n][k] = *(const LAS bf16x8*)(lds + PG8_SB(b, h) + boff + n * 2048 + (FP8 ? k * 16 : k * 1024)); } while (0)
; #define PG8_WAIT_V(n) asm volatile("s_waitcnt vmcnt(" #n ")" ::: "memory")
; #define PG8_WAIT_L(n) asm volatile("s_waitcnt lgkmcnt(" #n ")" ::: "memory")
; #define PG8_BAR __builtin_amdgcn_s_barrier()
; #define PG8_SCHED __builtin_amdgcn_sched_barrier(0)
; template <class Epi, class Sched, bool ALIGN_EPI, bool SP2, int MODE  >
; __device__ __forceinline__ void gemm_phase(LAS unsigned char* lds, const Gemm g, const Sched S, const Epi E, unsigned long long& probe_acc, int epi_id, int wv) {
;     ...
;             PG8_WAIT_V(8); PG8_WAIT_L(0); PG8_BAR; PG8_MMA(1, 0, At, B0); PG8_MMA(1, 1, At, B1); PG8_BAR; PG8_SCHED;
;             PG8_LDB(B0, 1, 0); PG8_LDB(B1, 1, 1); PG8_SCHED; PG8_LDA(At, 1, 0); PG8_STAGE(PG8_SA(0, 1), a2 + hA, voffA);
;             PG8_WAIT_V(8); PG8_WAIT_L(0); PG8_BAR; PG8_MMA(0, 0, At, B0); PG8_MMA(0, 1, At, B1); PG8_BAR; PG8_SCHED;
	v_mfma_i32_16x16x64_i8 v[86:89], v[132:135], v[164:167], 0
	v_mfma_i32_16x16x64_i8 v[30:33], v[140:143], v[164:167], 0
	v_mfma_i32_16x16x64_i8 v[78:81], v[132:135], v[172:175], 0
	v_mfma_i32_16x16x64_i8 v[22:25], v[140:143], v[172:175], 0
	v_mfma_i32_16x16x64_i8 v[70:73], v[132:135], v[180:183], 0
	v_mfma_i32_16x16x64_i8 v[14:17], v[140:143], v[180:183], 0
	v_mfma_i32_16x16x64_i8 v[62:65], v[132:135], v[196:199], 0
	v_mfma_i32_16x16x64_i8 v[2:5], v[140:143], v[196:199], 0
	v_mfma_i32_16x16x64_i8 v[86:89], v[136:139], v[168:171], v[86:89]
	v_mfma_i32_16x16x64_i8 v[30:33], v[144:147], v[168:171], v[30:33]
	v_mfma_i32_16x16x64_i8 v[78:81], v[136:139], v[176:179], v[78:81]
	v_mfma_i32_16x16x64_i8 v[22:25], v[144:147], v[176:179], v[22:25]
	v_mfma_i32_16x16x64_i8 v[70:73], v[136:139], v[190:193], v[70:73]
	v_mfma_i32_16x16x64_i8 v[14:17], v[144:147], v[190:193], v[14:17]
	v_mfma_i32_16x16x64_i8 v[62:65], v[136:139], v[200:203], v[62:65]
	v_mfma_i32_16x16x64_i8 v[2:5], v[144:147], v[200:203], v[2:5]
	v_mfma_i32_16x16x64_i8 v[66:69], v[148:151], v[164:167], 0
	v_mfma_i32_16x16x64_i8 v[26:29], v[156:159], v[164:167], 0
	v_mfma_i32_16x16x64_i8 v[58:61], v[148:151], v[172:175], 0
	v_mfma_i32_16x16x64_i8 v[18:21], v[156:159], v[172:175], 0
	v_mfma_i32_16x16x64_i8 v[54:57], v[148:151], v[180:183], 0
	v_mfma_i32_16x16x64_i8 v[10:13], v[156:159], v[180:183], 0
	v_mfma_i32_16x16x64_i8 v[50:53], v[148:151], v[196:199], 0
	v_mfma_i32_16x16x64_i8 v[6:9], v[156:159], v[196:199], 0
	v_mfma_i32_16x16x64_i8 v[66:69], v[152:155], v[168:171], v[66:69]
	v_mfma_i32_16x16x64_i8 v[26:29], v[160:163], v[168:171], v[26:29]
	v_mfma_i32_16x16x64_i8 v[58:61], v[152:155], v[176:179], v[58:61]
	v_mfma_i32_16x16x64_i8 v[18:21], v[160:163], v[176:179], v[18:21]
	v_mfma_i32_16x16x64_i8 v[54:57], v[152:155], v[190:193], v[54:57]
	v_mfma_i32_16x16x64_i8 v[10:13], v[160:163], v[190:193], v[10:13]
	v_mfma_i32_16x16x64_i8 v[50:53], v[152:155], v[200:203], v[50:53]
	v_mfma_i32_16x16x64_i8 v[6:9], v[160:163], v[200:203], v[6:9]
	s_barrier
	s_setprio 0
	v_add_u32_e32 v0, s90, v212
	ds_read_b128 v[132:135], v0
	ds_read_b128 v[136:139], v0 offset:1024
	ds_read_b128 v[140:143], v0 offset:2048
	ds_read_b128 v[144:147], v0 offset:3072
	v_add_u32_e32 v0, s95, v212
	ds_read_b128 v[148:151], v0
	ds_read_b128 v[152:155], v0 offset:1024
	ds_read_b128 v[156:159], v0 offset:2048
	ds_read_b128 v[160:163], v0 offset:3072
	s_mov_b32 m0, s87
	v_lshl_add_u64 v[206:207], v[204:205], 0, s[72:73]
	ds_read_b128 v[164:167], v213 offset:32768
	ds_read_b128 v[168:171], v213 offset:33792
	ds_read_b128 v[172:175], v213 offset:34816
	ds_read_b128 v[176:179], v213 offset:35840
	ds_read_b128 v[180:183], v213 offset:36864
	ds_read_b128 v[190:193], v213 offset:37888
	ds_read_b128 v[196:199], v213 offset:38912
	ds_read_b128 v[200:203], v213 offset:39936
	global_load_lds_dwordx4 v[206:207], off
	v_lshl_add_u64 v[206:207], v[204:205], 0, s[74:75]
	s_mov_b32 m0, s88
	s_nop 0
	global_load_lds_dwordx4 v[206:207], off
	s_waitcnt vmcnt(8)
	s_waitcnt lgkmcnt(0)
	s_setprio 1
	s_barrier
	v_mfma_i32_16x16x64_i8 v[126:129], v[132:135], v[164:167], v[126:129]
	v_mfma_i32_16x16x64_i8 v[102:105], v[140:143], v[164:167], v[102:105]
	v_mfma_i32_16x16x64_i8 v[122:125], v[132:135], v[172:175], v[122:125]
	v_mfma_i32_16x16x64_i8 v[94:97], v[140:143], v[172:175], v[94:97]
	v_mfma_i32_16x16x64_i8 v[118:121], v[132:135], v[180:183], v[118:121]
	v_mfma_i32_16x16x64_i8 v[46:49], v[140:143], v[180:183], v[46:49]
	v_mfma_i32_16x16x64_i8 v[110:113], v[132:135], v[196:199], v[110:113]
	v_mfma_i32_16x16x64_i8 v[38:41], v[140:143], v[196:199], v[38:41]
	v_mfma_i32_16x16x64_i8 v[126:129], v[136:139], v[168:171], v[126:129]
	v_mfma_i32_16x16x64_i8 v[102:105], v[144:147], v[168:171], v[102:105]
	v_mfma_i32_16x16x64_i8 v[122:125], v[136:139], v[176:179], v[122:125]
	v_mfma_i32_16x16x64_i8 v[94:97], v[144:147], v[176:179], v[94:97]
	v_mfma_i32_16x16x64_i8 v[118:121], v[136:139], v[190:193], v[118:121]
	v_mfma_i32_16x16x64_i8 v[46:49], v[144:147], v[190:193], v[46:49]
	v_mfma_i32_16x16x64_i8 v[110:113], v[136:139], v[200:203], v[110:113]
	v_mfma_i32_16x16x64_i8 v[38:41], v[144:147], v[200:203], v[38:41]
	v_mfma_i32_16x16x64_i8 v[114:117], v[148:151], v[164:167], v[114:117]
	v_mfma_i32_16x16x64_i8 v[82:85], v[156:159], v[164:167], v[82:85]
	v_mfma_i32_16x16x64_i8 v[106:109], v[148:151], v[172:175], v[106:109]
	v_mfma_i32_16x16x64_i8 v[74:77], v[156:159], v[172:175], v[74:77]
	v_mfma_i32_16x16x64_i8 v[98:101], v[148:151], v[180:183], v[98:101]
	v_mfma_i32_16x16x64_i8 v[42:45], v[156:159], v[180:183], v[42:45]
	v_mfma_i32_16x16x64_i8 v[90:93], v[148:151], v[196:199], v[90:93]
	v_mfma_i32_16x16x64_i8 v[34:37], v[156:159], v[196:199], v[34:37]
	v_mfma_i32_16x16x64_i8 v[114:117], v[152:155], v[168:171], v[114:117]
	v_mfma_i32_16x16x64_i8 v[82:85], v[160:163], v[168:171], v[82:85]
	v_mfma_i32_16x16x64_i8 v[106:109], v[152:155], v[176:179], v[106:109]
	v_mfma_i32_16x16x64_i8 v[74:77], v[160:163], v[176:179], v[74:77]
	v_mfma_i32_16x16x64_i8 v[98:101], v[152:155], v[190:193], v[98:101]
	v_mfma_i32_16x16x64_i8 v[42:45], v[160:163], v[190:193], v[42:45]
	v_mfma_i32_16x16x64_i8 v[90:93], v[152:155], v[200:203], v[90:93]
	v_mfma_i32_16x16x64_i8 v[34:37], v[160:163], v[200:203], v[34:37]
	s_barrier
; #define PG8_STAGE(bufoff, gbase, unused) do { _Pragma("unroll") for (int _i = 0; _i < 2; ++_i) \
;         __builtin_amdgcn_global_load_lds((const unsigned*)((const char*)(gbase) + voff + _i * 8192), (LAS unsigned*)(lds + (bufoff) + ldsw + _i * 8192), 16, 0, 0); } while (0)
; #define PG8_LDA(dst, b, h) do { _Pragma("unroll") for (int m = 0; m < 4; ++m) _Pragma("unroll") for (int k = 0; k < 2; ++k) dst[m][k] = *(const LAS bf16x8*)(lds + PG8_SA(b, h) + aoff + m * 2048 + (FP8 ? k * 16 : k * 1024)); } while (0)
; #define PG8_LDB(dst, b, h) do { _Pragma("unroll") for (int n = 0; n < 2; ++n) _Pragma("unroll") for (int k = 0; k < 2; ++k) dst[n][k] = *(const LAS bf16x8*)(lds + PG8_SB(b, h) + boff + n * 2048 + (FP8 ? k * 16 : k * 1024)); } while (0)
; #define PG8_WAIT_V(n) asm volatile("s_waitcnt vmcnt(" #n ")" ::: "memory")
; #define PG8_WAIT_L(n) asm volatile("s_waitcnt lgkmcnt(" #n ")" ::: "memory")
; #define PG8_BAR __builtin_amdgcn_s_barrier()
; #define PG8_SCHED __builtin_amdgcn_sched_barrier(0)
; template <class Epi, class Sched, bool ALIGN_EPI, bool SP2, int MODE  >
; __device__ __forceinline__ void gemm_phase(LAS unsigned char* lds, const Gemm g, const Sched S, const Epi E, unsigned long long& probe_acc, int epi_id, int wv) {
;     ...
;         for (int t = 0; t < nt; t += 2) {
;             const bool last = (t == nt - 2);
;             const char* a1 = cA + (size_t)(t + 1) * kstep;
;             const char* a2 = last ? nA : cA + (size_t)(t + 2) * kstep; const char* b2 = last ? nB : cB + (size_t)(t + 2) * kstep;
;             const char* a3 = a2 + kstep; const char* b3 = b2 + kstep;
;             if constexpr (SP2) {
;             PG8_LDB(B0, 0, 0); PG8_LDB(B1, 0, 1); PG8_SCHED; PG8_LDA(At, 0, 0); PG8_STAGE(PG8_SA(1, 1), a1 + hA, voffA);
;             PG8_WAIT_V(8); PG8_WAIT_L(0); PG8_BAR; PG8_MMA(0, 0, At, B0); PG8_MMA(0, 1, At, B1); PG8_BAR; PG8_SCHED;
;     ...
;             PG8_LDA(At, 1, 1); PG8_STAGE(PG8_SB(1, 0), b3, voffB); PG8_STAGE(PG8_SB(1, 1), b3 + hB, voffB); PG8_STAGE(PG8_SA(1, 0), a3, voffA);
;             PG8_WAIT_V(8); PG8_WAIT_L(0); PG8_BAR; PG8_MMA(1, 0, At, B0); PG8_MMA(1, 1, At, B1); PG8_BAR; PG8_SCHED;
	s_setprio 0
	s_mov_b32 m0, s91
	v_lshl_add_u64 v[206:207], v[184:185], 0, s[76:77]
	ds_read_b128 v[164:167], v213 offset:49152
	ds_read_b128 v[168:171], v213 offset:50176
	ds_read_b128 v[172:175], v213 offset:51200
	ds_read_b128 v[176:179], v213 offset:52224
	ds_read_b128 v[180:183], v213 offset:53248
	ds_read_b128 v[190:193], v213 offset:54272
	ds_read_b128 v[196:199], v213 offset:55296
	ds_read_b128 v[200:203], v213 offset:56320
	global_load_lds_dwordx4 v[206:207], off
	v_lshl_add_u64 v[206:207], v[184:185], 0, s[78:79]
	s_mov_b32 m0, s92
	s_nop 0
	global_load_lds_dwordx4 v[206:207], off
	v_lshl_add_u64 v[206:207], v[184:185], 0, s[80:81]
	s_mov_b32 m0, s2
	v_lshl_add_u64 v[184:185], v[184:185], 0, s[82:83]
	global_load_lds_dwordx4 v[206:207], off
	s_mov_b32 m0, s3
	s_nop 0
	global_load_lds_dwordx4 v[184:185], off
	v_lshl_add_u64 v[184:185], v[204:205], 0, s[76:77]
	s_mov_b32 m0, s93
	s_nop 0
	global_load_lds_dwordx4 v[184:185], off
	v_lshl_add_u64 v[184:185], v[204:205], 0, s[78:79]
	s_mov_b32 m0, s94
	s_nop 0
	global_load_lds_dwordx4 v[184:185], off
	s_waitcnt vmcnt(8)
	s_waitcnt lgkmcnt(0)
	s_setprio 1
	s_barrier
	v_mfma_i32_16x16x64_i8 v[86:89], v[132:135], v[164:167], v[86:89]
	v_mfma_i32_16x16x64_i8 v[30:33], v[140:143], v[164:167], v[30:33]
	v_mfma_i32_16x16x64_i8 v[78:81], v[132:135], v[172:175], v[78:81]
	v_mfma_i32_16x16x64_i8 v[22:25], v[140:143], v[172:175], v[22:25]
	v_mfma_i32_16x16x64_i8 v[70:73], v[132:135], v[180:183], v[70:73]
	v_mfma_i32_16x16x64_i8 v[14:17], v[140:143], v[180:183], v[14:17]
	v_mfma_i32_16x16x64_i8 v[62:65], v[132:135], v[196:199], v[62:65]
	v_mfma_i32_16x16x64_i8 v[2:5], v[140:143], v[196:199], v[2:5]
	v_mfma_i32_16x16x64_i8 v[86:89], v[136:139], v[168:171], v[86:89]
	v_mfma_i32_16x16x64_i8 v[30:33], v[144:147], v[168:171], v[30:33]
	v_mfma_i32_16x16x64_i8 v[78:81], v[136:139], v[176:179], v[78:81]
	v_mfma_i32_16x16x64_i8 v[22:25], v[144:147], v[176:179], v[22:25]
	v_mfma_i32_16x16x64_i8 v[70:73], v[136:139], v[190:193], v[70:73]
	v_mfma_i32_16x16x64_i8 v[14:17], v[144:147], v[190:193], v[14:17]
	v_mfma_i32_16x16x64_i8 v[62:65], v[136:139], v[200:203], v[62:65]
	v_mfma_i32_16x16x64_i8 v[2:5], v[144:147], v[200:203], v[2:5]
	v_mfma_i32_16x16x64_i8 v[66:69], v[148:151], v[164:167], v[66:69]
	v_mfma_i32_16x16x64_i8 v[26:29], v[156:159], v[164:167], v[26:29]
	v_mfma_i32_16x16x64_i8 v[58:61], v[148:151], v[172:175], v[58:61]
	v_mfma_i32_16x16x64_i8 v[18:21], v[156:159], v[172:175], v[18:21]
	v_mfma_i32_16x16x64_i8 v[54:57], v[148:151], v[180:183], v[54:57]
	v_mfma_i32_16x16x64_i8 v[10:13], v[156:159], v[180:183], v[10:13]
	v_mfma_i32_16x16x64_i8 v[50:53], v[148:151], v[196:199], v[50:53]
	v_mfma_i32_16x16x64_i8 v[6:9], v[156:159], v[196:199], v[6:9]
	v_mfma_i32_16x16x64_i8 v[66:69], v[152:155], v[168:171], v[66:69]
	v_mfma_i32_16x16x64_i8 v[26:29], v[160:163], v[168:171], v[26:29]
	v_mfma_i32_16x16x64_i8 v[58:61], v[152:155], v[176:179], v[58:61]
	v_mfma_i32_16x16x64_i8 v[18:21], v[160:163], v[176:179], v[18:21]
	v_mfma_i32_16x16x64_i8 v[54:57], v[152:155], v[190:193], v[54:57]
	v_mfma_i32_16x16x64_i8 v[10:13], v[160:163], v[190:193], v[10:13]
	v_mfma_i32_16x16x64_i8 v[50:53], v[152:155], v[200:203], v[50:53]
	v_mfma_i32_16x16x64_i8 v[6:9], v[160:163], v[200:203], v[6:9]
	s_barrier
	s_setprio 0
	s_add_i32 s14, s14, 2
	s_add_u32 s16, s16, 0x8000
	s_addc_u32 s17, s17, 0
	s_cmp_gt_u32 s14, 13
	s_mov_b64 s[28:29], s[30:31]
.LBB0_326:
	v_add_u32_e32 v0, s39, v212
	ds_read_b128 v[132:135], v0
	ds_read_b128 v[136:139], v0 offset:1024
	ds_read_b128 v[140:143], v0 offset:2048
	ds_read_b128 v[144:147], v0 offset:3072
	v_add_u32_e32 v0, s65, v212
	ds_read_b128 v[148:151], v0
	ds_read_b128 v[152:155], v0 offset:1024
	ds_read_b128 v[156:159], v0 offset:2048
	ds_read_b128 v[160:163], v0 offset:3072
	s_add_u32 s30, s28, 0x8000
	s_addc_u32 s31, s29, 0
	s_cmp_eq_u32 s14, 12
	s_cselect_b32 s23, s27, s31
	s_cselect_b32 s22, s46, s30
	s_cselect_b32 s21, vcc_lo, s17
	s_cselect_b32 s20, vcc_hi, s16
	v_lshl_add_u64 v[184:185], s[28:29], 0, v[130:131]
	v_lshl_add_u64 v[204:205], v[184:185], 0, s[80:81]
	s_add_i32 m0, s85, 0xc000
	ds_read_b128 v[164:167], v213
	ds_read_b128 v[168:171], v213 offset:1024
	ds_read_b128 v[172:175], v213 offset:2048
	ds_read_b128 v[176:179], v213 offset:3072
	ds_read_b128 v[180:183], v213 offset:4096
	ds_read_b128 v[190:193], v213 offset:5120
	ds_read_b128 v[196:199], v213 offset:6144
	ds_read_b128 v[200:203], v213 offset:7168
	global_load_lds_dwordx4 v[204:205], off
	v_lshl_add_u64 v[184:185], v[184:185], 0, s[82:83]
	s_add_i32 m0, s85, 0xe000
	s_nop 0
	global_load_lds_dwordx4 v[184:185], off
	s_waitcnt vmcnt(8)
	s_waitcnt lgkmcnt(0)
	s_setprio 1
	s_barrier
; #define PG8_STAGE(bufoff, gbase, unused) do { _Pragma("unroll") for (int _i = 0; _i < 2; ++_i) \
;         __builtin_amdgcn_global_load_lds((const unsigned*)((const char*)(gbase) + voff + _i * 8192), (LAS unsigned*)(lds + (bufoff) + ldsw + _i * 8192), 16, 0, 0); } while (0)
; #define PG8_LDA(dst, b, h) do { _Pragma("unroll") for (int m = 0; m < 4; ++m) _Pragma("unroll") for (int k = 0; k < 2; ++k) dst[m][k] = *(const LAS bf16x8*)(lds + PG8_SA(b, h) + aoff + m * 2048 + (FP8 ? k * 16 : k * 1024)); } while (0)
; #define PG8_WAIT_V(n) asm volatile("s_waitcnt vmcnt(" #n ")" ::: "memory")
; #define PG8_WAIT_L(n) asm volatile("s_waitcnt lgkmcnt(" #n ")" ::: "memory")
; #define PG8_BAR __builtin_amdgcn_s_barrier()
; #define PG8_SCHED __builtin_amdgcn_sched_barrier(0)
; template <class Epi, class Sched, bool ALIGN_EPI, bool SP2, int MODE  >
; __device__ __forceinline__ void gemm_phase(LAS unsigned char* lds, const Gemm g, const Sched S, const Epi E, unsigned long long& probe_acc, int epi_id, int wv) {
;     ...
;             PG8_WAIT_V(8); PG8_WAIT_L(0); PG8_BAR; PG8_MMA(0, 0, At, B0); PG8_MMA(0, 1, At, B1); PG8_BAR; PG8_SCHED;
;             PG8_LDA(At, 0, 1); PG8_STAGE(PG8_SB(0, 0), b2, voffB); PG8_STAGE(PG8_SB(0, 1), b2 + hB, voffB); PG8_STAGE(PG8_SA(0, 0), a2, voffA);
;             PG8_WAIT_V(8); PG8_WAIT_L(0); PG8_BAR; PG8_MMA(1, 0, At, B0); PG8_MMA(1, 1, At, B1); PG8_BAR; PG8_SCHED;
	v_mfma_i32_16x16x64_i8 v[126:129], v[132:135], v[164:167], v[126:129]
	v_mfma_i32_16x16x64_i8 v[102:105], v[140:143], v[164:167], v[102:105]
	v_mfma_i32_16x16x64_i8 v[122:125], v[132:135], v[172:175], v[122:125]
	v_mfma_i32_16x16x64_i8 v[94:97], v[140:143], v[172:175], v[94:97]
	v_mfma_i32_16x16x64_i8 v[118:121], v[132:135], v[180:183], v[118:121]
	v_mfma_i32_16x16x64_i8 v[46:49], v[140:143], v[180:183], v[46:49]
	v_mfma_i32_16x16x64_i8 v[110:113], v[132:135], v[196:199], v[110:113]
	v_mfma_i32_16x16x64_i8 v[38:41], v[140:143], v[196:199], v[38:41]
	v_mfma_i32_16x16x64_i8 v[126:129], v[136:139], v[168:171], v[126:129]
	v_mfma_i32_16x16x64_i8 v[102:105], v[144:147], v[168:171], v[102:105]
	v_mfma_i32_16x16x64_i8 v[122:125], v[136:139], v[176:179], v[122:125]
	v_mfma_i32_16x16x64_i8 v[94:97], v[144:147], v[176:179], v[94:97]
	v_mfma_i32_16x16x64_i8 v[118:121], v[136:139], v[190:193], v[118:121]
	v_mfma_i32_16x16x64_i8 v[46:49], v[144:147], v[190:193], v[46:49]
	v_mfma_i32_16x16x64_i8 v[110:113], v[136:139], v[200:203], v[110:113]
	v_mfma_i32_16x16x64_i8 v[38:41], v[144:147], v[200:203], v[38:41]
	v_mfma_i32_16x16x64_i8 v[114:117], v[148:151], v[164:167], v[114:117]
	v_mfma_i32_16x16x64_i8 v[82:85], v[156:159], v[164:167], v[82:85]
	v_mfma_i32_16x16x64_i8 v[106:109], v[148:151], v[172:175], v[106:109]
	v_mfma_i32_16x16x64_i8 v[74:77], v[156:159], v[172:175], v[74:77]
	v_mfma_i32_16x16x64_i8 v[98:101], v[148:151], v[180:183], v[98:101]
	v_mfma_i32_16x16x64_i8 v[42:45], v[156:159], v[180:183], v[42:45]
	v_mfma_i32_16x16x64_i8 v[90:93], v[148:151], v[196:199], v[90:93]
	v_mfma_i32_16x16x64_i8 v[34:37], v[156:159], v[196:199], v[34:37]
	v_mfma_i32_16x16x64_i8 v[114:117], v[152:155], v[168:171], v[114:117]
	v_mfma_i32_16x16x64_i8 v[82:85], v[160:163], v[168:171], v[82:85]
	v_mfma_i32_16x16x64_i8 v[106:109], v[152:155], v[176:179], v[106:109]
	v_mfma_i32_16x16x64_i8 v[74:77], v[160:163], v[176:179], v[74:77]
	v_mfma_i32_16x16x64_i8 v[98:101], v[152:155], v[190:193], v[98:101]
	v_mfma_i32_16x16x64_i8 v[42:45], v[160:163], v[190:193], v[42:45]
	v_mfma_i32_16x16x64_i8 v[90:93], v[152:155], v[200:203], v[90:93]
	v_mfma_i32_16x16x64_i8 v[34:37], v[160:163], v[200:203], v[34:37]
	s_barrier
	s_setprio 0
	s_mov_b32 m0, s41
	v_lshl_add_u64 v[184:185], s[20:21], 0, v[130:131]
	ds_read_b128 v[164:167], v213 offset:16384
	ds_read_b128 v[168:171], v213 offset:17408
	ds_read_b128 v[172:175], v213 offset:18432
	ds_read_b128 v[176:179], v213 offset:19456
	ds_read_b128 v[180:183], v213 offset:20480
	ds_read_b128 v[190:193], v213 offset:21504
	ds_read_b128 v[196:199], v213 offset:22528
	ds_read_b128 v[200:203], v213 offset:23552
	global_load_lds_dwordx4 v[184:185], off
	v_lshl_add_u64 v[204:205], v[184:185], 0, s[70:71]
	s_mov_b32 m0, s64
	s_nop 0
	global_load_lds_dwordx4 v[204:205], off
	v_lshl_add_u64 v[204:205], v[184:185], 0, s[72:73]
	s_mov_b32 m0, s68
	s_nop 0
	global_load_lds_dwordx4 v[204:205], off
	v_lshl_add_u64 v[204:205], v[184:185], 0, s[74:75]
	s_mov_b32 m0, s84
	s_nop 0
	global_load_lds_dwordx4 v[204:205], off
	v_lshl_add_u64 v[204:205], s[22:23], 0, v[130:131]
	s_mov_b32 m0, s85
	v_lshl_add_u64 v[206:207], v[204:205], 0, s[70:71]
	global_load_lds_dwordx4 v[204:205], off
	s_mov_b32 m0, s86
	s_nop 0
	global_load_lds_dwordx4 v[206:207], off
	s_waitcnt vmcnt(8)
	s_waitcnt lgkmcnt(0)
	s_setprio 1
	s_barrier
	v_mfma_i32_16x16x64_i8 v[86:89], v[132:135], v[164:167], v[86:89]
	v_mfma_i32_16x16x64_i8 v[30:33], v[140:143], v[164:167], v[30:33]
	v_mfma_i32_16x16x64_i8 v[78:81], v[132:135], v[172:175], v[78:81]
	v_mfma_i32_16x16x64_i8 v[22:25], v[140:143], v[172:175], v[22:25]
	v_mfma_i32_16x16x64_i8 v[70:73], v[132:135], v[180:183], v[70:73]
	v_mfma_i32_16x16x64_i8 v[14:17], v[140:143], v[180:183], v[14:17]
	v_mfma_i32_16x16x64_i8 v[62:65], v[132:135], v[196:199], v[62:65]
	v_mfma_i32_16x16x64_i8 v[2:5], v[140:143], v[196:199], v[2:5]
	v_mfma_i32_16x16x64_i8 v[86:89], v[136:139], v[168:171], v[86:89]
	v_mfma_i32_16x16x64_i8 v[30:33], v[144:147], v[168:171], v[30:33]
	v_mfma_i32_16x16x64_i8 v[78:81], v[136:139], v[176:179], v[78:81]
	v_mfma_i32_16x16x64_i8 v[22:25], v[144:147], v[176:179], v[22:25]
	v_mfma_i32_16x16x64_i8 v[70:73], v[136:139], v[190:193], v[70:73]
	v_mfma_i32_16x16x64_i8 v[14:17], v[144:147], v[190:193], v[14:17]
	v_mfma_i32_16x16x64_i8 v[62:65], v[136:139], v[200:203], v[62:65]
	v_mfma_i32_16x16x64_i8 v[2:5], v[144:147], v[200:203], v[2:5]
	v_mfma_i32_16x16x64_i8 v[66:69], v[148:151], v[164:167], v[66:69]
	v_mfma_i32_16x16x64_i8 v[26:29], v[156:159], v[164:167], v[26:29]
	v_mfma_i32_16x16x64_i8 v[58:61], v[148:151], v[172:175], v[58:61]
	v_mfma_i32_16x16x64_i8 v[18:21], v[156:159], v[172:175], v[18:21]
	v_mfma_i32_16x16x64_i8 v[54:57], v[148:151], v[180:183], v[54:57]
	v_mfma_i32_16x16x64_i8 v[10:13], v[156:159], v[180:183], v[10:13]
	v_mfma_i32_16x16x64_i8 v[50:53], v[148:151], v[196:199], v[50:53]
	v_mfma_i32_16x16x64_i8 v[6:9], v[156:159], v[196:199], v[6:9]
	v_mfma_i32_16x16x64_i8 v[66:69], v[152:155], v[168:171], v[66:69]
	v_mfma_i32_16x16x64_i8 v[26:29], v[160:163], v[168:171], v[26:29]
	v_mfma_i32_16x16x64_i8 v[58:61], v[152:155], v[176:179], v[58:61]
	v_mfma_i32_16x16x64_i8 v[18:21], v[160:163], v[176:179], v[18:21]
	v_mfma_i32_16x16x64_i8 v[54:57], v[152:155], v[190:193], v[54:57]
	v_mfma_i32_16x16x64_i8 v[10:13], v[160:163], v[190:193], v[10:13]
	v_mfma_i32_16x16x64_i8 v[50:53], v[152:155], v[200:203], v[50:53]
	v_mfma_i32_16x16x64_i8 v[6:9], v[160:163], v[200:203], v[6:9]
	s_barrier
; #define PG8_STAGE(bufoff, gbase, unused) do { _Pragma("unroll") for (int _i = 0; _i < 2; ++_i) \
;         __builtin_amdgcn_global_load_lds((const unsigned*)((const char*)(gbase) + voff + _i * 8192), (LAS unsigned*)(lds + (bufoff) + ldsw + _i * 8192), 16, 0, 0); } while (0)
; #define PG8_LDA(dst, b, h) do { _Pragma("unroll") for (int m = 0; m < 4; ++m) _Pragma("unroll") for (int k = 0; k < 2; ++k) dst[m][k] = *(const LAS bf16x8*)(lds + PG8_SA(b, h) + aoff + m * 2048 + (FP8 ? k * 16 : k * 1024)); } while (0)
; #define PG8_LDB(dst, b, h) do { _Pragma("unroll") for (int n = 0; n < 2; ++n) _Pragma("unroll") for (int k = 0; k < 2; ++k) dst[n][k] = *(const LAS bf16x8*)(lds + PG8_SB(b, h) + boff + n * 2048 + (FP8 ? k * 16 : k * 1024)); } while (0)
; #define PG8_WAIT_V(n) asm volatile("s_waitcnt vmcnt(" #n ")" ::: "memory")
; #define PG8_WAIT_L(n) asm volatile("s_waitcnt lgkmcnt(" #n ")" ::: "memory")
; #define PG8_BAR __builtin_amdgcn_s_barrier()
; #define PG8_SCHED __builtin_amdgcn_sched_barrier(0)
; template <class Epi, class Sched, bool ALIGN_EPI, bool SP2, int MODE  >
; __device__ __forceinline__ void gemm_phase(LAS unsigned char* lds, const Gemm g, const Sched S, const Epi E, unsigned long long& probe_acc, int epi_id, int wv) {
;     ...
;             PG8_LDB(B0, 1, 0); PG8_LDB(B1, 1, 1); PG8_SCHED; PG8_LDA(At, 1, 0); PG8_STAGE(PG8_SA(0, 1), a2 + hA, voffA);
;             PG8_WAIT_V(8); PG8_WAIT_L(0); PG8_BAR; PG8_MMA(0, 0, At, B0); PG8_MMA(0, 1, At, B1); PG8_BAR; PG8_SCHED;
;             PG8_LDA(At, 1, 1); PG8_STAGE(PG8_SB(1, 0), b3, voffB); PG8_STAGE(PG8_SB(1, 1), b3 + hB, voffB); PG8_STAGE(PG8_SA(1, 0), a3, voffA);
;             PG8_WAIT_V(8); PG8_WAIT_L(0); PG8_BAR; PG8_MMA(1, 0, At, B0); PG8_MMA(1, 1, At, B1); PG8_BAR; PG8_SCHED;
	s_setprio 0
	v_add_u32_e32 v0, s90, v212
	ds_read_b128 v[132:135], v0
	ds_read_b128 v[136:139], v0 offset:1024
	ds_read_b128 v[140:143], v0 offset:2048
	ds_read_b128 v[144:147], v0 offset:3072
	v_add_u32_e32 v0, s95, v212
	ds_read_b128 v[148:151], v0
	ds_read_b128 v[152:155], v0 offset:1024
	ds_read_b128 v[156:159], v0 offset:2048
	ds_read_b128 v[160:163], v0 offset:3072
	s_mov_b32 m0, s87
	v_lshl_add_u64 v[206:207], v[204:205], 0, s[72:73]
	ds_read_b128 v[164:167], v213 offset:32768
	ds_read_b128 v[168:171], v213 offset:33792
	ds_read_b128 v[172:175], v213 offset:34816
	ds_read_b128 v[176:179], v213 offset:35840
	ds_read_b128 v[180:183], v213 offset:36864
	ds_read_b128 v[190:193], v213 offset:37888
	ds_read_b128 v[196:199], v213 offset:38912
	ds_read_b128 v[200:203], v213 offset:39936
	global_load_lds_dwordx4 v[206:207], off
	v_lshl_add_u64 v[206:207], v[204:205], 0, s[74:75]
	s_mov_b32 m0, s88
	s_nop 0
	global_load_lds_dwordx4 v[206:207], off
	s_waitcnt vmcnt(8)
	s_waitcnt lgkmcnt(0)
	s_setprio 1
	s_barrier
	v_mfma_i32_16x16x64_i8 v[126:129], v[132:135], v[164:167], v[126:129]
	v_mfma_i32_16x16x64_i8 v[102:105], v[140:143], v[164:167], v[102:105]
	v_mfma_i32_16x16x64_i8 v[122:125], v[132:135], v[172:175], v[122:125]
	v_mfma_i32_16x16x64_i8 v[94:97], v[140:143], v[172:175], v[94:97]
	v_mfma_i32_16x16x64_i8 v[118:121], v[132:135], v[180:183], v[118:121]
	v_mfma_i32_16x16x64_i8 v[46:49], v[140:143], v[180:183], v[46:49]
	v_mfma_i32_16x16x64_i8 v[110:113], v[132:135], v[196:199], v[110:113]
	v_mfma_i32_16x16x64_i8 v[38:41], v[140:143], v[196:199], v[38:41]
	v_mfma_i32_16x16x64_i8 v[126:129], v[136:139], v[168:171], v[126:129]
	v_mfma_i32_16x16x64_i8 v[102:105], v[144:147], v[168:171], v[102:105]
	v_mfma_i32_16x16x64_i8 v[122:125], v[136:139], v[176:179], v[122:125]
	v_mfma_i32_16x16x64_i8 v[94:97], v[144:147], v[176:179], v[94:97]
	v_mfma_i32_16x16x64_i8 v[118:121], v[136:139], v[190:193], v[118:121]
	v_mfma_i32_16x16x64_i8 v[46:49], v[144:147], v[190:193], v[46:49]
	v_mfma_i32_16x16x64_i8 v[110:113], v[136:139], v[200:203], v[110:113]
	v_mfma_i32_16x16x64_i8 v[38:41], v[144:147], v[200:203], v[38:41]
	v_mfma_i32_16x16x64_i8 v[114:117], v[148:151], v[164:167], v[114:117]
	v_mfma_i32_16x16x64_i8 v[82:85], v[156:159], v[164:167], v[82:85]
	v_mfma_i32_16x16x64_i8 v[106:109], v[148:151], v[172:175], v[106:109]
	v_mfma_i32_16x16x64_i8 v[74:77], v[156:159], v[172:175], v[74:77]
	v_mfma_i32_16x16x64_i8 v[98:101], v[148:151], v[180:183], v[98:101]
	v_mfma_i32_16x16x64_i8 v[42:45], v[156:159], v[180:183], v[42:45]
	v_mfma_i32_16x16x64_i8 v[90:93], v[148:151], v[196:199], v[90:93]
	v_mfma_i32_16x16x64_i8 v[34:37], v[156:159], v[196:199], v[34:37]
	v_mfma_i32_16x16x64_i8 v[114:117], v[152:155], v[168:171], v[114:117]
	v_mfma_i32_16x16x64_i8 v[82:85], v[160:163], v[168:171], v[82:85]
	v_mfma_i32_16x16x64_i8 v[106:109], v[152:155], v[176:179], v[106:109]
	v_mfma_i32_16x16x64_i8 v[74:77], v[160:163], v[176:179], v[74:77]
	v_mfma_i32_16x16x64_i8 v[98:101], v[152:155], v[190:193], v[98:101]
	v_mfma_i32_16x16x64_i8 v[42:45], v[160:163], v[190:193], v[42:45]
	v_mfma_i32_16x16x64_i8 v[90:93], v[152:155], v[200:203], v[90:93]
	v_mfma_i32_16x16x64_i8 v[34:37], v[160:163], v[200:203], v[34:37]
	s_barrier
	s_setprio 0
	s_mov_b32 m0, s91
	v_lshl_add_u64 v[206:207], v[184:185], 0, s[76:77]
	ds_read_b128 v[164:167], v213 offset:49152
	ds_read_b128 v[168:171], v213 offset:50176
	ds_read_b128 v[172:175], v213 offset:51200
	ds_read_b128 v[176:179], v213 offset:52224
	ds_read_b128 v[180:183], v213 offset:53248
	ds_read_b128 v[190:193], v213 offset:54272
	ds_read_b128 v[196:199], v213 offset:55296
	ds_read_b128 v[200:203], v213 offset:56320
	global_load_lds_dwordx4 v[206:207], off
	v_lshl_add_u64 v[206:207], v[184:185], 0, s[78:79]
	s_mov_b32 m0, s92
	s_nop 0
	global_load_lds_dwordx4 v[206:207], off
	v_lshl_add_u64 v[206:207], v[184:185], 0, s[80:81]
	s_mov_b32 m0, s2
	v_lshl_add_u64 v[184:185], v[184:185], 0, s[82:83]
	global_load_lds_dwordx4 v[206:207], off
	s_mov_b32 m0, s3
	s_nop 0
	global_load_lds_dwordx4 v[184:185], off
	v_lshl_add_u64 v[184:185], v[204:205], 0, s[76:77]
	s_mov_b32 m0, s93
	s_nop 0
	global_load_lds_dwordx4 v[184:185], off
	v_lshl_add_u64 v[184:185], v[204:205], 0, s[78:79]
	s_mov_b32 m0, s94
	s_nop 0
	global_load_lds_dwordx4 v[184:185], off
	s_waitcnt vmcnt(8)
	s_waitcnt lgkmcnt(0)
	s_setprio 1
	s_barrier
	v_mfma_i32_16x16x64_i8 v[86:89], v[132:135], v[164:167], v[86:89]
	v_mfma_i32_16x16x64_i8 v[30:33], v[140:143], v[164:167], v[30:33]
	v_mfma_i32_16x16x64_i8 v[78:81], v[132:135], v[172:175], v[78:81]
	v_mfma_i32_16x16x64_i8 v[22:25], v[140:143], v[172:175], v[22:25]
	v_mfma_i32_16x16x64_i8 v[70:73], v[132:135], v[180:183], v[70:73]
	v_mfma_i32_16x16x64_i8 v[14:17], v[140:143], v[180:183], v[14:17]
	v_mfma_i32_16x16x64_i8 v[62:65], v[132:135], v[196:199], v[62:65]
	v_mfma_i32_16x16x64_i8 v[2:5], v[140:143], v[196:199], v[2:5]
	v_mfma_i32_16x16x64_i8 v[86:89], v[136:139], v[168:171], v[86:89]
	v_mfma_i32_16x16x64_i8 v[30:33], v[144:147], v[168:171], v[30:33]
	v_mfma_i32_16x16x64_i8 v[78:81], v[136:139], v[176:179], v[78:81]
	v_mfma_i32_16x16x64_i8 v[22:25], v[144:147], v[176:179], v[22:25]
	v_mfma_i32_16x16x64_i8 v[70:73], v[136:139], v[190:193], v[70:73]
	v_mfma_i32_16x16x64_i8 v[14:17], v[144:147], v[190:193], v[14:17]
	v_mfma_i32_16x16x64_i8 v[62:65], v[136:139], v[200:203], v[62:65]
	v_mfma_i32_16x16x64_i8 v[2:5], v[144:147], v[200:203], v[2:5]
	v_mfma_i32_16x16x64_i8 v[66:69], v[148:151], v[164:167], v[66:69]
	v_mfma_i32_16x16x64_i8 v[26:29], v[156:159], v[164:167], v[26:29]
	v_mfma_i32_16x16x64_i8 v[58:61], v[148:151], v[172:175], v[58:61]
	v_mfma_i32_16x16x64_i8 v[18:21], v[156:159], v[172:175], v[18:21]
	v_mfma_i32_16x16x64_i8 v[54:57], v[148:151], v[180:183], v[54:57]
	v_mfma_i32_16x16x64_i8 v[10:13], v[156:159], v[180:183], v[10:13]
	v_mfma_i32_16x16x64_i8 v[50:53], v[148:151], v[196:199], v[50:53]
	v_mfma_i32_16x16x64_i8 v[6:9], v[156:159], v[196:199], v[6:9]
	v_mfma_i32_16x16x64_i8 v[66:69], v[152:155], v[168:171], v[66:69]
	v_mfma_i32_16x16x64_i8 v[26:29], v[160:163], v[168:171], v[26:29]
	v_mfma_i32_16x16x64_i8 v[58:61], v[152:155], v[176:179], v[58:61]
	v_mfma_i32_16x16x64_i8 v[18:21], v[160:163], v[176:179], v[18:21]
	v_mfma_i32_16x16x64_i8 v[54:57], v[152:155], v[190:193], v[54:57]
	v_mfma_i32_16x16x64_i8 v[10:13], v[160:163], v[190:193], v[10:13]
	v_mfma_i32_16x16x64_i8 v[50:53], v[152:155], v[200:203], v[50:53]
	v_mfma_i32_16x16x64_i8 v[6:9], v[160:163], v[200:203], v[6:9]
	s_barrier
	s_setprio 0
	s_add_i32 s14, s14, 2
	s_add_u32 s16, s16, 0x8000
	s_addc_u32 s17, s17, 0
	s_cmp_gt_u32 s14, 13
	s_mov_b64 s[28:29], s[30:31]
	s_cbranch_scc0 .LBB0_326
	v_readlane_b32 s14, v255, 11
	v_readlane_b32 s15, v255, 12
	s_and_b64 vcc, exec, s[14:15]
	s_cbranch_vccz .LBB0_329
	s_barrier

;     __device__ __forceinline__ bool next(int i, Unit& u) const { const int off = i * H + (r >> 1); if (off >= 8 * nN) return false; u.pm = 16 * g + 8 * (r & 1) + (off & 7); u.pn = off >> 3; return true; }
; #define PG8_STAGE(bufoff, gbase, unused) do { _Pragma("unroll") for (int _i = 0; _i < 2; ++_i) \
;         __builtin_amdgcn_global_load_lds((const unsigned*)((const char*)(gbase) + voff + _i * 8192), (LAS unsigned*)(lds + (bufoff) + ldsw + _i * 8192), 16, 0, 0); } while (0)
; #define PG8_LDA(dst, b, h) do { _Pragma("unroll") for (int m = 0; m < 4; ++m) _Pragma("unroll") for (int k = 0; k < 2; ++k) dst[m][k] = *(const LAS bf16x8*)(lds + PG8_SA(b, h) + aoff + m * 2048 + (FP8 ? k * 16 : k * 1024)); } while (0)
; #define PG8_LDB(dst, b, h) do { _Pragma("unroll") for (int n = 0; n < 2; ++n) _Pragma("unroll") for (int k = 0; k < 2; ++k) dst[n][k] = *(const LAS bf16x8*)(lds + PG8_SB(b, h) + boff + n * 2048 + (FP8 ? k * 16 : k * 1024)); } while (0)
; #define PG8_BAR __builtin_amdgcn_s_barrier()
; template <class Epi, class Sched, bool ALIGN_EPI, bool SP2, int MODE  >
; __device__ __forceinline__ void gemm_phase(LAS unsigned char* lds, const Gemm g, const Sched S, const Epi E, unsigned long long& probe_acc, int epi_id, int wv) {
;     ...
;         const bool has_next = S.next(ui + 1, nxt);
;         const char* nA = has_next ? (const char*)g.A + (size_t)nxt.pm * tA + (g.gt ? (size_t)(nxt.pn / g.gt) * gK2 : 0) : cA; const char* nB = has_next ? (const char*)g.Bt + (size_t)nxt.pn * tB : cB;
;         for (int t = 0; t < nt; t += 2) {
;             const bool last = (t == nt - 2);
;             const char* a1 = cA + (size_t)(t + 1) * kstep;
;             const char* a2 = last ? nA : cA + (size_t)(t + 2) * kstep; const char* b2 = last ? nB : cB + (size_t)(t + 2) * kstep;
;             const char* a3 = a2 + kstep; const char* b3 = b2 + kstep;
;             if constexpr (SP2) {
;             PG8_LDB(B0, 0, 0); PG8_LDB(B1, 0, 1); PG8_SCHED; PG8_LDA(At, 0, 0); PG8_STAGE(PG8_SA(1, 1), a1 + hA, voffA);
;             PG8_WAIT_V(8); PG8_WAIT_L(0); PG8_BAR; PG8_MMA(0, 0, At, B0); PG8_MMA(0, 1, At, B1); PG8_BAR; PG8_SCHED;
;             PG8_LDA(At, 0, 1); PG8_STAGE(PG8_SB(0, 0), b2, voffB); PG8_STAGE(PG8_SB(0, 1), b2 + hB, voffB); PG8_STAGE(PG8_SA(0, 0), a2, voffA);
;             PG8_WAIT_V(8); PG8_WAIT_L(0); PG8_BAR; PG8_MMA(1, 0, At, B0); PG8_MMA(1, 1, At, B1); PG8_BAR; PG8_SCHED;
.LBB0_364:
	s_mov_b64 s[20:21], s[4:5]
	s_add_i32 s84, s84, 1
	v_readlane_b32 s4, v254, 6
	s_mul_i32 s4, s84, s4
	v_readlane_b32 s5, v254, 35
	s_add_i32 s4, s4, s5
	s_cmpk_lt_i32 s4, 0xc0
	s_mov_b64 s[18:19], s[10:11]
	s_cselect_b64 s[16:17], -1, 0
	s_and_b32 s5, s4, 7
	v_readlane_b32 s10, v254, 18
	s_mov_b32 s8, s87
	s_mov_b32 s9, s86
	s_mov_b32 s88, s87
	s_mov_b32 s89, s86
	s_or_b32 s87, s5, s10
	s_ashr_i32 s86, s4, 3
	s_and_b64 s[4:5], s[16:17], exec
	s_cselect_b32 s10, s87, s8
	s_cselect_b32 s4, s86, s9
	s_ashr_i32 s11, s10, 31
	s_lshl_b64 s[10:11], s[10:11], 20
	s_add_u32 s10, s58, s10
	s_addc_u32 s11, s59, s11
	s_and_b64 s[90:91], s[16:17], exec
	s_cselect_b32 s46, s11, s19
	s_cselect_b32 s90, s10, s18
	s_ashr_i32 s5, s4, 31
	s_lshl_b64 s[4:5], s[4:5], 20
	s_add_u32 s4, s0, s4
	s_addc_u32 s5, s1, s5
	s_and_b64 s[92:93], s[16:17], exec
	s_cselect_b32 s91, s5, s21
	s_cselect_b32 s92, s4, s20
	s_add_u32 s93, s20, 0x8000
	s_addc_u32 s94, s21, 0
	s_mov_b32 s95, -2
	v_add_u32_e32 v0, s2, v166
	s_waitcnt vmcnt(0)
	ds_read_b128 v[130:133], v0
	ds_read_b128 v[134:137], v0 offset:1024
	ds_read_b128 v[138:141], v0 offset:2048
	ds_read_b128 v[142:145], v0 offset:3072
	v_add_u32_e32 v0, s23, v166
	ds_read_b128 v[146:149], v0
	ds_read_b128 v[150:153], v0 offset:1024
	s_waitcnt lgkmcnt(0)
	ds_read_b128 v[156:159], v0 offset:2048
	ds_read_b128 v[160:163], v0 offset:3072
	s_add_u32 s20, s18, 0x8000
	s_addc_u32 s21, s19, 0
	s_cmp_eq_u32 s95, 28
	s_cselect_b32 vcc_hi, s46, s21
	s_cselect_b32 vcc_lo, s90, s20
	s_cselect_b32 s9, s91, s94
	s_cselect_b32 s8, s92, s93
	v_lshl_add_u64 v[184:185], s[18:19], 0, v[154:155]
	v_lshl_add_u64 v[204:205], v[184:185], 0, s[52:53]
	s_add_i32 m0, s26, 0xc000
	ds_read_b128 v[168:171], v167
	ds_read_b128 v[172:175], v167 offset:1024
	ds_read_b128 v[176:179], v167 offset:2048
	ds_read_b128 v[180:183], v167 offset:3072
	ds_read_b128 v[188:191], v167 offset:4096
	ds_read_b128 v[192:195], v167 offset:5120
	ds_read_b128 v[196:199], v167 offset:6144
	ds_read_b128 v[200:203], v167 offset:7168
	global_load_lds_dwordx4 v[204:205], off
	v_lshl_add_u64 v[184:185], v[184:185], 0, s[54:55]
	s_add_i32 m0, s26, 0xe000
	s_nop 0
	global_load_lds_dwordx4 v[184:185], off
	s_waitcnt vmcnt(8)
	s_waitcnt lgkmcnt(0)
	s_setprio 1
	s_barrier
	v_mfma_f32_16x16x32_bf16 v[126:129], v[130:133], v[168:171], 0
	v_mfma_f32_16x16x32_bf16 v[122:125], v[138:141], v[168:171], 0
	v_mfma_f32_16x16x32_bf16 v[110:113], v[130:133], v[176:179], 0
	v_mfma_f32_16x16x32_bf16 v[106:109], v[138:141], v[176:179], 0
	v_mfma_f32_16x16x32_bf16 v[94:97], v[130:133], v[188:191], 0
	v_mfma_f32_16x16x32_bf16 v[90:93], v[138:141], v[188:191], 0
	v_mfma_f32_16x16x32_bf16 v[78:81], v[130:133], v[196:199], 0
	v_mfma_f32_16x16x32_bf16 v[74:77], v[138:141], v[196:199], 0
	v_mfma_f32_16x16x32_bf16 v[126:129], v[134:137], v[172:175], v[126:129]
	v_mfma_f32_16x16x32_bf16 v[122:125], v[142:145], v[172:175], v[122:125]
	v_mfma_f32_16x16x32_bf16 v[110:113], v[134:137], v[180:183], v[110:113]
	v_mfma_f32_16x16x32_bf16 v[106:109], v[142:145], v[180:183], v[106:109]
	v_mfma_f32_16x16x32_bf16 v[94:97], v[134:137], v[192:195], v[94:97]
	v_mfma_f32_16x16x32_bf16 v[90:93], v[142:145], v[192:195], v[90:93]
	v_mfma_f32_16x16x32_bf16 v[78:81], v[134:137], v[200:203], v[78:81]
	v_mfma_f32_16x16x32_bf16 v[74:77], v[142:145], v[200:203], v[74:77]
	v_mfma_f32_16x16x32_bf16 v[118:121], v[146:149], v[168:171], 0
	v_mfma_f32_16x16x32_bf16 v[114:117], v[156:159], v[168:171], 0
	v_mfma_f32_16x16x32_bf16 v[102:105], v[146:149], v[176:179], 0
	v_mfma_f32_16x16x32_bf16 v[98:101], v[156:159], v[176:179], 0
	v_mfma_f32_16x16x32_bf16 v[86:89], v[146:149], v[188:191], 0
	v_mfma_f32_16x16x32_bf16 v[82:85], v[156:159], v[188:191], 0
	v_mfma_f32_16x16x32_bf16 v[70:73], v[146:149], v[196:199], 0
	v_mfma_f32_16x16x32_bf16 v[66:69], v[156:159], v[196:199], 0
	v_mfma_f32_16x16x32_bf16 v[118:121], v[150:153], v[172:175], v[118:121]
	v_mfma_f32_16x16x32_bf16 v[114:117], v[160:163], v[172:175], v[114:117]
	v_mfma_f32_16x16x32_bf16 v[102:105], v[150:153], v[180:183], v[102:105]
	v_mfma_f32_16x16x32_bf16 v[98:101], v[160:163], v[180:183], v[98:101]
	v_mfma_f32_16x16x32_bf16 v[86:89], v[150:153], v[192:195], v[86:89]
	v_mfma_f32_16x16x32_bf16 v[82:85], v[160:163], v[192:195], v[82:85]
	v_mfma_f32_16x16x32_bf16 v[70:73], v[150:153], v[200:203], v[70:73]
	v_mfma_f32_16x16x32_bf16 v[66:69], v[160:163], v[200:203], v[66:69]
	s_barrier
	s_setprio 0
	s_mov_b32 m0, s3
	v_lshl_add_u64 v[184:185], s[8:9], 0, v[154:155]
	ds_read_b128 v[168:171], v167 offset:16384
	ds_read_b128 v[172:175], v167 offset:17408
	ds_read_b128 v[176:179], v167 offset:18432
	ds_read_b128 v[180:183], v167 offset:19456
	ds_read_b128 v[188:191], v167 offset:20480
	ds_read_b128 v[192:195], v167 offset:21504
	ds_read_b128 v[196:199], v167 offset:22528
	ds_read_b128 v[200:203], v167 offset:23552
	global_load_lds_dwordx4 v[184:185], off
	v_lshl_add_u64 v[204:205], v[184:185], 0, s[70:71]
	s_mov_b32 m0, s22
	s_nop 0
	global_load_lds_dwordx4 v[204:205], off
	v_lshl_add_u64 v[204:205], v[184:185], 0, s[96:97]
	s_mov_b32 m0, s24
	s_nop 0
	global_load_lds_dwordx4 v[204:205], off
	v_lshl_add_u64 v[204:205], v[184:185], 0, s[60:61]
	s_mov_b32 m0, s25
	s_nop 0
	global_load_lds_dwordx4 v[204:205], off
	v_lshl_add_u64 v[204:205], vcc, 0, v[154:155]
	s_mov_b32 m0, s26
	v_lshl_add_u64 v[206:207], v[204:205], 0, s[70:71]
	global_load_lds_dwordx4 v[204:205], off
	s_mov_b32 m0, s27
	s_nop 0
	global_load_lds_dwordx4 v[206:207], off
	s_waitcnt vmcnt(8)
	s_waitcnt lgkmcnt(0)
	s_setprio 1
	s_barrier
; #define PG8_STAGE(bufoff, gbase, unused) do { _Pragma("unroll") for (int _i = 0; _i < 2; ++_i) \
;         __builtin_amdgcn_global_load_lds((const unsigned*)((const char*)(gbase) + voff + _i * 8192), (LAS unsigned*)(lds + (bufoff) + ldsw + _i * 8192), 16, 0, 0); } while (0)
; #define PG8_LDA(dst, b, h) do { _Pragma("unroll") for (int m = 0; m < 4; ++m) _Pragma("unroll") for (int k = 0; k < 2; ++k) dst[m][k] = *(const LAS bf16x8*)(lds + PG8_SA(b, h) + aoff + m * 2048 + (FP8 ? k * 16 : k * 1024)); } while (0)
; #define PG8_LDB(dst, b, h) do { _Pragma("unroll") for (int n = 0; n < 2; ++n) _Pragma("unroll") for (int k = 0; k < 2; ++k) dst[n][k] = *(const LAS bf16x8*)(lds + PG8_SB(b, h) + boff + n * 2048 + (FP8 ? k * 16 : k * 1024)); } while (0)
; #define PG8_WAIT_V(n) asm volatile("s_waitcnt vmcnt(" #n ")" ::: "memory")
; #define PG8_WAIT_L(n) asm volatile("s_waitcnt lgkmcnt(" #n ")" ::: "memory")
; #define PG8_BAR __builtin_amdgcn_s_barrier()
; #define PG8_SCHED __builtin_amdgcn_sched_barrier(0)
; template <class Epi, class Sched, bool ALIGN_EPI, bool SP2, int MODE  >
; __device__ __forceinline__ void gemm_phase(LAS unsigned char* lds, const Gemm g, const Sched S, const Epi E, unsigned long long& probe_acc, int epi_id, int wv) {
;     ...
;             PG8_WAIT_V(8); PG8_WAIT_L(0); PG8_BAR; PG8_MMA(1, 0, At, B0); PG8_MMA(1, 1, At, B1); PG8_BAR; PG8_SCHED;
;             PG8_LDB(B0, 1, 0); PG8_LDB(B1, 1, 1); PG8_SCHED; PG8_LDA(At, 1, 0); PG8_STAGE(PG8_SA(0, 1), a2 + hA, voffA);
;             PG8_WAIT_V(8); PG8_WAIT_L(0); PG8_BAR; PG8_MMA(0, 0, At, B0); PG8_MMA(0, 1, At, B1); PG8_BAR; PG8_SCHED;
	v_mfma_f32_16x16x32_bf16 v[62:65], v[130:133], v[168:171], 0
	v_mfma_f32_16x16x32_bf16 v[58:61], v[138:141], v[168:171], 0
	v_mfma_f32_16x16x32_bf16 v[46:49], v[130:133], v[176:179], 0
	v_mfma_f32_16x16x32_bf16 v[42:45], v[138:141], v[176:179], 0
	v_mfma_f32_16x16x32_bf16 v[30:33], v[130:133], v[188:191], 0
	v_mfma_f32_16x16x32_bf16 v[26:29], v[138:141], v[188:191], 0
	v_mfma_f32_16x16x32_bf16 v[14:17], v[130:133], v[196:199], 0
	v_mfma_f32_16x16x32_bf16 v[10:13], v[138:141], v[196:199], 0
	v_mfma_f32_16x16x32_bf16 v[62:65], v[134:137], v[172:175], v[62:65]
	v_mfma_f32_16x16x32_bf16 v[58:61], v[142:145], v[172:175], v[58:61]
	v_mfma_f32_16x16x32_bf16 v[46:49], v[134:137], v[180:183], v[46:49]
	v_mfma_f32_16x16x32_bf16 v[42:45], v[142:145], v[180:183], v[42:45]
	v_mfma_f32_16x16x32_bf16 v[30:33], v[134:137], v[192:195], v[30:33]
	v_mfma_f32_16x16x32_bf16 v[26:29], v[142:145], v[192:195], v[26:29]
	v_mfma_f32_16x16x32_bf16 v[14:17], v[134:137], v[200:203], v[14:17]
	v_mfma_f32_16x16x32_bf16 v[10:13], v[142:145], v[200:203], v[10:13]
	v_mfma_f32_16x16x32_bf16 v[54:57], v[146:149], v[168:171], 0
	v_mfma_f32_16x16x32_bf16 v[50:53], v[156:159], v[168:171], 0
	v_mfma_f32_16x16x32_bf16 v[38:41], v[146:149], v[176:179], 0
	v_mfma_f32_16x16x32_bf16 v[34:37], v[156:159], v[176:179], 0
	v_mfma_f32_16x16x32_bf16 v[22:25], v[146:149], v[188:191], 0
	v_mfma_f32_16x16x32_bf16 v[18:21], v[156:159], v[188:191], 0
	v_mfma_f32_16x16x32_bf16 v[6:9], v[146:149], v[196:199], 0
	v_mfma_f32_16x16x32_bf16 v[2:5], v[156:159], v[196:199], 0
	v_mfma_f32_16x16x32_bf16 v[54:57], v[150:153], v[172:175], v[54:57]
	v_mfma_f32_16x16x32_bf16 v[50:53], v[160:163], v[172:175], v[50:53]
	v_mfma_f32_16x16x32_bf16 v[38:41], v[150:153], v[180:183], v[38:41]
	v_mfma_f32_16x16x32_bf16 v[34:37], v[160:163], v[180:183], v[34:37]
	v_mfma_f32_16x16x32_bf16 v[22:25], v[150:153], v[192:195], v[22:25]
	v_mfma_f32_16x16x32_bf16 v[18:21], v[160:163], v[192:195], v[18:21]
	v_mfma_f32_16x16x32_bf16 v[6:9], v[150:153], v[200:203], v[6:9]
	v_mfma_f32_16x16x32_bf16 v[2:5], v[160:163], v[200:203], v[2:5]
	s_barrier
	s_setprio 0
	v_add_u32_e32 v0, s31, v166
	ds_read_b128 v[130:133], v0
	ds_read_b128 v[134:137], v0 offset:1024
	ds_read_b128 v[138:141], v0 offset:2048
	ds_read_b128 v[142:145], v0 offset:3072
	v_add_u32_e32 v0, s39, v166
	ds_read_b128 v[146:149], v0
	ds_read_b128 v[150:153], v0 offset:1024
	ds_read_b128 v[156:159], v0 offset:2048
	ds_read_b128 v[160:163], v0 offset:3072
	s_mov_b32 m0, s28
	v_lshl_add_u64 v[206:207], v[204:205], 0, s[96:97]
	ds_read_b128 v[168:171], v167 offset:32768
	ds_read_b128 v[172:175], v167 offset:33792
	ds_read_b128 v[176:179], v167 offset:34816
	ds_read_b128 v[180:183], v167 offset:35840
	ds_read_b128 v[188:191], v167 offset:36864
	ds_read_b128 v[192:195], v167 offset:37888
	ds_read_b128 v[196:199], v167 offset:38912
	ds_read_b128 v[200:203], v167 offset:39936
	global_load_lds_dwordx4 v[206:207], off
	v_lshl_add_u64 v[206:207], v[204:205], 0, s[60:61]
	s_mov_b32 m0, s29
	s_nop 0
	global_load_lds_dwordx4 v[206:207], off
	s_waitcnt vmcnt(8)
	s_waitcnt lgkmcnt(0)
	s_setprio 1
	s_barrier
	v_mfma_f32_16x16x32_bf16 v[126:129], v[130:133], v[168:171], v[126:129]
	v_mfma_f32_16x16x32_bf16 v[122:125], v[138:141], v[168:171], v[122:125]
	v_mfma_f32_16x16x32_bf16 v[110:113], v[130:133], v[176:179], v[110:113]
	v_mfma_f32_16x16x32_bf16 v[106:109], v[138:141], v[176:179], v[106:109]
	v_mfma_f32_16x16x32_bf16 v[94:97], v[130:133], v[188:191], v[94:97]
	v_mfma_f32_16x16x32_bf16 v[90:93], v[138:141], v[188:191], v[90:93]
	v_mfma_f32_16x16x32_bf16 v[78:81], v[130:133], v[196:199], v[78:81]
	v_mfma_f32_16x16x32_bf16 v[74:77], v[138:141], v[196:199], v[74:77]
	v_mfma_f32_16x16x32_bf16 v[126:129], v[134:137], v[172:175], v[126:129]
	v_mfma_f32_16x16x32_bf16 v[122:125], v[142:145], v[172:175], v[122:125]
	v_mfma_f32_16x16x32_bf16 v[110:113], v[134:137], v[180:183], v[110:113]
	v_mfma_f32_16x16x32_bf16 v[106:109], v[142:145], v[180:183], v[106:109]
	v_mfma_f32_16x16x32_bf16 v[94:97], v[134:137], v[192:195], v[94:97]
	v_mfma_f32_16x16x32_bf16 v[90:93], v[142:145], v[192:195], v[90:93]
	v_mfma_f32_16x16x32_bf16 v[78:81], v[134:137], v[200:203], v[78:81]
	v_mfma_f32_16x16x32_bf16 v[74:77], v[142:145], v[200:203], v[74:77]
	v_mfma_f32_16x16x32_bf16 v[118:121], v[146:149], v[168:171], v[118:121]
	v_mfma_f32_16x16x32_bf16 v[114:117], v[156:159], v[168:171], v[114:117]
	v_mfma_f32_16x16x32_bf16 v[102:105], v[146:149], v[176:179], v[102:105]
	v_mfma_f32_16x16x32_bf16 v[98:101], v[156:159], v[176:179], v[98:101]
	v_mfma_f32_16x16x32_bf16 v[86:89], v[146:149], v[188:191], v[86:89]
	v_mfma_f32_16x16x32_bf16 v[82:85], v[156:159], v[188:191], v[82:85]
	v_mfma_f32_16x16x32_bf16 v[70:73], v[146:149], v[196:199], v[70:73]
	v_mfma_f32_16x16x32_bf16 v[66:69], v[156:159], v[196:199], v[66:69]
	v_mfma_f32_16x16x32_bf16 v[118:121], v[150:153], v[172:175], v[118:121]
	v_mfma_f32_16x16x32_bf16 v[114:117], v[160:163], v[172:175], v[114:117]
	v_mfma_f32_16x16x32_bf16 v[102:105], v[150:153], v[180:183], v[102:105]
	v_mfma_f32_16x16x32_bf16 v[98:101], v[160:163], v[180:183], v[98:101]
	v_mfma_f32_16x16x32_bf16 v[86:89], v[150:153], v[192:195], v[86:89]
	v_mfma_f32_16x16x32_bf16 v[82:85], v[160:163], v[192:195], v[82:85]
	v_mfma_f32_16x16x32_bf16 v[70:73], v[150:153], v[200:203], v[70:73]
	v_mfma_f32_16x16x32_bf16 v[66:69], v[160:163], v[200:203], v[66:69]
	s_barrier
; #define PG8_STAGE(bufoff, gbase, unused) do { _Pragma("unroll") for (int _i = 0; _i < 2; ++_i) \
;         __builtin_amdgcn_global_load_lds((const unsigned*)((const char*)(gbase) + voff + _i * 8192), (LAS unsigned*)(lds + (bufoff) + ldsw + _i * 8192), 16, 0, 0); } while (0)
; #define PG8_LDA(dst, b, h) do { _Pragma("unroll") for (int m = 0; m < 4; ++m) _Pragma("unroll") for (int k = 0; k < 2; ++k) dst[m][k] = *(const LAS bf16x8*)(lds + PG8_SA(b, h) + aoff + m * 2048 + (FP8 ? k * 16 : k * 1024)); } while (0)
; #define PG8_LDB(dst, b, h) do { _Pragma("unroll") for (int n = 0; n < 2; ++n) _Pragma("unroll") for (int k = 0; k < 2; ++k) dst[n][k] = *(const LAS bf16x8*)(lds + PG8_SB(b, h) + boff + n * 2048 + (FP8 ? k * 16 : k * 1024)); } while (0)
; #define PG8_WAIT_V(n) asm volatile("s_waitcnt vmcnt(" #n ")" ::: "memory")
; #define PG8_WAIT_L(n) asm volatile("s_waitcnt lgkmcnt(" #n ")" ::: "memory")
; #define PG8_BAR __builtin_amdgcn_s_barrier()
; #define PG8_SCHED __builtin_amdgcn_sched_barrier(0)
; template <class Epi, class Sched, bool ALIGN_EPI, bool SP2, int MODE  >
; __device__ __forceinline__ void gemm_phase(LAS unsigned char* lds, const Gemm g, const Sched S, const Epi E, unsigned long long& probe_acc, int epi_id, int wv) {
;     ...
;         for (int t = 0; t < nt; t += 2) {
;             const bool last = (t == nt - 2);
;             const char* a1 = cA + (size_t)(t + 1) * kstep;
;             const char* a2 = last ? nA : cA + (size_t)(t + 2) * kstep; const char* b2 = last ? nB : cB + (size_t)(t + 2) * kstep;
;             const char* a3 = a2 + kstep; const char* b3 = b2 + kstep;
;             if constexpr (SP2) {
;             PG8_LDB(B0, 0, 0); PG8_LDB(B1, 0, 1); PG8_SCHED; PG8_LDA(At, 0, 0); PG8_STAGE(PG8_SA(1, 1), a1 + hA, voffA);
;             PG8_WAIT_V(8); PG8_WAIT_L(0); PG8_BAR; PG8_MMA(0, 0, At, B0); PG8_MMA(0, 1, At, B1); PG8_BAR; PG8_SCHED;
;     ...
;             PG8_LDA(At, 1, 1); PG8_STAGE(PG8_SB(1, 0), b3, voffB); PG8_STAGE(PG8_SB(1, 1), b3 + hB, voffB); PG8_STAGE(PG8_SA(1, 0), a3, voffA);
;             PG8_WAIT_V(8); PG8_WAIT_L(0); PG8_BAR; PG8_MMA(1, 0, At, B0); PG8_MMA(1, 1, At, B1); PG8_BAR; PG8_SCHED;
	s_setprio 0
	s_mov_b32 m0, s34
	v_lshl_add_u64 v[206:207], v[184:185], 0, s[76:77]
	ds_read_b128 v[168:171], v167 offset:49152
	ds_read_b128 v[172:175], v167 offset:50176
	ds_read_b128 v[176:179], v167 offset:51200
	ds_read_b128 v[180:183], v167 offset:52224
	ds_read_b128 v[188:191], v167 offset:53248
	ds_read_b128 v[192:195], v167 offset:54272
	ds_read_b128 v[196:199], v167 offset:55296
	ds_read_b128 v[200:203], v167 offset:56320
	global_load_lds_dwordx4 v[206:207], off
	v_lshl_add_u64 v[206:207], v[184:185], 0, s[78:79]
	s_mov_b32 m0, s35
	s_nop 0
	global_load_lds_dwordx4 v[206:207], off
	v_lshl_add_u64 v[206:207], v[184:185], 0, s[52:53]
	s_mov_b32 m0, s40
	v_lshl_add_u64 v[184:185], v[184:185], 0, s[54:55]
	global_load_lds_dwordx4 v[206:207], off
	s_mov_b32 m0, s41
	s_nop 0
	global_load_lds_dwordx4 v[184:185], off
	v_lshl_add_u64 v[184:185], v[204:205], 0, s[76:77]
	s_mov_b32 m0, s36
	s_nop 0
	global_load_lds_dwordx4 v[184:185], off
	v_lshl_add_u64 v[184:185], v[204:205], 0, s[78:79]
	s_mov_b32 m0, s37
	s_nop 0
	global_load_lds_dwordx4 v[184:185], off
	s_waitcnt vmcnt(8)
	s_waitcnt lgkmcnt(0)
	s_setprio 1
	s_barrier
	v_mfma_f32_16x16x32_bf16 v[62:65], v[130:133], v[168:171], v[62:65]
	v_mfma_f32_16x16x32_bf16 v[58:61], v[138:141], v[168:171], v[58:61]
	v_mfma_f32_16x16x32_bf16 v[46:49], v[130:133], v[176:179], v[46:49]
	v_mfma_f32_16x16x32_bf16 v[42:45], v[138:141], v[176:179], v[42:45]
	v_mfma_f32_16x16x32_bf16 v[30:33], v[130:133], v[188:191], v[30:33]
	v_mfma_f32_16x16x32_bf16 v[26:29], v[138:141], v[188:191], v[26:29]
	v_mfma_f32_16x16x32_bf16 v[14:17], v[130:133], v[196:199], v[14:17]
	v_mfma_f32_16x16x32_bf16 v[10:13], v[138:141], v[196:199], v[10:13]
	v_mfma_f32_16x16x32_bf16 v[62:65], v[134:137], v[172:175], v[62:65]
	v_mfma_f32_16x16x32_bf16 v[58:61], v[142:145], v[172:175], v[58:61]
	v_mfma_f32_16x16x32_bf16 v[46:49], v[134:137], v[180:183], v[46:49]
	v_mfma_f32_16x16x32_bf16 v[42:45], v[142:145], v[180:183], v[42:45]
	v_mfma_f32_16x16x32_bf16 v[30:33], v[134:137], v[192:195], v[30:33]
	v_mfma_f32_16x16x32_bf16 v[26:29], v[142:145], v[192:195], v[26:29]
	v_mfma_f32_16x16x32_bf16 v[14:17], v[134:137], v[200:203], v[14:17]
	v_mfma_f32_16x16x32_bf16 v[10:13], v[142:145], v[200:203], v[10:13]
	v_mfma_f32_16x16x32_bf16 v[54:57], v[146:149], v[168:171], v[54:57]
	v_mfma_f32_16x16x32_bf16 v[50:53], v[156:159], v[168:171], v[50:53]
	v_mfma_f32_16x16x32_bf16 v[38:41], v[146:149], v[176:179], v[38:41]
	v_mfma_f32_16x16x32_bf16 v[34:37], v[156:159], v[176:179], v[34:37]
	v_mfma_f32_16x16x32_bf16 v[22:25], v[146:149], v[188:191], v[22:25]
	v_mfma_f32_16x16x32_bf16 v[18:21], v[156:159], v[188:191], v[18:21]
	v_mfma_f32_16x16x32_bf16 v[6:9], v[146:149], v[196:199], v[6:9]
	v_mfma_f32_16x16x32_bf16 v[2:5], v[156:159], v[196:199], v[2:5]
	v_mfma_f32_16x16x32_bf16 v[54:57], v[150:153], v[172:175], v[54:57]
	v_mfma_f32_16x16x32_bf16 v[50:53], v[160:163], v[172:175], v[50:53]
	v_mfma_f32_16x16x32_bf16 v[38:41], v[150:153], v[180:183], v[38:41]
	v_mfma_f32_16x16x32_bf16 v[34:37], v[160:163], v[180:183], v[34:37]
	v_mfma_f32_16x16x32_bf16 v[22:25], v[150:153], v[192:195], v[22:25]
	v_mfma_f32_16x16x32_bf16 v[18:21], v[160:163], v[192:195], v[18:21]
	v_mfma_f32_16x16x32_bf16 v[6:9], v[150:153], v[200:203], v[6:9]
	v_mfma_f32_16x16x32_bf16 v[2:5], v[160:163], v[200:203], v[2:5]
	s_barrier
	s_setprio 0
	s_add_i32 s95, s95, 2
	s_add_u32 s93, s93, 0x8000
	s_addc_u32 s94, s94, 0
	s_cmp_gt_u32 s95, 29
	s_mov_b64 s[18:19], s[20:21]
.LBB0_365:
	v_add_u32_e32 v0, s2, v166
	s_waitcnt vmcnt(0)
	ds_read_b128 v[130:133], v0
	ds_read_b128 v[134:137], v0 offset:1024
	ds_read_b128 v[138:141], v0 offset:2048
	ds_read_b128 v[142:145], v0 offset:3072
	v_add_u32_e32 v0, s23, v166
	ds_read_b128 v[146:149], v0
	ds_read_b128 v[150:153], v0 offset:1024
	s_waitcnt lgkmcnt(0)
	ds_read_b128 v[156:159], v0 offset:2048
	ds_read_b128 v[160:163], v0 offset:3072
	s_add_u32 s20, s18, 0x8000
	s_addc_u32 s21, s19, 0
	s_cmp_eq_u32 s95, 28
	s_cselect_b32 vcc_hi, s46, s21
	s_cselect_b32 vcc_lo, s90, s20
	s_cselect_b32 s9, s91, s94
	s_cselect_b32 s8, s92, s93
	v_lshl_add_u64 v[184:185], s[18:19], 0, v[154:155]
	v_lshl_add_u64 v[204:205], v[184:185], 0, s[52:53]
	s_add_i32 m0, s26, 0xc000
	ds_read_b128 v[168:171], v167
	ds_read_b128 v[172:175], v167 offset:1024
	ds_read_b128 v[176:179], v167 offset:2048
	ds_read_b128 v[180:183], v167 offset:3072
	ds_read_b128 v[188:191], v167 offset:4096
	ds_read_b128 v[192:195], v167 offset:5120
	ds_read_b128 v[196:199], v167 offset:6144
	ds_read_b128 v[200:203], v167 offset:7168
	global_load_lds_dwordx4 v[204:205], off
	v_lshl_add_u64 v[184:185], v[184:185], 0, s[54:55]
	s_add_i32 m0, s26, 0xe000
	s_nop 0
	global_load_lds_dwordx4 v[184:185], off
	s_waitcnt vmcnt(8)
	s_waitcnt lgkmcnt(0)
	s_setprio 1
	s_barrier
; #define PG8_STAGE(bufoff, gbase, unused) do { _Pragma("unroll") for (int _i = 0; _i < 2; ++_i) \
;         __builtin_amdgcn_global_load_lds((const unsigned*)((const char*)(gbase) + voff + _i * 8192), (LAS unsigned*)(lds + (bufoff) + ldsw + _i * 8192), 16, 0, 0); } while (0)
; #define PG8_LDA(dst, b, h) do { _Pragma("unroll") for (int m = 0; m < 4; ++m) _Pragma("unroll") for (int k = 0; k < 2; ++k) dst[m][k] = *(const LAS bf16x8*)(lds + PG8_SA(b, h) + aoff + m * 2048 + (FP8 ? k * 16 : k * 1024)); } while (0)
; #define PG8_LDB(dst, b, h) do { _Pragma("unroll") for (int n = 0; n < 2; ++n) _Pragma("unroll") for (int k = 0; k < 2; ++k) dst[n][k] = *(const LAS bf16x8*)(lds + PG8_SB(b, h) + boff + n * 2048 + (FP8 ? k * 16 : k * 1024)); } while (0)
; #define PG8_WAIT_V(n) asm volatile("s_waitcnt vmcnt(" #n ")" ::: "memory")
; #define PG8_WAIT_L(n) asm volatile("s_waitcnt lgkmcnt(" #n ")" ::: "memory")
; #define PG8_BAR __builtin_amdgcn_s_barrier()
; #define PG8_SCHED __builtin_amdgcn_sched_barrier(0)
; template <class Epi, class Sched, bool ALIGN_EPI, bool SP2, int MODE  >
; __device__ __forceinline__ void gemm_phase(LAS unsigned char* lds, const Gemm g, const Sched S, const Epi E, unsigned long long& probe_acc, int epi_id, int wv) {
;     ...
;             PG8_WAIT_V(8); PG8_WAIT_L(0); PG8_BAR; PG8_MMA(0, 0, At, B0); PG8_MMA(0, 1, At, B1); PG8_BAR; PG8_SCHED;
;             PG8_LDA(At, 0, 1); PG8_STAGE(PG8_SB(0, 0), b2, voffB); PG8_STAGE(PG8_SB(0, 1), b2 + hB, voffB); PG8_STAGE(PG8_SA(0, 0), a2, voffA);
;             PG8_WAIT_V(8); PG8_WAIT_L(0); PG8_BAR; PG8_MMA(1, 0, At, B0); PG8_MMA(1, 1, At, B1); PG8_BAR; PG8_SCHED;
;             PG8_LDB(B0, 1, 0); PG8_LDB(B1, 1, 1); PG8_SCHED; PG8_LDA(At, 1, 0); PG8_STAGE(PG8_SA(0, 1), a2 + hA, voffA);
;             PG8_WAIT_V(8); PG8_WAIT_L(0); PG8_BAR; PG8_MMA(0, 0, At, B0); PG8_MMA(0, 1, At, B1); PG8_BAR; PG8_SCHED;
;             PG8_LDA(At, 1, 1); PG8_STAGE(PG8_SB(1, 0), b3, voffB); PG8_STAGE(PG8_SB(1, 1), b3 + hB, voffB); PG8_STAGE(PG8_SA(1, 0), a3, voffA);
;             PG8_WAIT_V(8); PG8_WAIT_L(0); PG8_BAR; PG8_MMA(1, 0, At, B0); PG8_MMA(1, 1, At, B1); PG8_BAR; PG8_SCHED;
	v_mfma_f32_16x16x32_bf16 v[126:129], v[130:133], v[168:171], v[126:129]
	v_mfma_f32_16x16x32_bf16 v[122:125], v[138:141], v[168:171], v[122:125]
	v_mfma_f32_16x16x32_bf16 v[110:113], v[130:133], v[176:179], v[110:113]
	v_mfma_f32_16x16x32_bf16 v[106:109], v[138:141], v[176:179], v[106:109]
	v_mfma_f32_16x16x32_bf16 v[94:97], v[130:133], v[188:191], v[94:97]
	v_mfma_f32_16x16x32_bf16 v[90:93], v[138:141], v[188:191], v[90:93]
	v_mfma_f32_16x16x32_bf16 v[78:81], v[130:133], v[196:199], v[78:81]
	v_mfma_f32_16x16x32_bf16 v[74:77], v[138:141], v[196:199], v[74:77]
	v_mfma_f32_16x16x32_bf16 v[126:129], v[134:137], v[172:175], v[126:129]
	v_mfma_f32_16x16x32_bf16 v[122:125], v[142:145], v[172:175], v[122:125]
	v_mfma_f32_16x16x32_bf16 v[110:113], v[134:137], v[180:183], v[110:113]
	v_mfma_f32_16x16x32_bf16 v[106:109], v[142:145], v[180:183], v[106:109]
	v_mfma_f32_16x16x32_bf16 v[94:97], v[134:137], v[192:195], v[94:97]
	v_mfma_f32_16x16x32_bf16 v[90:93], v[142:145], v[192:195], v[90:93]
	v_mfma_f32_16x16x32_bf16 v[78:81], v[134:137], v[200:203], v[78:81]
	v_mfma_f32_16x16x32_bf16 v[74:77], v[142:145], v[200:203], v[74:77]
	v_mfma_f32_16x16x32_bf16 v[118:121], v[146:149], v[168:171], v[118:121]
	v_mfma_f32_16x16x32_bf16 v[114:117], v[156:159], v[168:171], v[114:117]
	v_mfma_f32_16x16x32_bf16 v[102:105], v[146:149], v[176:179], v[102:105]
	v_mfma_f32_16x16x32_bf16 v[98:101], v[156:159], v[176:179], v[98:101]
	v_mfma_f32_16x16x32_bf16 v[86:89], v[146:149], v[188:191], v[86:89]
	v_mfma_f32_16x16x32_bf16 v[82:85], v[156:159], v[188:191], v[82:85]
	v_mfma_f32_16x16x32_bf16 v[70:73], v[146:149], v[196:199], v[70:73]
	v_mfma_f32_16x16x32_bf16 v[66:69], v[156:159], v[196:199], v[66:69]
	v_mfma_f32_16x16x32_bf16 v[118:121], v[150:153], v[172:175], v[118:121]
	v_mfma_f32_16x16x32_bf16 v[114:117], v[160:163], v[172:175], v[114:117]
	v_mfma_f32_16x16x32_bf16 v[102:105], v[150:153], v[180:183], v[102:105]
	v_mfma_f32_16x16x32_bf16 v[98:101], v[160:163], v[180:183], v[98:101]
	v_mfma_f32_16x16x32_bf16 v[86:89], v[150:153], v[192:195], v[86:89]
	v_mfma_f32_16x16x32_bf16 v[82:85], v[160:163], v[192:195], v[82:85]
	v_mfma_f32_16x16x32_bf16 v[70:73], v[150:153], v[200:203], v[70:73]
	v_mfma_f32_16x16x32_bf16 v[66:69], v[160:163], v[200:203], v[66:69]
	s_barrier
	s_setprio 0
	s_mov_b32 m0, s3
	v_lshl_add_u64 v[184:185], s[8:9], 0, v[154:155]
	ds_read_b128 v[168:171], v167 offset:16384
	ds_read_b128 v[172:175], v167 offset:17408
	ds_read_b128 v[176:179], v167 offset:18432
	ds_read_b128 v[180:183], v167 offset:19456
	ds_read_b128 v[188:191], v167 offset:20480
	ds_read_b128 v[192:195], v167 offset:21504
	ds_read_b128 v[196:199], v167 offset:22528
	ds_read_b128 v[200:203], v167 offset:23552
	global_load_lds_dwordx4 v[184:185], off
	v_lshl_add_u64 v[204:205], v[184:185], 0, s[70:71]
	s_mov_b32 m0, s22
	s_nop 0
	global_load_lds_dwordx4 v[204:205], off
	v_lshl_add_u64 v[204:205], v[184:185], 0, s[96:97]
	s_mov_b32 m0, s24
	s_nop 0
	global_load_lds_dwordx4 v[204:205], off
	v_lshl_add_u64 v[204:205], v[184:185], 0, s[60:61]
	s_mov_b32 m0, s25
	s_nop 0
	global_load_lds_dwordx4 v[204:205], off
	v_lshl_add_u64 v[204:205], vcc, 0, v[154:155]
	s_mov_b32 m0, s26
	v_lshl_add_u64 v[206:207], v[204:205], 0, s[70:71]
	global_load_lds_dwordx4 v[204:205], off
	s_mov_b32 m0, s27
	s_nop 0
	global_load_lds_dwordx4 v[206:207], off
	s_waitcnt vmcnt(8)
	s_waitcnt lgkmcnt(0)
	s_setprio 1
	s_barrier
	v_mfma_f32_16x16x32_bf16 v[62:65], v[130:133], v[168:171], v[62:65]
	v_mfma_f32_16x16x32_bf16 v[58:61], v[138:141], v[168:171], v[58:61]
	v_mfma_f32_16x16x32_bf16 v[46:49], v[130:133], v[176:179], v[46:49]
	v_mfma_f32_16x16x32_bf16 v[42:45], v[138:141], v[176:179], v[42:45]
	v_mfma_f32_16x16x32_bf16 v[30:33], v[130:133], v[188:191], v[30:33]
	v_mfma_f32_16x16x32_bf16 v[26:29], v[138:141], v[188:191], v[26:29]
	v_mfma_f32_16x16x32_bf16 v[14:17], v[130:133], v[196:199], v[14:17]
	v_mfma_f32_16x16x32_bf16 v[10:13], v[138:141], v[196:199], v[10:13]
	v_mfma_f32_16x16x32_bf16 v[62:65], v[134:137], v[172:175], v[62:65]
	v_mfma_f32_16x16x32_bf16 v[58:61], v[142:145], v[172:175], v[58:61]
	v_mfma_f32_16x16x32_bf16 v[46:49], v[134:137], v[180:183], v[46:49]
	v_mfma_f32_16x16x32_bf16 v[42:45], v[142:145], v[180:183], v[42:45]
	v_mfma_f32_16x16x32_bf16 v[30:33], v[134:137], v[192:195], v[30:33]
	v_mfma_f32_16x16x32_bf16 v[26:29], v[142:145], v[192:195], v[26:29]
	v_mfma_f32_16x16x32_bf16 v[14:17], v[134:137], v[200:203], v[14:17]
	v_mfma_f32_16x16x32_bf16 v[10:13], v[142:145], v[200:203], v[10:13]
	v_mfma_f32_16x16x32_bf16 v[54:57], v[146:149], v[168:171], v[54:57]
	v_mfma_f32_16x16x32_bf16 v[50:53], v[156:159], v[168:171], v[50:53]
	v_mfma_f32_16x16x32_bf16 v[38:41], v[146:149], v[176:179], v[38:41]
	v_mfma_f32_16x16x32_bf16 v[34:37], v[156:159], v[176:179], v[34:37]
	v_mfma_f32_16x16x32_bf16 v[22:25], v[146:149], v[188:191], v[22:25]
	v_mfma_f32_16x16x32_bf16 v[18:21], v[156:159], v[188:191], v[18:21]
	v_mfma_f32_16x16x32_bf16 v[6:9], v[146:149], v[196:199], v[6:9]
	v_mfma_f32_16x16x32_bf16 v[2:5], v[156:159], v[196:199], v[2:5]
	v_mfma_f32_16x16x32_bf16 v[54:57], v[150:153], v[172:175], v[54:57]
	v_mfma_f32_16x16x32_bf16 v[50:53], v[160:163], v[172:175], v[50:53]
	v_mfma_f32_16x16x32_bf16 v[38:41], v[150:153], v[180:183], v[38:41]
	v_mfma_f32_16x16x32_bf16 v[34:37], v[160:163], v[180:183], v[34:37]
	v_mfma_f32_16x16x32_bf16 v[22:25], v[150:153], v[192:195], v[22:25]
	v_mfma_f32_16x16x32_bf16 v[18:21], v[160:163], v[192:195], v[18:21]
	v_mfma_f32_16x16x32_bf16 v[6:9], v[150:153], v[200:203], v[6:9]
	v_mfma_f32_16x16x32_bf16 v[2:5], v[160:163], v[200:203], v[2:5]
	s_barrier
; #define PG8_STAGE(bufoff, gbase, unused) do { _Pragma("unroll") for (int _i = 0; _i < 2; ++_i) \
;         __builtin_amdgcn_global_load_lds((const unsigned*)((const char*)(gbase) + voff + _i * 8192), (LAS unsigned*)(lds + (bufoff) + ldsw + _i * 8192), 16, 0, 0); } while (0)
; #define PG8_LDA(dst, b, h) do { _Pragma("unroll") for (int m = 0; m < 4; ++m) _Pragma("unroll") for (int k = 0; k < 2; ++k) dst[m][k] = *(const LAS bf16x8*)(lds + PG8_SA(b, h) + aoff + m * 2048 + (FP8 ? k * 16 : k * 1024)); } while (0)
; #define PG8_LDB(dst, b, h) do { _Pragma("unroll") for (int n = 0; n < 2; ++n) _Pragma("unroll") for (int k = 0; k < 2; ++k) dst[n][k] = *(const LAS bf16x8*)(lds + PG8_SB(b, h) + boff + n * 2048 + (FP8 ? k * 16 : k * 1024)); } while (0)
; #define PG8_WAIT_V(n) asm volatile("s_waitcnt vmcnt(" #n ")" ::: "memory")
; #define PG8_WAIT_L(n) asm volatile("s_waitcnt lgkmcnt(" #n ")" ::: "memory")
; #define PG8_BAR __builtin_amdgcn_s_barrier()
; #define PG8_SCHED __builtin_amdgcn_sched_barrier(0)
; template <class Epi, class Sched, bool ALIGN_EPI, bool SP2, int MODE  >
; __device__ __forceinline__ void gemm_phase(LAS unsigned char* lds, const Gemm g, const Sched S, const Epi E, unsigned long long& probe_acc, int epi_id, int wv) {
;     ...
;             PG8_LDB(B0, 1, 0); PG8_LDB(B1, 1, 1); PG8_SCHED; PG8_LDA(At, 1, 0); PG8_STAGE(PG8_SA(0, 1), a2 + hA, voffA);
;             PG8_WAIT_V(8); PG8_WAIT_L(0); PG8_BAR; PG8_MMA(0, 0, At, B0); PG8_MMA(0, 1, At, B1); PG8_BAR; PG8_SCHED;
;             PG8_LDA(At, 1, 1); PG8_STAGE(PG8_SB(1, 0), b3, voffB); PG8_STAGE(PG8_SB(1, 1), b3 + hB, voffB); PG8_STAGE(PG8_SA(1, 0), a3, voffA);
;             PG8_WAIT_V(8); PG8_WAIT_L(0); PG8_BAR; PG8_MMA(1, 0, At, B0); PG8_MMA(1, 1, At, B1); PG8_BAR; PG8_SCHED;
;     ...
;         if constexpr (ALIGN_EPI) { if (wr == 0) PG8_BAR; }
	s_setprio 0
	v_add_u32_e32 v0, s31, v166
	ds_read_b128 v[130:133], v0
	ds_read_b128 v[134:137], v0 offset:1024
	ds_read_b128 v[138:141], v0 offset:2048
	ds_read_b128 v[142:145], v0 offset:3072
	v_add_u32_e32 v0, s39, v166
	ds_read_b128 v[146:149], v0
	ds_read_b128 v[150:153], v0 offset:1024
	ds_read_b128 v[156:159], v0 offset:2048
	ds_read_b128 v[160:163], v0 offset:3072
	s_mov_b32 m0, s28
	v_lshl_add_u64 v[206:207], v[204:205], 0, s[96:97]
	ds_read_b128 v[168:171], v167 offset:32768
	ds_read_b128 v[172:175], v167 offset:33792
	ds_read_b128 v[176:179], v167 offset:34816
	ds_read_b128 v[180:183], v167 offset:35840
	ds_read_b128 v[188:191], v167 offset:36864
	ds_read_b128 v[192:195], v167 offset:37888
	ds_read_b128 v[196:199], v167 offset:38912
	ds_read_b128 v[200:203], v167 offset:39936
	global_load_lds_dwordx4 v[206:207], off
	v_lshl_add_u64 v[206:207], v[204:205], 0, s[60:61]
	s_mov_b32 m0, s29
	s_nop 0
	global_load_lds_dwordx4 v[206:207], off
	s_waitcnt vmcnt(8)
	s_waitcnt lgkmcnt(0)
	s_setprio 1
	s_barrier
	v_mfma_f32_16x16x32_bf16 v[126:129], v[130:133], v[168:171], v[126:129]
	v_mfma_f32_16x16x32_bf16 v[122:125], v[138:141], v[168:171], v[122:125]
	v_mfma_f32_16x16x32_bf16 v[110:113], v[130:133], v[176:179], v[110:113]
	v_mfma_f32_16x16x32_bf16 v[106:109], v[138:141], v[176:179], v[106:109]
	v_mfma_f32_16x16x32_bf16 v[94:97], v[130:133], v[188:191], v[94:97]
	v_mfma_f32_16x16x32_bf16 v[90:93], v[138:141], v[188:191], v[90:93]
	v_mfma_f32_16x16x32_bf16 v[78:81], v[130:133], v[196:199], v[78:81]
	v_mfma_f32_16x16x32_bf16 v[74:77], v[138:141], v[196:199], v[74:77]
	v_mfma_f32_16x16x32_bf16 v[126:129], v[134:137], v[172:175], v[126:129]
	v_mfma_f32_16x16x32_bf16 v[122:125], v[142:145], v[172:175], v[122:125]
	v_mfma_f32_16x16x32_bf16 v[110:113], v[134:137], v[180:183], v[110:113]
	v_mfma_f32_16x16x32_bf16 v[106:109], v[142:145], v[180:183], v[106:109]
	v_mfma_f32_16x16x32_bf16 v[94:97], v[134:137], v[192:195], v[94:97]
	v_mfma_f32_16x16x32_bf16 v[90:93], v[142:145], v[192:195], v[90:93]
	v_mfma_f32_16x16x32_bf16 v[78:81], v[134:137], v[200:203], v[78:81]
	v_mfma_f32_16x16x32_bf16 v[74:77], v[142:145], v[200:203], v[74:77]
	v_mfma_f32_16x16x32_bf16 v[118:121], v[146:149], v[168:171], v[118:121]
	v_mfma_f32_16x16x32_bf16 v[114:117], v[156:159], v[168:171], v[114:117]
	v_mfma_f32_16x16x32_bf16 v[102:105], v[146:149], v[176:179], v[102:105]
	v_mfma_f32_16x16x32_bf16 v[98:101], v[156:159], v[176:179], v[98:101]
	v_mfma_f32_16x16x32_bf16 v[86:89], v[146:149], v[188:191], v[86:89]
	v_mfma_f32_16x16x32_bf16 v[82:85], v[156:159], v[188:191], v[82:85]
	v_mfma_f32_16x16x32_bf16 v[70:73], v[146:149], v[196:199], v[70:73]
	v_mfma_f32_16x16x32_bf16 v[66:69], v[156:159], v[196:199], v[66:69]
	v_mfma_f32_16x16x32_bf16 v[118:121], v[150:153], v[172:175], v[118:121]
	v_mfma_f32_16x16x32_bf16 v[114:117], v[160:163], v[172:175], v[114:117]
	v_mfma_f32_16x16x32_bf16 v[102:105], v[150:153], v[180:183], v[102:105]
	v_mfma_f32_16x16x32_bf16 v[98:101], v[160:163], v[180:183], v[98:101]
	v_mfma_f32_16x16x32_bf16 v[86:89], v[150:153], v[192:195], v[86:89]
	v_mfma_f32_16x16x32_bf16 v[82:85], v[160:163], v[192:195], v[82:85]
	v_mfma_f32_16x16x32_bf16 v[70:73], v[150:153], v[200:203], v[70:73]
	v_mfma_f32_16x16x32_bf16 v[66:69], v[160:163], v[200:203], v[66:69]
	s_barrier
	s_setprio 0
	s_mov_b32 m0, s34
	v_lshl_add_u64 v[206:207], v[184:185], 0, s[76:77]
	ds_read_b128 v[168:171], v167 offset:49152
	ds_read_b128 v[172:175], v167 offset:50176
	ds_read_b128 v[176:179], v167 offset:51200
	ds_read_b128 v[180:183], v167 offset:52224
	ds_read_b128 v[188:191], v167 offset:53248
	ds_read_b128 v[192:195], v167 offset:54272
	ds_read_b128 v[196:199], v167 offset:55296
	ds_read_b128 v[200:203], v167 offset:56320
	global_load_lds_dwordx4 v[206:207], off
	v_lshl_add_u64 v[206:207], v[184:185], 0, s[78:79]
	s_mov_b32 m0, s35
	s_nop 0
	global_load_lds_dwordx4 v[206:207], off
	v_lshl_add_u64 v[206:207], v[184:185], 0, s[52:53]
	s_mov_b32 m0, s40
	v_lshl_add_u64 v[184:185], v[184:185], 0, s[54:55]
	global_load_lds_dwordx4 v[206:207], off
	s_mov_b32 m0, s41
	s_nop 0
	global_load_lds_dwordx4 v[184:185], off
	v_lshl_add_u64 v[184:185], v[204:205], 0, s[76:77]
	s_mov_b32 m0, s36
	s_nop 0
	global_load_lds_dwordx4 v[184:185], off
	v_lshl_add_u64 v[184:185], v[204:205], 0, s[78:79]
	s_mov_b32 m0, s37
	s_nop 0
	global_load_lds_dwordx4 v[184:185], off
	s_waitcnt vmcnt(8)
	s_waitcnt lgkmcnt(0)
	s_setprio 1
	s_barrier
	v_mfma_f32_16x16x32_bf16 v[62:65], v[130:133], v[168:171], v[62:65]
	v_mfma_f32_16x16x32_bf16 v[58:61], v[138:141], v[168:171], v[58:61]
	v_mfma_f32_16x16x32_bf16 v[46:49], v[130:133], v[176:179], v[46:49]
	v_mfma_f32_16x16x32_bf16 v[42:45], v[138:141], v[176:179], v[42:45]
	v_mfma_f32_16x16x32_bf16 v[30:33], v[130:133], v[188:191], v[30:33]
	v_mfma_f32_16x16x32_bf16 v[26:29], v[138:141], v[188:191], v[26:29]
	v_mfma_f32_16x16x32_bf16 v[14:17], v[130:133], v[196:199], v[14:17]
	v_mfma_f32_16x16x32_bf16 v[10:13], v[138:141], v[196:199], v[10:13]
	v_mfma_f32_16x16x32_bf16 v[62:65], v[134:137], v[172:175], v[62:65]
	v_mfma_f32_16x16x32_bf16 v[58:61], v[142:145], v[172:175], v[58:61]
	v_mfma_f32_16x16x32_bf16 v[46:49], v[134:137], v[180:183], v[46:49]
	v_mfma_f32_16x16x32_bf16 v[42:45], v[142:145], v[180:183], v[42:45]
	v_mfma_f32_16x16x32_bf16 v[30:33], v[134:137], v[192:195], v[30:33]
	v_mfma_f32_16x16x32_bf16 v[26:29], v[142:145], v[192:195], v[26:29]
	v_mfma_f32_16x16x32_bf16 v[14:17], v[134:137], v[200:203], v[14:17]
	v_mfma_f32_16x16x32_bf16 v[10:13], v[142:145], v[200:203], v[10:13]
	v_mfma_f32_16x16x32_bf16 v[54:57], v[146:149], v[168:171], v[54:57]
	v_mfma_f32_16x16x32_bf16 v[50:53], v[156:159], v[168:171], v[50:53]
	v_mfma_f32_16x16x32_bf16 v[38:41], v[146:149], v[176:179], v[38:41]
	v_mfma_f32_16x16x32_bf16 v[34:37], v[156:159], v[176:179], v[34:37]
	v_mfma_f32_16x16x32_bf16 v[22:25], v[146:149], v[188:191], v[22:25]
	v_mfma_f32_16x16x32_bf16 v[18:21], v[156:159], v[188:191], v[18:21]
	v_mfma_f32_16x16x32_bf16 v[6:9], v[146:149], v[196:199], v[6:9]
	v_mfma_f32_16x16x32_bf16 v[2:5], v[156:159], v[196:199], v[2:5]
	v_mfma_f32_16x16x32_bf16 v[54:57], v[150:153], v[172:175], v[54:57]
	v_mfma_f32_16x16x32_bf16 v[50:53], v[160:163], v[172:175], v[50:53]
	v_mfma_f32_16x16x32_bf16 v[38:41], v[150:153], v[180:183], v[38:41]
	v_mfma_f32_16x16x32_bf16 v[34:37], v[160:163], v[180:183], v[34:37]
	v_mfma_f32_16x16x32_bf16 v[22:25], v[150:153], v[192:195], v[22:25]
	v_mfma_f32_16x16x32_bf16 v[18:21], v[160:163], v[192:195], v[18:21]
	v_mfma_f32_16x16x32_bf16 v[6:9], v[150:153], v[200:203], v[6:9]
	v_mfma_f32_16x16x32_bf16 v[2:5], v[160:163], v[200:203], v[2:5]
	s_barrier
	s_setprio 0
	s_add_i32 s95, s95, 2
	s_add_u32 s93, s93, 0x8000
	s_addc_u32 s94, s94, 0
	s_cmp_gt_u32 s95, 29
	s_mov_b64 s[18:19], s[20:21]
	s_cbranch_scc0 .LBB0_365
	s_and_b64 vcc, exec, s[14:15]
	s_cbranch_vccz .LBB0_368
	s_barrier

; #define PG8_STAGE(bufoff, gbase, unused) do { _Pragma("unroll") for (int _i = 0; _i < 2; ++_i) \
;         __builtin_amdgcn_global_load_lds((const unsigned*)((const char*)(gbase) + voff + _i * 8192), (LAS unsigned*)(lds + (bufoff) + ldsw + _i * 8192), 16, 0, 0); } while (0)
; #define PG8_LDA(dst, b, h) do { _Pragma("unroll") for (int m = 0; m < 4; ++m) _Pragma("unroll") for (int k = 0; k < 2; ++k) dst[m][k] = *(const LAS bf16x8*)(lds + PG8_SA(b, h) + aoff + m * 2048 + (FP8 ? k * 16 : k * 1024)); } while (0)
; #define PG8_LDB(dst, b, h) do { _Pragma("unroll") for (int n = 0; n < 2; ++n) _Pragma("unroll") for (int k = 0; k < 2; ++k) dst[n][k] = *(const LAS bf16x8*)(lds + PG8_SB(b, h) + boff + n * 2048 + (FP8 ? k * 16 : k * 1024)); } while (0)
; #define PG8_WAIT_V(n) asm volatile("s_waitcnt vmcnt(" #n ")" ::: "memory")
; #define PG8_WAIT_L(n) asm volatile("s_waitcnt lgkmcnt(" #n ")" ::: "memory")
; #define PG8_BAR __builtin_amdgcn_s_barrier()
; #define PG8_SCHED __builtin_amdgcn_sched_barrier(0)
; template <class Epi, class Sched, bool ALIGN_EPI, bool SP2, int MODE  >
; __device__ __forceinline__ void gemm_phase(LAS unsigned char* lds, const Gemm g, const Sched S, const Epi E, unsigned long long& probe_acc, int epi_id, int wv) {
;     ...
;                 for (int n = 0; n < 2; ++n) acc[a][b][m][n] = (f32x4){0.f, 0.f, 0.f, 0.f};
;     ...
;             PG8_LDB(B0, 0, 0); PG8_SCHED; PG8_LDA(At, 0, 0); PG8_STAGE(PG8_SA(1, 1), a1 + hA, voffA);
;             PG8_WAIT_L(8); PG8_BAR; PG8_WAIT_L(0); PG8_MMA(0, 0, At, B0); PG8_BAR; PG8_SCHED;
;             PG8_LDB(B1, 0, 1); PG8_STAGE(PG8_SB(0, 0), b2, voffB);
;             PG8_BAR; PG8_WAIT_L(0); PG8_MMA(0, 1, At, B1); PG8_BAR;
;             PG8_LDA(At, 0, 1); PG8_STAGE(PG8_SA(0, 0), a2, voffA);
;             PG8_BAR; PG8_WAIT_L(0); PG8_MMA(1, 0, At, B0); PG8_BAR; PG8_SCHED;
;             PG8_STAGE(PG8_SB(0, 1), b2 + hB, voffB);
;             PG8_WAIT_V(6); PG8_BAR; PG8_MMA(1, 1, At, B1); PG8_BAR;
.LBB0_673:
	s_add_u32 s10, s4, 0x8000
	s_addc_u32 s11, s5, 0
	s_add_u32 s4, s6, 0x8000
	s_addc_u32 s5, s7, 0
	s_mov_b32 s6, 0
	s_waitcnt lgkmcnt(0)
	s_waitcnt vmcnt(0)
	v_add_u32_e32 v142, s15, v193
	v_add_u32_e32 v156, s39, v193
	ds_read_b128 v[130:133], v142
	ds_read_b128 v[134:137], v142 offset:1024
	ds_read_b128 v[138:141], v142 offset:2048
	ds_read_b128 v[142:145], v142 offset:3072
	ds_read_b128 v[146:149], v156
	ds_read_b128 v[150:153], v156 offset:1024
	ds_read_b128 v[158:161], v156 offset:2048
	ds_read_b128 v[162:165], v156 offset:3072
	s_add_i32 s40, s6, 2
	s_cmp_eq_u32 s93, s6
	s_cselect_b32 s6, s34, s10
	s_cselect_b32 s9, s87, s5
	s_cselect_b32 s8, s86, s4
	s_cselect_b32 s7, s35, s11
	s_movk_i32 vcc_lo, 0xc000
	v_lshl_add_u64 v[190:191], s[4:5], 0, v[154:155]
	s_mov_b32 vcc_hi, -1
	v_lshl_add_u64 v[196:197], v[190:191], 0, vcc
	s_movk_i32 vcc_lo, 0xe000
	s_add_i32 m0, s88, 0xc000
	s_mov_b32 vcc_hi, -1
	ds_read_b128 v[166:169], v194
	ds_read_b128 v[170:173], v194 offset:1024
	ds_read_b128 v[174:177], v194 offset:2048
	ds_read_b128 v[178:181], v194 offset:3072
	ds_read_b128 v[182:185], v194 offset:4096
	ds_read_b128 v[186:189], v194 offset:5120
	ds_read_b128 v[200:203], v194 offset:6144
	ds_read_b128 v[204:207], v194 offset:7168
	global_load_lds_dwordx4 v[196:197], off
	v_lshl_add_u64 v[190:191], v[190:191], 0, vcc
	s_add_i32 m0, s88, 0xe000
	s_nop 0
	global_load_lds_dwordx4 v[190:191], off
	s_waitcnt vmcnt(8)
	s_waitcnt lgkmcnt(0)
	s_setprio 1
	s_barrier
	v_mfma_f32_16x16x32_bf16 v[126:129], v[130:133], v[166:169], 0
	v_mfma_f32_16x16x32_bf16 v[122:125], v[138:141], v[166:169], 0
	v_mfma_f32_16x16x32_bf16 v[118:121], v[130:133], v[174:177], 0
	v_mfma_f32_16x16x32_bf16 v[114:117], v[138:141], v[174:177], 0
	v_mfma_f32_16x16x32_bf16 v[110:113], v[130:133], v[182:185], 0
	v_mfma_f32_16x16x32_bf16 v[106:109], v[138:141], v[182:185], 0
	v_mfma_f32_16x16x32_bf16 v[102:105], v[130:133], v[200:203], 0
	v_mfma_f32_16x16x32_bf16 v[98:101], v[138:141], v[200:203], 0
	v_mfma_f32_16x16x32_bf16 v[126:129], v[134:137], v[170:173], v[126:129]
	v_mfma_f32_16x16x32_bf16 v[122:125], v[142:145], v[170:173], v[122:125]
	v_mfma_f32_16x16x32_bf16 v[118:121], v[134:137], v[178:181], v[118:121]
	v_mfma_f32_16x16x32_bf16 v[114:117], v[142:145], v[178:181], v[114:117]
	v_mfma_f32_16x16x32_bf16 v[110:113], v[134:137], v[186:189], v[110:113]
	v_mfma_f32_16x16x32_bf16 v[106:109], v[142:145], v[186:189], v[106:109]
	v_mfma_f32_16x16x32_bf16 v[102:105], v[134:137], v[204:207], v[102:105]
	v_mfma_f32_16x16x32_bf16 v[98:101], v[142:145], v[204:207], v[98:101]
	v_mfma_f32_16x16x32_bf16 v[62:65], v[146:149], v[166:169], 0
	v_mfma_f32_16x16x32_bf16 v[58:61], v[158:161], v[166:169], 0
	v_mfma_f32_16x16x32_bf16 v[54:57], v[146:149], v[174:177], 0
	v_mfma_f32_16x16x32_bf16 v[50:53], v[158:161], v[174:177], 0
	v_mfma_f32_16x16x32_bf16 v[46:49], v[146:149], v[182:185], 0
	v_mfma_f32_16x16x32_bf16 v[42:45], v[158:161], v[182:185], 0
	v_mfma_f32_16x16x32_bf16 v[38:41], v[146:149], v[200:203], 0
	v_mfma_f32_16x16x32_bf16 v[34:37], v[158:161], v[200:203], 0
	v_mfma_f32_16x16x32_bf16 v[62:65], v[150:153], v[170:173], v[62:65]
	v_mfma_f32_16x16x32_bf16 v[58:61], v[162:165], v[170:173], v[58:61]
	v_mfma_f32_16x16x32_bf16 v[54:57], v[150:153], v[178:181], v[54:57]
	v_mfma_f32_16x16x32_bf16 v[50:53], v[162:165], v[178:181], v[50:53]
	v_mfma_f32_16x16x32_bf16 v[46:49], v[150:153], v[186:189], v[46:49]
	v_mfma_f32_16x16x32_bf16 v[42:45], v[162:165], v[186:189], v[42:45]
	v_mfma_f32_16x16x32_bf16 v[38:41], v[150:153], v[204:207], v[38:41]
	v_mfma_f32_16x16x32_bf16 v[34:37], v[162:165], v[204:207], v[34:37]
	s_barrier
	s_setprio 0
	s_mov_b32 m0, s26
	v_lshl_add_u64 v[190:191], s[6:7], 0, v[0:1]
	s_add_u32 vcc_lo, s6, s13
	ds_read_b128 v[166:169], v194 offset:16384
	ds_read_b128 v[170:173], v194 offset:17408
	ds_read_b128 v[174:177], v194 offset:18432
	ds_read_b128 v[178:181], v194 offset:19456
	ds_read_b128 v[182:185], v194 offset:20480
	ds_read_b128 v[186:189], v194 offset:21504
	ds_read_b128 v[200:203], v194 offset:22528
	ds_read_b128 v[204:207], v194 offset:23552
	global_load_lds_dwordx4 v[190:191], off
	v_lshl_add_u64 v[190:191], v[190:191], 0, s[70:71]
	s_mov_b32 m0, s27
	s_addc_u32 vcc_hi, s7, 0
	global_load_lds_dwordx4 v[190:191], off
	v_lshl_add_u64 v[190:191], vcc, 0, v[0:1]
	s_mov_b32 m0, s84
	s_nop 0
	global_load_lds_dwordx4 v[190:191], off
	v_lshl_add_u64 v[190:191], v[190:191], 0, s[70:71]
	s_mov_b32 m0, s85
	s_nop 0
	global_load_lds_dwordx4 v[190:191], off
	v_lshl_add_u64 v[190:191], s[8:9], 0, v[0:1]
	s_mov_b32 m0, s88
	v_lshl_add_u64 v[196:197], v[190:191], 0, s[70:71]
	global_load_lds_dwordx4 v[190:191], off
	s_mov_b32 m0, s89
	s_nop 0
	global_load_lds_dwordx4 v[196:197], off
	s_waitcnt vmcnt(8)
	s_waitcnt lgkmcnt(0)
	s_setprio 1
	s_barrier
; #define PG8_STAGE(bufoff, gbase, unused) do { _Pragma("unroll") for (int _i = 0; _i < 2; ++_i) \
;         __builtin_amdgcn_global_load_lds((const unsigned*)((const char*)(gbase) + voff + _i * 8192), (LAS unsigned*)(lds + (bufoff) + ldsw + _i * 8192), 16, 0, 0); } while (0)
; #define PG8_LDA(dst, b, h) do { _Pragma("unroll") for (int m = 0; m < 4; ++m) _Pragma("unroll") for (int k = 0; k < 2; ++k) dst[m][k] = *(const LAS bf16x8*)(lds + PG8_SA(b, h) + aoff + m * 2048 + (FP8 ? k * 16 : k * 1024)); } while (0)
; #define PG8_LDB(dst, b, h) do { _Pragma("unroll") for (int n = 0; n < 2; ++n) _Pragma("unroll") for (int k = 0; k < 2; ++k) dst[n][k] = *(const LAS bf16x8*)(lds + PG8_SB(b, h) + boff + n * 2048 + (FP8 ? k * 16 : k * 1024)); } while (0)
; #define PG8_WAIT_V(n) asm volatile("s_waitcnt vmcnt(" #n ")" ::: "memory")
; #define PG8_WAIT_L(n) asm volatile("s_waitcnt lgkmcnt(" #n ")" ::: "memory")
; #define PG8_BAR __builtin_amdgcn_s_barrier()
; #define PG8_SCHED __builtin_amdgcn_sched_barrier(0)
; template <class Epi, class Sched, bool ALIGN_EPI, bool SP2, int MODE  >
; __device__ __forceinline__ void gemm_phase(LAS unsigned char* lds, const Gemm g, const Sched S, const Epi E, unsigned long long& probe_acc, int epi_id, int wv) {
;     ...
;             PG8_BAR; PG8_WAIT_L(0); PG8_MMA(1, 0, At, B0); PG8_BAR; PG8_SCHED;
;             PG8_STAGE(PG8_SB(0, 1), b2 + hB, voffB);
;             PG8_WAIT_V(6); PG8_BAR; PG8_MMA(1, 1, At, B1); PG8_BAR;
;             PG8_LDB(B0, 1, 0); PG8_SCHED; PG8_LDA(At, 1, 0); PG8_STAGE(PG8_SA(0, 1), a2 + hA, voffA);
;             PG8_WAIT_L(8); PG8_BAR; PG8_WAIT_L(0); PG8_MMA(0, 0, At, B0); PG8_BAR; PG8_SCHED;
;             PG8_LDB(B1, 1, 1); PG8_STAGE(PG8_SB(1, 0), b3, voffB);
;             PG8_BAR; PG8_WAIT_L(0); PG8_MMA(0, 1, At, B1); PG8_BAR;
;             PG8_LDA(At, 1, 1); PG8_STAGE(PG8_SA(1, 0), a3, voffA);
;             PG8_BAR; PG8_WAIT_L(0); PG8_MMA(1, 0, At, B0); PG8_BAR; PG8_SCHED;
	v_mfma_f32_16x16x32_bf16 v[94:97], v[130:133], v[166:169], 0
	v_mfma_f32_16x16x32_bf16 v[90:93], v[138:141], v[166:169], 0
	v_mfma_f32_16x16x32_bf16 v[86:89], v[130:133], v[174:177], 0
	v_mfma_f32_16x16x32_bf16 v[82:85], v[138:141], v[174:177], 0
	v_mfma_f32_16x16x32_bf16 v[78:81], v[130:133], v[182:185], 0
	v_mfma_f32_16x16x32_bf16 v[74:77], v[138:141], v[182:185], 0
	v_mfma_f32_16x16x32_bf16 v[70:73], v[130:133], v[200:203], 0
	v_mfma_f32_16x16x32_bf16 v[66:69], v[138:141], v[200:203], 0
	v_mfma_f32_16x16x32_bf16 v[94:97], v[134:137], v[170:173], v[94:97]
	v_mfma_f32_16x16x32_bf16 v[90:93], v[142:145], v[170:173], v[90:93]
	v_mfma_f32_16x16x32_bf16 v[86:89], v[134:137], v[178:181], v[86:89]
	v_mfma_f32_16x16x32_bf16 v[82:85], v[142:145], v[178:181], v[82:85]
	v_mfma_f32_16x16x32_bf16 v[78:81], v[134:137], v[186:189], v[78:81]
	v_mfma_f32_16x16x32_bf16 v[74:77], v[142:145], v[186:189], v[74:77]
	v_mfma_f32_16x16x32_bf16 v[70:73], v[134:137], v[204:207], v[70:73]
	v_mfma_f32_16x16x32_bf16 v[66:69], v[142:145], v[204:207], v[66:69]
	v_mfma_f32_16x16x32_bf16 v[30:33], v[146:149], v[166:169], 0
	v_mfma_f32_16x16x32_bf16 v[26:29], v[158:161], v[166:169], 0
	v_mfma_f32_16x16x32_bf16 v[22:25], v[146:149], v[174:177], 0
	v_mfma_f32_16x16x32_bf16 v[18:21], v[158:161], v[174:177], 0
	v_mfma_f32_16x16x32_bf16 v[14:17], v[146:149], v[182:185], 0
	v_mfma_f32_16x16x32_bf16 v[10:13], v[158:161], v[182:185], 0
	v_mfma_f32_16x16x32_bf16 v[6:9], v[146:149], v[200:203], 0
	v_mfma_f32_16x16x32_bf16 v[2:5], v[158:161], v[200:203], 0
	v_mfma_f32_16x16x32_bf16 v[30:33], v[150:153], v[170:173], v[30:33]
	v_mfma_f32_16x16x32_bf16 v[26:29], v[162:165], v[170:173], v[26:29]
	v_mfma_f32_16x16x32_bf16 v[22:25], v[150:153], v[178:181], v[22:25]
	v_mfma_f32_16x16x32_bf16 v[18:21], v[162:165], v[178:181], v[18:21]
	v_mfma_f32_16x16x32_bf16 v[14:17], v[150:153], v[186:189], v[14:17]
	v_mfma_f32_16x16x32_bf16 v[10:13], v[162:165], v[186:189], v[10:13]
	v_mfma_f32_16x16x32_bf16 v[6:9], v[150:153], v[204:207], v[6:9]
	v_mfma_f32_16x16x32_bf16 v[2:5], v[162:165], v[204:207], v[2:5]
	s_barrier
	s_setprio 0
	v_add_u32_e32 v142, s28, v193
	v_add_u32_e32 v156, s94, v193
	ds_read_b128 v[130:133], v142
	ds_read_b128 v[134:137], v142 offset:1024
	ds_read_b128 v[138:141], v142 offset:2048
	ds_read_b128 v[142:145], v142 offset:3072
	ds_read_b128 v[146:149], v156
	ds_read_b128 v[150:153], v156 offset:1024
	ds_read_b128 v[158:161], v156 offset:2048
	ds_read_b128 v[162:165], v156 offset:3072
	s_add_u32 s8, s8, s36
	s_addc_u32 s9, s9, 0
	s_mov_b32 m0, s29
	v_lshl_add_u64 v[196:197], s[8:9], 0, v[0:1]
	ds_read_b128 v[166:169], v194 offset:32768
	ds_read_b128 v[170:173], v194 offset:33792
	ds_read_b128 v[174:177], v194 offset:34816
	ds_read_b128 v[178:181], v194 offset:35840
	ds_read_b128 v[182:185], v194 offset:36864
	ds_read_b128 v[186:189], v194 offset:37888
	ds_read_b128 v[200:203], v194 offset:38912
	ds_read_b128 v[204:207], v194 offset:39936
	global_load_lds_dwordx4 v[196:197], off
	v_lshl_add_u64 v[196:197], v[196:197], 0, s[70:71]
	s_mov_b32 m0, s92
	s_nop 0
	global_load_lds_dwordx4 v[196:197], off
	s_waitcnt vmcnt(8)
	s_waitcnt lgkmcnt(0)
	s_setprio 1
	s_barrier
	v_mfma_f32_16x16x32_bf16 v[126:129], v[130:133], v[166:169], v[126:129]
	v_mfma_f32_16x16x32_bf16 v[122:125], v[138:141], v[166:169], v[122:125]
	v_mfma_f32_16x16x32_bf16 v[118:121], v[130:133], v[174:177], v[118:121]
	v_mfma_f32_16x16x32_bf16 v[114:117], v[138:141], v[174:177], v[114:117]
	v_mfma_f32_16x16x32_bf16 v[110:113], v[130:133], v[182:185], v[110:113]
	v_mfma_f32_16x16x32_bf16 v[106:109], v[138:141], v[182:185], v[106:109]
	v_mfma_f32_16x16x32_bf16 v[102:105], v[130:133], v[200:203], v[102:105]
	v_mfma_f32_16x16x32_bf16 v[98:101], v[138:141], v[200:203], v[98:101]
	v_mfma_f32_16x16x32_bf16 v[126:129], v[134:137], v[170:173], v[126:129]
	v_mfma_f32_16x16x32_bf16 v[122:125], v[142:145], v[170:173], v[122:125]
	v_mfma_f32_16x16x32_bf16 v[118:121], v[134:137], v[178:181], v[118:121]
	v_mfma_f32_16x16x32_bf16 v[114:117], v[142:145], v[178:181], v[114:117]
	v_mfma_f32_16x16x32_bf16 v[110:113], v[134:137], v[186:189], v[110:113]
	v_mfma_f32_16x16x32_bf16 v[106:109], v[142:145], v[186:189], v[106:109]
	v_mfma_f32_16x16x32_bf16 v[102:105], v[134:137], v[204:207], v[102:105]
	v_mfma_f32_16x16x32_bf16 v[98:101], v[142:145], v[204:207], v[98:101]
	v_mfma_f32_16x16x32_bf16 v[62:65], v[146:149], v[166:169], v[62:65]
	v_mfma_f32_16x16x32_bf16 v[58:61], v[158:161], v[166:169], v[58:61]
	v_mfma_f32_16x16x32_bf16 v[54:57], v[146:149], v[174:177], v[54:57]
	v_mfma_f32_16x16x32_bf16 v[50:53], v[158:161], v[174:177], v[50:53]
	v_mfma_f32_16x16x32_bf16 v[46:49], v[146:149], v[182:185], v[46:49]
	v_mfma_f32_16x16x32_bf16 v[42:45], v[158:161], v[182:185], v[42:45]
	v_mfma_f32_16x16x32_bf16 v[38:41], v[146:149], v[200:203], v[38:41]
	v_mfma_f32_16x16x32_bf16 v[34:37], v[158:161], v[200:203], v[34:37]
	v_mfma_f32_16x16x32_bf16 v[62:65], v[150:153], v[170:173], v[62:65]
	v_mfma_f32_16x16x32_bf16 v[58:61], v[162:165], v[170:173], v[58:61]
	v_mfma_f32_16x16x32_bf16 v[54:57], v[150:153], v[178:181], v[54:57]
	v_mfma_f32_16x16x32_bf16 v[50:53], v[162:165], v[178:181], v[50:53]
	v_mfma_f32_16x16x32_bf16 v[46:49], v[150:153], v[186:189], v[46:49]
	v_mfma_f32_16x16x32_bf16 v[42:45], v[162:165], v[186:189], v[42:45]
	v_mfma_f32_16x16x32_bf16 v[38:41], v[150:153], v[204:207], v[38:41]
	v_mfma_f32_16x16x32_bf16 v[34:37], v[162:165], v[204:207], v[34:37]
	s_barrier
; #define PG8_STAGE(bufoff, gbase, unused) do { _Pragma("unroll") for (int _i = 0; _i < 2; ++_i) \
;         __builtin_amdgcn_global_load_lds((const unsigned*)((const char*)(gbase) + voff + _i * 8192), (LAS unsigned*)(lds + (bufoff) + ldsw + _i * 8192), 16, 0, 0); } while (0)
; #define PG8_LDA(dst, b, h) do { _Pragma("unroll") for (int m = 0; m < 4; ++m) _Pragma("unroll") for (int k = 0; k < 2; ++k) dst[m][k] = *(const LAS bf16x8*)(lds + PG8_SA(b, h) + aoff + m * 2048 + (FP8 ? k * 16 : k * 1024)); } while (0)
; #define PG8_LDB(dst, b, h) do { _Pragma("unroll") for (int n = 0; n < 2; ++n) _Pragma("unroll") for (int k = 0; k < 2; ++k) dst[n][k] = *(const LAS bf16x8*)(lds + PG8_SB(b, h) + boff + n * 2048 + (FP8 ? k * 16 : k * 1024)); } while (0)
; #define PG8_WAIT_V(n) asm volatile("s_waitcnt vmcnt(" #n ")" ::: "memory")
; #define PG8_WAIT_L(n) asm volatile("s_waitcnt lgkmcnt(" #n ")" ::: "memory")
; #define PG8_BAR __builtin_amdgcn_s_barrier()
; #define PG8_SCHED __builtin_amdgcn_sched_barrier(0)
; template <class Epi, class Sched, bool ALIGN_EPI, bool SP2, int MODE  >
; __device__ __forceinline__ void gemm_phase(LAS unsigned char* lds, const Gemm g, const Sched S, const Epi E, unsigned long long& probe_acc, int epi_id, int wv) {
;     ...
;         for (int t = 0; t < nt; t += 2) {
;             const bool last = (t == nt - 2);
;             const char* a1 = cA + (size_t)(t + 1) * kstep;
;             const char* a2 = last ? nA : cA + (size_t)(t + 2) * kstep; const char* b2 = last ? nB : cB + (size_t)(t + 2) * kstep;
;             const char* a3 = a2 + kstep; const char* b3 = b2 + kstep;
;             if constexpr (SP2) {
;             PG8_LDB(B0, 0, 0); PG8_LDB(B1, 0, 1); PG8_SCHED; PG8_LDA(At, 0, 0); PG8_STAGE(PG8_SA(1, 1), a1 + hA, voffA);
;     ...
;             PG8_LDA(At, 1, 1); PG8_STAGE(PG8_SB(1, 0), b3, voffB); PG8_STAGE(PG8_SB(1, 1), b3 + hB, voffB); PG8_STAGE(PG8_SA(1, 0), a3, voffA);
;             PG8_WAIT_V(8); PG8_WAIT_L(0); PG8_BAR; PG8_MMA(1, 0, At, B0); PG8_MMA(1, 1, At, B1); PG8_BAR; PG8_SCHED;
	s_setprio 0
	s_add_u32 s6, s6, 0x4000
	s_addc_u32 s7, s7, 0
	s_mov_b32 m0, s2
	v_lshl_add_u64 v[196:197], s[6:7], 0, v[0:1]
	s_add_u32 s6, s6, s13
	ds_read_b128 v[166:169], v194 offset:49152
	ds_read_b128 v[170:173], v194 offset:50176
	ds_read_b128 v[174:177], v194 offset:51200
	ds_read_b128 v[178:181], v194 offset:52224
	ds_read_b128 v[182:185], v194 offset:53248
	ds_read_b128 v[186:189], v194 offset:54272
	ds_read_b128 v[200:203], v194 offset:55296
	ds_read_b128 v[204:207], v194 offset:56320
	global_load_lds_dwordx4 v[196:197], off
	v_lshl_add_u64 v[196:197], v[196:197], 0, s[70:71]
	s_mov_b32 m0, s3
	s_addc_u32 s7, s7, 0
	global_load_lds_dwordx4 v[196:197], off
	v_lshl_add_u64 v[196:197], s[6:7], 0, v[0:1]
	s_mov_b32 m0, s12
	s_nop 0
	global_load_lds_dwordx4 v[196:197], off
	v_lshl_add_u64 v[196:197], v[196:197], 0, s[70:71]
	s_mov_b32 m0, s95
	s_nop 0
	global_load_lds_dwordx4 v[196:197], off
	v_lshl_add_u64 v[196:197], v[190:191], 0, s[76:77]
	s_mov_b32 m0, s50
	v_lshl_add_u64 v[190:191], v[190:191], 0, s[78:79]
	global_load_lds_dwordx4 v[196:197], off
	s_mov_b32 m0, s51
	s_nop 0
	global_load_lds_dwordx4 v[190:191], off
	s_waitcnt vmcnt(8)
	s_waitcnt lgkmcnt(0)
	s_setprio 1
	s_barrier
	v_mfma_f32_16x16x32_bf16 v[94:97], v[130:133], v[166:169], v[94:97]
	v_mfma_f32_16x16x32_bf16 v[90:93], v[138:141], v[166:169], v[90:93]
	v_mfma_f32_16x16x32_bf16 v[86:89], v[130:133], v[174:177], v[86:89]
	v_mfma_f32_16x16x32_bf16 v[82:85], v[138:141], v[174:177], v[82:85]
	v_mfma_f32_16x16x32_bf16 v[78:81], v[130:133], v[182:185], v[78:81]
	v_mfma_f32_16x16x32_bf16 v[74:77], v[138:141], v[182:185], v[74:77]
	v_mfma_f32_16x16x32_bf16 v[70:73], v[130:133], v[200:203], v[70:73]
	v_mfma_f32_16x16x32_bf16 v[66:69], v[138:141], v[200:203], v[66:69]
	v_mfma_f32_16x16x32_bf16 v[94:97], v[134:137], v[170:173], v[94:97]
	v_mfma_f32_16x16x32_bf16 v[90:93], v[142:145], v[170:173], v[90:93]
	v_mfma_f32_16x16x32_bf16 v[86:89], v[134:137], v[178:181], v[86:89]
	v_mfma_f32_16x16x32_bf16 v[82:85], v[142:145], v[178:181], v[82:85]
	v_mfma_f32_16x16x32_bf16 v[78:81], v[134:137], v[186:189], v[78:81]
	v_mfma_f32_16x16x32_bf16 v[74:77], v[142:145], v[186:189], v[74:77]
	v_mfma_f32_16x16x32_bf16 v[70:73], v[134:137], v[204:207], v[70:73]
	v_mfma_f32_16x16x32_bf16 v[66:69], v[142:145], v[204:207], v[66:69]
	v_mfma_f32_16x16x32_bf16 v[30:33], v[146:149], v[166:169], v[30:33]
	v_mfma_f32_16x16x32_bf16 v[26:29], v[158:161], v[166:169], v[26:29]
	v_mfma_f32_16x16x32_bf16 v[22:25], v[146:149], v[174:177], v[22:25]
	v_mfma_f32_16x16x32_bf16 v[18:21], v[158:161], v[174:177], v[18:21]
	v_mfma_f32_16x16x32_bf16 v[14:17], v[146:149], v[182:185], v[14:17]
	v_mfma_f32_16x16x32_bf16 v[10:13], v[158:161], v[182:185], v[10:13]
	v_mfma_f32_16x16x32_bf16 v[6:9], v[146:149], v[200:203], v[6:9]
	v_mfma_f32_16x16x32_bf16 v[2:5], v[158:161], v[200:203], v[2:5]
	v_mfma_f32_16x16x32_bf16 v[30:33], v[150:153], v[170:173], v[30:33]
	v_mfma_f32_16x16x32_bf16 v[26:29], v[162:165], v[170:173], v[26:29]
	v_mfma_f32_16x16x32_bf16 v[22:25], v[150:153], v[178:181], v[22:25]
	v_mfma_f32_16x16x32_bf16 v[18:21], v[162:165], v[178:181], v[18:21]
	v_mfma_f32_16x16x32_bf16 v[14:17], v[150:153], v[186:189], v[14:17]
	v_mfma_f32_16x16x32_bf16 v[10:13], v[162:165], v[186:189], v[10:13]
	v_mfma_f32_16x16x32_bf16 v[6:9], v[150:153], v[204:207], v[6:9]
	v_mfma_f32_16x16x32_bf16 v[2:5], v[162:165], v[204:207], v[2:5]
	s_barrier
	s_setprio 0
	s_add_u32 s10, s10, 0x8000
	s_addc_u32 s11, s11, 0
	s_add_u32 s4, s4, 0x8000
	s_addc_u32 s5, s5, 0
	s_cmp_ge_u32 s40, s58
	s_mov_b32 s6, s40
.LBB0_674:
	v_add_u32_e32 v142, s15, v193
	v_add_u32_e32 v156, s39, v193
	ds_read_b128 v[130:133], v142
	ds_read_b128 v[134:137], v142 offset:1024
	ds_read_b128 v[138:141], v142 offset:2048
	ds_read_b128 v[142:145], v142 offset:3072
	ds_read_b128 v[146:149], v156
	ds_read_b128 v[150:153], v156 offset:1024
	ds_read_b128 v[158:161], v156 offset:2048
	ds_read_b128 v[162:165], v156 offset:3072
	s_add_i32 s40, s6, 2
	s_cmp_eq_u32 s93, s6
	s_cselect_b32 s6, s34, s10
	s_cselect_b32 s9, s87, s5
	s_cselect_b32 s8, s86, s4
	s_cselect_b32 s7, s35, s11
	s_movk_i32 vcc_lo, 0xc000
	v_lshl_add_u64 v[190:191], s[4:5], 0, v[154:155]
	s_mov_b32 vcc_hi, -1
	v_lshl_add_u64 v[196:197], v[190:191], 0, vcc
	s_movk_i32 vcc_lo, 0xe000
	s_add_i32 m0, s88, 0xc000
	s_mov_b32 vcc_hi, -1
	ds_read_b128 v[166:169], v194
	ds_read_b128 v[170:173], v194 offset:1024
	ds_read_b128 v[174:177], v194 offset:2048
	ds_read_b128 v[178:181], v194 offset:3072
	ds_read_b128 v[182:185], v194 offset:4096
	ds_read_b128 v[186:189], v194 offset:5120
	ds_read_b128 v[200:203], v194 offset:6144
	ds_read_b128 v[204:207], v194 offset:7168
	global_load_lds_dwordx4 v[196:197], off
	v_lshl_add_u64 v[190:191], v[190:191], 0, vcc
	s_add_i32 m0, s88, 0xe000
	s_nop 0
	global_load_lds_dwordx4 v[190:191], off
	s_waitcnt vmcnt(8)
	s_waitcnt lgkmcnt(0)
	s_setprio 1
	s_barrier
; #define PG8_STAGE(bufoff, gbase, unused) do { _Pragma("unroll") for (int _i = 0; _i < 2; ++_i) \
;         __builtin_amdgcn_global_load_lds((const unsigned*)((const char*)(gbase) + voff + _i * 8192), (LAS unsigned*)(lds + (bufoff) + ldsw + _i * 8192), 16, 0, 0); } while (0)
; #define PG8_LDA(dst, b, h) do { _Pragma("unroll") for (int m = 0; m < 4; ++m) _Pragma("unroll") for (int k = 0; k < 2; ++k) dst[m][k] = *(const LAS bf16x8*)(lds + PG8_SA(b, h) + aoff + m * 2048 + (FP8 ? k * 16 : k * 1024)); } while (0)
; #define PG8_WAIT_V(n) asm volatile("s_waitcnt vmcnt(" #n ")" ::: "memory")
; #define PG8_WAIT_L(n) asm volatile("s_waitcnt lgkmcnt(" #n ")" ::: "memory")
; #define PG8_BAR __builtin_amdgcn_s_barrier()
; #define PG8_SCHED __builtin_amdgcn_sched_barrier(0)
; template <class Epi, class Sched, bool ALIGN_EPI, bool SP2, int MODE  >
; __device__ __forceinline__ void gemm_phase(LAS unsigned char* lds, const Gemm g, const Sched S, const Epi E, unsigned long long& probe_acc, int epi_id, int wv) {
;     ...
;             PG8_WAIT_V(8); PG8_WAIT_L(0); PG8_BAR; PG8_MMA(0, 0, At, B0); PG8_MMA(0, 1, At, B1); PG8_BAR; PG8_SCHED;
;             PG8_LDA(At, 0, 1); PG8_STAGE(PG8_SB(0, 0), b2, voffB); PG8_STAGE(PG8_SB(0, 1), b2 + hB, voffB); PG8_STAGE(PG8_SA(0, 0), a2, voffA);
;             PG8_WAIT_V(8); PG8_WAIT_L(0); PG8_BAR; PG8_MMA(1, 0, At, B0); PG8_MMA(1, 1, At, B1); PG8_BAR; PG8_SCHED;
	v_mfma_f32_16x16x32_bf16 v[126:129], v[130:133], v[166:169], v[126:129]
	v_mfma_f32_16x16x32_bf16 v[122:125], v[138:141], v[166:169], v[122:125]
	v_mfma_f32_16x16x32_bf16 v[118:121], v[130:133], v[174:177], v[118:121]
	v_mfma_f32_16x16x32_bf16 v[114:117], v[138:141], v[174:177], v[114:117]
	v_mfma_f32_16x16x32_bf16 v[110:113], v[130:133], v[182:185], v[110:113]
	v_mfma_f32_16x16x32_bf16 v[106:109], v[138:141], v[182:185], v[106:109]
	v_mfma_f32_16x16x32_bf16 v[102:105], v[130:133], v[200:203], v[102:105]
	v_mfma_f32_16x16x32_bf16 v[98:101], v[138:141], v[200:203], v[98:101]
	v_mfma_f32_16x16x32_bf16 v[126:129], v[134:137], v[170:173], v[126:129]
	v_mfma_f32_16x16x32_bf16 v[122:125], v[142:145], v[170:173], v[122:125]
	v_mfma_f32_16x16x32_bf16 v[118:121], v[134:137], v[178:181], v[118:121]
	v_mfma_f32_16x16x32_bf16 v[114:117], v[142:145], v[178:181], v[114:117]
	v_mfma_f32_16x16x32_bf16 v[110:113], v[134:137], v[186:189], v[110:113]
	v_mfma_f32_16x16x32_bf16 v[106:109], v[142:145], v[186:189], v[106:109]
	v_mfma_f32_16x16x32_bf16 v[102:105], v[134:137], v[204:207], v[102:105]
	v_mfma_f32_16x16x32_bf16 v[98:101], v[142:145], v[204:207], v[98:101]
	v_mfma_f32_16x16x32_bf16 v[62:65], v[146:149], v[166:169], v[62:65]
	v_mfma_f32_16x16x32_bf16 v[58:61], v[158:161], v[166:169], v[58:61]
	v_mfma_f32_16x16x32_bf16 v[54:57], v[146:149], v[174:177], v[54:57]
	v_mfma_f32_16x16x32_bf16 v[50:53], v[158:161], v[174:177], v[50:53]
	v_mfma_f32_16x16x32_bf16 v[46:49], v[146:149], v[182:185], v[46:49]
	v_mfma_f32_16x16x32_bf16 v[42:45], v[158:161], v[182:185], v[42:45]
	v_mfma_f32_16x16x32_bf16 v[38:41], v[146:149], v[200:203], v[38:41]
	v_mfma_f32_16x16x32_bf16 v[34:37], v[158:161], v[200:203], v[34:37]
	v_mfma_f32_16x16x32_bf16 v[62:65], v[150:153], v[170:173], v[62:65]
	v_mfma_f32_16x16x32_bf16 v[58:61], v[162:165], v[170:173], v[58:61]
	v_mfma_f32_16x16x32_bf16 v[54:57], v[150:153], v[178:181], v[54:57]
	v_mfma_f32_16x16x32_bf16 v[50:53], v[162:165], v[178:181], v[50:53]
	v_mfma_f32_16x16x32_bf16 v[46:49], v[150:153], v[186:189], v[46:49]
	v_mfma_f32_16x16x32_bf16 v[42:45], v[162:165], v[186:189], v[42:45]
	v_mfma_f32_16x16x32_bf16 v[38:41], v[150:153], v[204:207], v[38:41]
	v_mfma_f32_16x16x32_bf16 v[34:37], v[162:165], v[204:207], v[34:37]
	s_barrier
	s_setprio 0
	s_mov_b32 m0, s26
	v_lshl_add_u64 v[190:191], s[6:7], 0, v[0:1]
	s_add_u32 vcc_lo, s6, s13
	ds_read_b128 v[166:169], v194 offset:16384
	ds_read_b128 v[170:173], v194 offset:17408
	ds_read_b128 v[174:177], v194 offset:18432
	ds_read_b128 v[178:181], v194 offset:19456
	ds_read_b128 v[182:185], v194 offset:20480
	ds_read_b128 v[186:189], v194 offset:21504
	ds_read_b128 v[200:203], v194 offset:22528
	ds_read_b128 v[204:207], v194 offset:23552
	global_load_lds_dwordx4 v[190:191], off
	v_lshl_add_u64 v[190:191], v[190:191], 0, s[70:71]
	s_mov_b32 m0, s27
	s_addc_u32 vcc_hi, s7, 0
	global_load_lds_dwordx4 v[190:191], off
	v_lshl_add_u64 v[190:191], vcc, 0, v[0:1]
	s_mov_b32 m0, s84
	s_nop 0
	global_load_lds_dwordx4 v[190:191], off
	v_lshl_add_u64 v[190:191], v[190:191], 0, s[70:71]
	s_mov_b32 m0, s85
	s_nop 0
	global_load_lds_dwordx4 v[190:191], off
	v_lshl_add_u64 v[190:191], s[8:9], 0, v[0:1]
	s_mov_b32 m0, s88
	v_lshl_add_u64 v[196:197], v[190:191], 0, s[70:71]
	global_load_lds_dwordx4 v[190:191], off
	s_mov_b32 m0, s89
	s_nop 0
	global_load_lds_dwordx4 v[196:197], off
	s_waitcnt vmcnt(8)
	s_waitcnt lgkmcnt(0)
	s_setprio 1
	s_barrier
	v_mfma_f32_16x16x32_bf16 v[94:97], v[130:133], v[166:169], v[94:97]
	v_mfma_f32_16x16x32_bf16 v[90:93], v[138:141], v[166:169], v[90:93]
	v_mfma_f32_16x16x32_bf16 v[86:89], v[130:133], v[174:177], v[86:89]
	v_mfma_f32_16x16x32_bf16 v[82:85], v[138:141], v[174:177], v[82:85]
	v_mfma_f32_16x16x32_bf16 v[78:81], v[130:133], v[182:185], v[78:81]
	v_mfma_f32_16x16x32_bf16 v[74:77], v[138:141], v[182:185], v[74:77]
	v_mfma_f32_16x16x32_bf16 v[70:73], v[130:133], v[200:203], v[70:73]
	v_mfma_f32_16x16x32_bf16 v[66:69], v[138:141], v[200:203], v[66:69]
	v_mfma_f32_16x16x32_bf16 v[94:97], v[134:137], v[170:173], v[94:97]
	v_mfma_f32_16x16x32_bf16 v[90:93], v[142:145], v[170:173], v[90:93]
	v_mfma_f32_16x16x32_bf16 v[86:89], v[134:137], v[178:181], v[86:89]
	v_mfma_f32_16x16x32_bf16 v[82:85], v[142:145], v[178:181], v[82:85]
	v_mfma_f32_16x16x32_bf16 v[78:81], v[134:137], v[186:189], v[78:81]
	v_mfma_f32_16x16x32_bf16 v[74:77], v[142:145], v[186:189], v[74:77]
	v_mfma_f32_16x16x32_bf16 v[70:73], v[134:137], v[204:207], v[70:73]
	v_mfma_f32_16x16x32_bf16 v[66:69], v[142:145], v[204:207], v[66:69]
	v_mfma_f32_16x16x32_bf16 v[30:33], v[146:149], v[166:169], v[30:33]
	v_mfma_f32_16x16x32_bf16 v[26:29], v[158:161], v[166:169], v[26:29]
	v_mfma_f32_16x16x32_bf16 v[22:25], v[146:149], v[174:177], v[22:25]
	v_mfma_f32_16x16x32_bf16 v[18:21], v[158:161], v[174:177], v[18:21]
	v_mfma_f32_16x16x32_bf16 v[14:17], v[146:149], v[182:185], v[14:17]
	v_mfma_f32_16x16x32_bf16 v[10:13], v[158:161], v[182:185], v[10:13]
	v_mfma_f32_16x16x32_bf16 v[6:9], v[146:149], v[200:203], v[6:9]
	v_mfma_f32_16x16x32_bf16 v[2:5], v[158:161], v[200:203], v[2:5]
	v_mfma_f32_16x16x32_bf16 v[30:33], v[150:153], v[170:173], v[30:33]
	v_mfma_f32_16x16x32_bf16 v[26:29], v[162:165], v[170:173], v[26:29]
	v_mfma_f32_16x16x32_bf16 v[22:25], v[150:153], v[178:181], v[22:25]
	v_mfma_f32_16x16x32_bf16 v[18:21], v[162:165], v[178:181], v[18:21]
	v_mfma_f32_16x16x32_bf16 v[14:17], v[150:153], v[186:189], v[14:17]
	v_mfma_f32_16x16x32_bf16 v[10:13], v[162:165], v[186:189], v[10:13]
	v_mfma_f32_16x16x32_bf16 v[6:9], v[150:153], v[204:207], v[6:9]
	v_mfma_f32_16x16x32_bf16 v[2:5], v[162:165], v[204:207], v[2:5]
	s_barrier
; #define PG8_STAGE(bufoff, gbase, unused) do { _Pragma("unroll") for (int _i = 0; _i < 2; ++_i) \
;         __builtin_amdgcn_global_load_lds((const unsigned*)((const char*)(gbase) + voff + _i * 8192), (LAS unsigned*)(lds + (bufoff) + ldsw + _i * 8192), 16, 0, 0); } while (0)
; #define PG8_LDA(dst, b, h) do { _Pragma("unroll") for (int m = 0; m < 4; ++m) _Pragma("unroll") for (int k = 0; k < 2; ++k) dst[m][k] = *(const LAS bf16x8*)(lds + PG8_SA(b, h) + aoff + m * 2048 + (FP8 ? k * 16 : k * 1024)); } while (0)
; #define PG8_LDB(dst, b, h) do { _Pragma("unroll") for (int n = 0; n < 2; ++n) _Pragma("unroll") for (int k = 0; k < 2; ++k) dst[n][k] = *(const LAS bf16x8*)(lds + PG8_SB(b, h) + boff + n * 2048 + (FP8 ? k * 16 : k * 1024)); } while (0)
; #define PG8_WAIT_V(n) asm volatile("s_waitcnt vmcnt(" #n ")" ::: "memory")
; #define PG8_WAIT_L(n) asm volatile("s_waitcnt lgkmcnt(" #n ")" ::: "memory")
; #define PG8_BAR __builtin_amdgcn_s_barrier()
; #define PG8_SCHED __builtin_amdgcn_sched_barrier(0)
; template <class Epi, class Sched, bool ALIGN_EPI, bool SP2, int MODE  >
; __device__ __forceinline__ void gemm_phase(LAS unsigned char* lds, const Gemm g, const Sched S, const Epi E, unsigned long long& probe_acc, int epi_id, int wv) {
;     ...
;             PG8_LDB(B0, 1, 0); PG8_LDB(B1, 1, 1); PG8_SCHED; PG8_LDA(At, 1, 0); PG8_STAGE(PG8_SA(0, 1), a2 + hA, voffA);
;             PG8_WAIT_V(8); PG8_WAIT_L(0); PG8_BAR; PG8_MMA(0, 0, At, B0); PG8_MMA(0, 1, At, B1); PG8_BAR; PG8_SCHED;
	s_setprio 0
	v_add_u32_e32 v142, s28, v193
	v_add_u32_e32 v156, s94, v193
	ds_read_b128 v[130:133], v142
	ds_read_b128 v[134:137], v142 offset:1024
	ds_read_b128 v[138:141], v142 offset:2048
	ds_read_b128 v[142:145], v142 offset:3072
	ds_read_b128 v[146:149], v156
	ds_read_b128 v[150:153], v156 offset:1024
	ds_read_b128 v[158:161], v156 offset:2048
	ds_read_b128 v[162:165], v156 offset:3072
	s_add_u32 s8, s8, s36
	s_addc_u32 s9, s9, 0
	s_mov_b32 m0, s29
	v_lshl_add_u64 v[196:197], s[8:9], 0, v[0:1]
	ds_read_b128 v[166:169], v194 offset:32768
	ds_read_b128 v[170:173], v194 offset:33792
	ds_read_b128 v[174:177], v194 offset:34816
	ds_read_b128 v[178:181], v194 offset:35840
	ds_read_b128 v[182:185], v194 offset:36864
	ds_read_b128 v[186:189], v194 offset:37888
	ds_read_b128 v[200:203], v194 offset:38912
	ds_read_b128 v[204:207], v194 offset:39936
	global_load_lds_dwordx4 v[196:197], off
	v_lshl_add_u64 v[196:197], v[196:197], 0, s[70:71]
	s_mov_b32 m0, s92
	s_nop 0
	global_load_lds_dwordx4 v[196:197], off
	s_waitcnt vmcnt(8)
	s_waitcnt lgkmcnt(0)
	s_setprio 1
	s_barrier
	v_mfma_f32_16x16x32_bf16 v[126:129], v[130:133], v[166:169], v[126:129]
	v_mfma_f32_16x16x32_bf16 v[122:125], v[138:141], v[166:169], v[122:125]
	v_mfma_f32_16x16x32_bf16 v[118:121], v[130:133], v[174:177], v[118:121]
	v_mfma_f32_16x16x32_bf16 v[114:117], v[138:141], v[174:177], v[114:117]
	v_mfma_f32_16x16x32_bf16 v[110:113], v[130:133], v[182:185], v[110:113]
	v_mfma_f32_16x16x32_bf16 v[106:109], v[138:141], v[182:185], v[106:109]
	v_mfma_f32_16x16x32_bf16 v[102:105], v[130:133], v[200:203], v[102:105]
	v_mfma_f32_16x16x32_bf16 v[98:101], v[138:141], v[200:203], v[98:101]
	v_mfma_f32_16x16x32_bf16 v[126:129], v[134:137], v[170:173], v[126:129]
	v_mfma_f32_16x16x32_bf16 v[122:125], v[142:145], v[170:173], v[122:125]
	v_mfma_f32_16x16x32_bf16 v[118:121], v[134:137], v[178:181], v[118:121]
	v_mfma_f32_16x16x32_bf16 v[114:117], v[142:145], v[178:181], v[114:117]
	v_mfma_f32_16x16x32_bf16 v[110:113], v[134:137], v[186:189], v[110:113]
	v_mfma_f32_16x16x32_bf16 v[106:109], v[142:145], v[186:189], v[106:109]
	v_mfma_f32_16x16x32_bf16 v[102:105], v[134:137], v[204:207], v[102:105]
	v_mfma_f32_16x16x32_bf16 v[98:101], v[142:145], v[204:207], v[98:101]
	v_mfma_f32_16x16x32_bf16 v[62:65], v[146:149], v[166:169], v[62:65]
	v_mfma_f32_16x16x32_bf16 v[58:61], v[158:161], v[166:169], v[58:61]
	v_mfma_f32_16x16x32_bf16 v[54:57], v[146:149], v[174:177], v[54:57]
	v_mfma_f32_16x16x32_bf16 v[50:53], v[158:161], v[174:177], v[50:53]
	v_mfma_f32_16x16x32_bf16 v[46:49], v[146:149], v[182:185], v[46:49]
	v_mfma_f32_16x16x32_bf16 v[42:45], v[158:161], v[182:185], v[42:45]
	v_mfma_f32_16x16x32_bf16 v[38:41], v[146:149], v[200:203], v[38:41]
	v_mfma_f32_16x16x32_bf16 v[34:37], v[158:161], v[200:203], v[34:37]
	v_mfma_f32_16x16x32_bf16 v[62:65], v[150:153], v[170:173], v[62:65]
	v_mfma_f32_16x16x32_bf16 v[58:61], v[162:165], v[170:173], v[58:61]
	v_mfma_f32_16x16x32_bf16 v[54:57], v[150:153], v[178:181], v[54:57]
	v_mfma_f32_16x16x32_bf16 v[50:53], v[162:165], v[178:181], v[50:53]
	v_mfma_f32_16x16x32_bf16 v[46:49], v[150:153], v[186:189], v[46:49]
	v_mfma_f32_16x16x32_bf16 v[42:45], v[162:165], v[186:189], v[42:45]
	v_mfma_f32_16x16x32_bf16 v[38:41], v[150:153], v[204:207], v[38:41]
	v_mfma_f32_16x16x32_bf16 v[34:37], v[162:165], v[204:207], v[34:37]
	s_barrier
; #define PG8_STAGE(bufoff, gbase, unused) do { _Pragma("unroll") for (int _i = 0; _i < 2; ++_i) \
;         __builtin_amdgcn_global_load_lds((const unsigned*)((const char*)(gbase) + voff + _i * 8192), (LAS unsigned*)(lds + (bufoff) + ldsw + _i * 8192), 16, 0, 0); } while (0)
; #define PG8_LDA(dst, b, h) do { _Pragma("unroll") for (int m = 0; m < 4; ++m) _Pragma("unroll") for (int k = 0; k < 2; ++k) dst[m][k] = *(const LAS bf16x8*)(lds + PG8_SA(b, h) + aoff + m * 2048 + (FP8 ? k * 16 : k * 1024)); } while (0)
; #define PG8_WAIT_V(n) asm volatile("s_waitcnt vmcnt(" #n ")" ::: "memory")
; #define PG8_WAIT_L(n) asm volatile("s_waitcnt lgkmcnt(" #n ")" ::: "memory")
; #define PG8_BAR __builtin_amdgcn_s_barrier()
; #define PG8_SCHED __builtin_amdgcn_sched_barrier(0)
; template <class Epi, class Sched, bool ALIGN_EPI, bool SP2, int MODE  >
; __device__ __forceinline__ void gemm_phase(LAS unsigned char* lds, const Gemm g, const Sched S, const Epi E, unsigned long long& probe_acc, int epi_id, int wv) {
;     ...
;             PG8_LDA(At, 1, 1); PG8_STAGE(PG8_SB(1, 0), b3, voffB); PG8_STAGE(PG8_SB(1, 1), b3 + hB, voffB); PG8_STAGE(PG8_SA(1, 0), a3, voffA);
;             PG8_WAIT_V(8); PG8_WAIT_L(0); PG8_BAR; PG8_MMA(1, 0, At, B0); PG8_MMA(1, 1, At, B1); PG8_BAR; PG8_SCHED;
;     ...
;         if constexpr (ALIGN_EPI) { if (wr == 0) PG8_BAR; }
	s_setprio 0
	s_add_u32 s6, s6, 0x4000
	s_addc_u32 s7, s7, 0
	s_mov_b32 m0, s2
	v_lshl_add_u64 v[196:197], s[6:7], 0, v[0:1]
	s_add_u32 s6, s6, s13
	ds_read_b128 v[166:169], v194 offset:49152
	ds_read_b128 v[170:173], v194 offset:50176
	ds_read_b128 v[174:177], v194 offset:51200
	ds_read_b128 v[178:181], v194 offset:52224
	ds_read_b128 v[182:185], v194 offset:53248
	ds_read_b128 v[186:189], v194 offset:54272
	ds_read_b128 v[200:203], v194 offset:55296
	ds_read_b128 v[204:207], v194 offset:56320
	global_load_lds_dwordx4 v[196:197], off
	v_lshl_add_u64 v[196:197], v[196:197], 0, s[70:71]
	s_mov_b32 m0, s3
	s_addc_u32 s7, s7, 0
	global_load_lds_dwordx4 v[196:197], off
	v_lshl_add_u64 v[196:197], s[6:7], 0, v[0:1]
	s_mov_b32 m0, s12
	s_nop 0
	global_load_lds_dwordx4 v[196:197], off
	v_lshl_add_u64 v[196:197], v[196:197], 0, s[70:71]
	s_mov_b32 m0, s95
	s_nop 0
	global_load_lds_dwordx4 v[196:197], off
	v_lshl_add_u64 v[196:197], v[190:191], 0, s[76:77]
	s_mov_b32 m0, s50
	v_lshl_add_u64 v[190:191], v[190:191], 0, s[78:79]
	global_load_lds_dwordx4 v[196:197], off
	s_mov_b32 m0, s51
	s_nop 0
	global_load_lds_dwordx4 v[190:191], off
	s_waitcnt vmcnt(8)
	s_waitcnt lgkmcnt(0)
	s_setprio 1
	s_barrier
	v_mfma_f32_16x16x32_bf16 v[94:97], v[130:133], v[166:169], v[94:97]
	v_mfma_f32_16x16x32_bf16 v[90:93], v[138:141], v[166:169], v[90:93]
	v_mfma_f32_16x16x32_bf16 v[86:89], v[130:133], v[174:177], v[86:89]
	v_mfma_f32_16x16x32_bf16 v[82:85], v[138:141], v[174:177], v[82:85]
	v_mfma_f32_16x16x32_bf16 v[78:81], v[130:133], v[182:185], v[78:81]
	v_mfma_f32_16x16x32_bf16 v[74:77], v[138:141], v[182:185], v[74:77]
	v_mfma_f32_16x16x32_bf16 v[70:73], v[130:133], v[200:203], v[70:73]
	v_mfma_f32_16x16x32_bf16 v[66:69], v[138:141], v[200:203], v[66:69]
	v_mfma_f32_16x16x32_bf16 v[94:97], v[134:137], v[170:173], v[94:97]
	v_mfma_f32_16x16x32_bf16 v[90:93], v[142:145], v[170:173], v[90:93]
	v_mfma_f32_16x16x32_bf16 v[86:89], v[134:137], v[178:181], v[86:89]
	v_mfma_f32_16x16x32_bf16 v[82:85], v[142:145], v[178:181], v[82:85]
	v_mfma_f32_16x16x32_bf16 v[78:81], v[134:137], v[186:189], v[78:81]
	v_mfma_f32_16x16x32_bf16 v[74:77], v[142:145], v[186:189], v[74:77]
	v_mfma_f32_16x16x32_bf16 v[70:73], v[134:137], v[204:207], v[70:73]
	v_mfma_f32_16x16x32_bf16 v[66:69], v[142:145], v[204:207], v[66:69]
	v_mfma_f32_16x16x32_bf16 v[30:33], v[146:149], v[166:169], v[30:33]
	v_mfma_f32_16x16x32_bf16 v[26:29], v[158:161], v[166:169], v[26:29]
	v_mfma_f32_16x16x32_bf16 v[22:25], v[146:149], v[174:177], v[22:25]
	v_mfma_f32_16x16x32_bf16 v[18:21], v[158:161], v[174:177], v[18:21]
	v_mfma_f32_16x16x32_bf16 v[14:17], v[146:149], v[182:185], v[14:17]
	v_mfma_f32_16x16x32_bf16 v[10:13], v[158:161], v[182:185], v[10:13]
	v_mfma_f32_16x16x32_bf16 v[6:9], v[146:149], v[200:203], v[6:9]
	v_mfma_f32_16x16x32_bf16 v[2:5], v[158:161], v[200:203], v[2:5]
	v_mfma_f32_16x16x32_bf16 v[30:33], v[150:153], v[170:173], v[30:33]
	v_mfma_f32_16x16x32_bf16 v[26:29], v[162:165], v[170:173], v[26:29]
	v_mfma_f32_16x16x32_bf16 v[22:25], v[150:153], v[178:181], v[22:25]
	v_mfma_f32_16x16x32_bf16 v[18:21], v[162:165], v[178:181], v[18:21]
	v_mfma_f32_16x16x32_bf16 v[14:17], v[150:153], v[186:189], v[14:17]
	v_mfma_f32_16x16x32_bf16 v[10:13], v[162:165], v[186:189], v[10:13]
	v_mfma_f32_16x16x32_bf16 v[6:9], v[150:153], v[204:207], v[6:9]
	v_mfma_f32_16x16x32_bf16 v[2:5], v[162:165], v[204:207], v[2:5]
	s_barrier
	s_setprio 0
	s_add_u32 s10, s10, 0x8000
	s_addc_u32 s11, s11, 0
	s_add_u32 s4, s4, 0x8000
	s_addc_u32 s5, s5, 0
	s_cmp_ge_u32 s40, s58
	s_mov_b32 s6, s40
	s_cbranch_scc0 .LBB0_674
	v_readlane_b32 s4, v255, 30
	v_readlane_b32 s5, v255, 31
	s_and_b64 vcc, exec, s[4:5]
	s_cbranch_vccz .LBB0_677
	s_barrier

; #define PG8_STAGE(bufoff, gbase, unused) do { _Pragma("unroll") for (int _i = 0; _i < 2; ++_i) \
;         __builtin_amdgcn_global_load_lds((const unsigned*)((const char*)(gbase) + voff + _i * 8192), (LAS unsigned*)(lds + (bufoff) + ldsw + _i * 8192), 16, 0, 0); } while (0)
; #define PG8_LDA(dst, b, h) do { _Pragma("unroll") for (int m = 0; m < 4; ++m) _Pragma("unroll") for (int k = 0; k < 2; ++k) dst[m][k] = *(const LAS bf16x8*)(lds + PG8_SA(b, h) + aoff + m * 2048 + (FP8 ? k * 16 : k * 1024)); } while (0)
; #define PG8_LDB(dst, b, h) do { _Pragma("unroll") for (int n = 0; n < 2; ++n) _Pragma("unroll") for (int k = 0; k < 2; ++k) dst[n][k] = *(const LAS bf16x8*)(lds + PG8_SB(b, h) + boff + n * 2048 + (FP8 ? k * 16 : k * 1024)); } while (0)
; #define PG8_WAIT_V(n) asm volatile("s_waitcnt vmcnt(" #n ")" ::: "memory")
; #define PG8_WAIT_L(n) asm volatile("s_waitcnt lgkmcnt(" #n ")" ::: "memory")
; #define PG8_BAR __builtin_amdgcn_s_barrier()
; #define PG8_SCHED __builtin_amdgcn_sched_barrier(0)
; template <class Epi, class Sched, bool ALIGN_EPI, bool SP2, int MODE  >
; __device__ __forceinline__ void gemm_phase(LAS unsigned char* lds, const Gemm g, const Sched S, const Epi E, unsigned long long& probe_acc, int epi_id, int wv) {
;     ...
;             PG8_WAIT_V(8); PG8_WAIT_L(0); PG8_BAR; PG8_MMA(0, 0, At, B0); PG8_MMA(0, 1, At, B1); PG8_BAR; PG8_SCHED;
;             PG8_LDA(At, 0, 1); PG8_STAGE(PG8_SB(0, 0), b2, voffB); PG8_STAGE(PG8_SB(0, 1), b2 + hB, voffB); PG8_STAGE(PG8_SA(0, 0), a2, voffA);
;             PG8_WAIT_V(8); PG8_WAIT_L(0); PG8_BAR; PG8_MMA(1, 0, At, B0); PG8_MMA(1, 1, At, B1); PG8_BAR; PG8_SCHED;
;             PG8_LDB(B0, 1, 0); PG8_LDB(B1, 1, 1); PG8_SCHED; PG8_LDA(At, 1, 0); PG8_STAGE(PG8_SA(0, 1), a2 + hA, voffA);
;             PG8_WAIT_V(8); PG8_WAIT_L(0); PG8_BAR; PG8_MMA(0, 0, At, B0); PG8_MMA(0, 1, At, B1); PG8_BAR; PG8_SCHED;
.LBB0_914:
	v_add_u32_e32 v144, s14, v191
	v_add_u32_e32 v148, s27, v191
	s_add_u32 s8, s4, s6
	ds_read_b128 v[132:135], v144
	v_xor_b32_e32 v154, 16, v144
	ds_read_b128 v[136:139], v154
	ds_read_b128 v[140:143], v144 offset:2048
	ds_read_b128 v[144:147], v154 offset:2048
	ds_read_b128 v[156:159], v148
	v_xor_b32_e32 v154, 16, v148
	ds_read_b128 v[160:163], v154
	ds_read_b128 v[164:167], v148 offset:2048
	ds_read_b128 v[168:171], v154 offset:2048
	s_addc_u32 s9, s5, s7
	s_add_u32 s8, s8, 0x8000
	s_addc_u32 s9, s9, 0
	s_add_u32 s10, s34, s6
	s_addc_u32 s11, s35, s7
	s_cmp_eq_u32 s6, 0xa8000
	s_cselect_b32 s9, s69, s9
	s_cselect_b32 s8, s68, s8
	s_cselect_b32 s11, s91, s11
	s_cselect_b32 s10, s90, s10
	v_lshl_add_u64 v[148:149], v[130:131], 0, s[6:7]
	v_lshl_add_u64 v[150:151], v[148:149], 0, s[76:77]
	s_add_i32 m0, s41, 0xc000
	ds_read_b128 v[172:175], v192
	ds_read_b128 v[176:179], v193
	ds_read_b128 v[180:183], v192 offset:2048
	ds_read_b128 v[184:187], v193 offset:2048
	ds_read_b128 v[212:215], v192 offset:4096
	ds_read_b128 v[216:219], v193 offset:4096
	ds_read_b128 v[220:223], v192 offset:6144
	ds_read_b128 v[224:227], v193 offset:6144
	global_load_lds_dwordx4 v[150:151], off
	v_lshl_add_u64 v[148:149], v[148:149], 0, s[78:79]
	s_add_i32 m0, s41, 0xe000
	s_nop 0
	global_load_lds_dwordx4 v[148:149], off
	s_waitcnt vmcnt(8)
	s_waitcnt lgkmcnt(0)
	s_setprio 1
	s_barrier
	v_mfma_scale_f32_16x16x128_f8f6f4 v[126:129], v[132:139], v[172:179], v[126:129], v208, v208 op_sel_hi:[0,0,0]
	v_mfma_scale_f32_16x16x128_f8f6f4 v[122:125], v[140:147], v[172:179], v[122:125], v208, v208 op_sel_hi:[0,0,0]
	v_mfma_scale_f32_16x16x128_f8f6f4 v[118:121], v[132:139], v[180:187], v[118:121], v208, v208 op_sel_hi:[0,0,0]
	v_mfma_scale_f32_16x16x128_f8f6f4 v[114:117], v[140:147], v[180:187], v[114:117], v208, v208 op_sel_hi:[0,0,0]
	v_mfma_scale_f32_16x16x128_f8f6f4 v[110:113], v[132:139], v[212:219], v[110:113], v208, v208 op_sel_hi:[0,0,0]
	v_mfma_scale_f32_16x16x128_f8f6f4 v[106:109], v[140:147], v[212:219], v[106:109], v208, v208 op_sel_hi:[0,0,0]
	v_mfma_scale_f32_16x16x128_f8f6f4 v[102:105], v[132:139], v[220:227], v[102:105], v208, v208 op_sel_hi:[0,0,0]
	v_mfma_scale_f32_16x16x128_f8f6f4 v[98:101], v[140:147], v[220:227], v[98:101], v208, v208 op_sel_hi:[0,0,0]
	v_mfma_scale_f32_16x16x128_f8f6f4 v[148:151], v[156:163], v[172:179], v[62:65], v208, v208 op_sel_hi:[0,0,0]
	v_mfma_scale_f32_16x16x128_f8f6f4 v[172:175], v[164:171], v[172:179], v[58:61], v208, v208 op_sel_hi:[0,0,0]
	v_mfma_scale_f32_16x16x128_f8f6f4 v[176:179], v[156:163], v[180:187], v[54:57], v208, v208 op_sel_hi:[0,0,0]
	v_mfma_scale_f32_16x16x128_f8f6f4 v[180:183], v[164:171], v[180:187], v[50:53], v208, v208 op_sel_hi:[0,0,0]
	v_mfma_scale_f32_16x16x128_f8f6f4 v[184:187], v[156:163], v[212:219], v[46:49], v208, v208 op_sel_hi:[0,0,0]
	v_mfma_scale_f32_16x16x128_f8f6f4 v[194:197], v[164:171], v[212:219], v[42:45], v208, v208 op_sel_hi:[0,0,0]
	v_mfma_scale_f32_16x16x128_f8f6f4 v[200:203], v[156:163], v[220:227], v[38:41], v208, v208 op_sel_hi:[0,0,0]
	v_mfma_scale_f32_16x16x128_f8f6f4 v[212:215], v[164:171], v[220:227], v[34:37], v208, v208 op_sel_hi:[0,0,0]
	s_barrier
	s_setprio 0
	s_mov_b32 m0, s15
	v_lshl_add_u64 v[152:153], s[10:11], 0, v[0:1]
	s_nop 2
	ds_read_b128 v[34:37], v192 offset:16384
	ds_read_b128 v[38:41], v193 offset:16384
	ds_read_b128 v[42:45], v192 offset:18432
	ds_read_b128 v[46:49], v193 offset:18432
	ds_read_b128 v[50:53], v192 offset:20480
	ds_read_b128 v[54:57], v193 offset:20480
	ds_read_b128 v[58:61], v192 offset:22528
	ds_read_b128 v[62:65], v193 offset:22528
	global_load_lds_dwordx4 v[152:153], off
	v_lshl_add_u64 v[188:189], v[152:153], 0, s[70:71]
	s_mov_b32 m0, s26
	s_nop 0
	global_load_lds_dwordx4 v[188:189], off
	v_lshl_add_u64 v[188:189], v[152:153], 0, s[42:43]
	s_mov_b32 m0, s39
	s_nop 0
	global_load_lds_dwordx4 v[188:189], off
	v_lshl_add_u64 v[188:189], v[152:153], 0, s[48:49]
	s_mov_b32 m0, s40
	s_nop 0
	global_load_lds_dwordx4 v[188:189], off
	v_lshl_add_u64 v[188:189], s[8:9], 0, v[0:1]
	s_mov_b32 m0, s41
	v_lshl_add_u64 v[204:205], v[188:189], 0, s[70:71]
	global_load_lds_dwordx4 v[188:189], off
	s_mov_b32 m0, s84
	s_nop 0
	global_load_lds_dwordx4 v[204:205], off
	s_waitcnt vmcnt(8)
	s_waitcnt lgkmcnt(0)
	s_setprio 1
	s_barrier
	v_mfma_scale_f32_16x16x128_f8f6f4 v[94:97], v[132:139], v[34:41], v[94:97], v208, v208 op_sel_hi:[0,0,0]
	v_mfma_scale_f32_16x16x128_f8f6f4 v[90:93], v[140:147], v[34:41], v[90:93], v208, v208 op_sel_hi:[0,0,0]
	v_mfma_scale_f32_16x16x128_f8f6f4 v[86:89], v[132:139], v[42:49], v[86:89], v208, v208 op_sel_hi:[0,0,0]
	v_mfma_scale_f32_16x16x128_f8f6f4 v[82:85], v[140:147], v[42:49], v[82:85], v208, v208 op_sel_hi:[0,0,0]
	v_mfma_scale_f32_16x16x128_f8f6f4 v[78:81], v[132:139], v[50:57], v[78:81], v208, v208 op_sel_hi:[0,0,0]
	v_mfma_scale_f32_16x16x128_f8f6f4 v[74:77], v[140:147], v[50:57], v[74:77], v208, v208 op_sel_hi:[0,0,0]
	v_mfma_scale_f32_16x16x128_f8f6f4 v[216:219], v[132:139], v[58:65], v[70:73], v208, v208 op_sel_hi:[0,0,0]
	v_mfma_scale_f32_16x16x128_f8f6f4 v[220:223], v[140:147], v[58:65], v[66:69], v208, v208 op_sel_hi:[0,0,0]
	v_mfma_scale_f32_16x16x128_f8f6f4 v[224:227], v[156:163], v[34:41], v[30:33], v208, v208 op_sel_hi:[0,0,0]
	v_mfma_scale_f32_16x16x128_f8f6f4 v[228:231], v[164:171], v[34:41], v[26:29], v208, v208 op_sel_hi:[0,0,0]
	v_mfma_scale_f32_16x16x128_f8f6f4 v[232:235], v[156:163], v[42:49], v[22:25], v208, v208 op_sel_hi:[0,0,0]
	v_mfma_scale_f32_16x16x128_f8f6f4 v[236:239], v[164:171], v[42:49], v[18:21], v208, v208 op_sel_hi:[0,0,0]
	v_mfma_scale_f32_16x16x128_f8f6f4 v[240:243], v[156:163], v[50:57], v[14:17], v208, v208 op_sel_hi:[0,0,0]
	v_mfma_scale_f32_16x16x128_f8f6f4 v[244:247], v[164:171], v[50:57], v[10:13], v208, v208 op_sel_hi:[0,0,0]
	v_mfma_scale_f32_16x16x128_f8f6f4 v[248:251], v[156:163], v[58:65], v[6:9], v208, v208 op_sel_hi:[0,0,0]
	v_mfma_scale_f32_16x16x128_f8f6f4 v[204:207], v[164:171], v[58:65], v[2:5], v208, v208 op_sel_hi:[0,0,0]
	s_barrier
; #define PG8_STAGE(bufoff, gbase, unused) do { _Pragma("unroll") for (int _i = 0; _i < 2; ++_i) \
;         __builtin_amdgcn_global_load_lds((const unsigned*)((const char*)(gbase) + voff + _i * 8192), (LAS unsigned*)(lds + (bufoff) + ldsw + _i * 8192), 16, 0, 0); } while (0)
; #define PG8_LDA(dst, b, h) do { _Pragma("unroll") for (int m = 0; m < 4; ++m) _Pragma("unroll") for (int k = 0; k < 2; ++k) dst[m][k] = *(const LAS bf16x8*)(lds + PG8_SA(b, h) + aoff + m * 2048 + (FP8 ? k * 16 : k * 1024)); } while (0)
; #define PG8_LDB(dst, b, h) do { _Pragma("unroll") for (int n = 0; n < 2; ++n) _Pragma("unroll") for (int k = 0; k < 2; ++k) dst[n][k] = *(const LAS bf16x8*)(lds + PG8_SB(b, h) + boff + n * 2048 + (FP8 ? k * 16 : k * 1024)); } while (0)
; #define PG8_WAIT_V(n) asm volatile("s_waitcnt vmcnt(" #n ")" ::: "memory")
; #define PG8_WAIT_L(n) asm volatile("s_waitcnt lgkmcnt(" #n ")" ::: "memory")
; #define PG8_BAR __builtin_amdgcn_s_barrier()
; #define PG8_SCHED __builtin_amdgcn_sched_barrier(0)
; template <class Epi, class Sched, bool ALIGN_EPI, bool SP2, int MODE  >
; __device__ __forceinline__ void gemm_phase(LAS unsigned char* lds, const Gemm g, const Sched S, const Epi E, unsigned long long& probe_acc, int epi_id, int wv) {
;     ...
;             PG8_LDB(B0, 1, 0); PG8_LDB(B1, 1, 1); PG8_SCHED; PG8_LDA(At, 1, 0); PG8_STAGE(PG8_SA(0, 1), a2 + hA, voffA);
;             PG8_WAIT_V(8); PG8_WAIT_L(0); PG8_BAR; PG8_MMA(0, 0, At, B0); PG8_MMA(0, 1, At, B1); PG8_BAR; PG8_SCHED;
;             PG8_LDA(At, 1, 1); PG8_STAGE(PG8_SB(1, 0), b3, voffB); PG8_STAGE(PG8_SB(1, 1), b3 + hB, voffB); PG8_STAGE(PG8_SA(1, 0), a3, voffA);
;             PG8_WAIT_V(8); PG8_WAIT_L(0); PG8_BAR; PG8_MMA(1, 0, At, B0); PG8_MMA(1, 1, At, B1); PG8_BAR; PG8_SCHED;
;     ...
;         if constexpr (ALIGN_EPI) { if (wr == 0) PG8_BAR; }
	s_setprio 0
	s_nop 1
	v_add_u32_e32 v14, s89, v191
	v_add_u32_e32 v18, s29, v191
	s_nop 0
	ds_read_b128 v[2:5], v14
	v_xor_b32_e32 v154, 16, v14
	ds_read_b128 v[6:9], v154
	ds_read_b128 v[10:13], v14 offset:2048
	ds_read_b128 v[14:17], v154 offset:2048
	ds_read_b128 v[132:135], v18
	v_xor_b32_e32 v154, 16, v18
	ds_read_b128 v[136:139], v154
	ds_read_b128 v[140:143], v18 offset:2048
	ds_read_b128 v[144:147], v154 offset:2048
	s_add_u32 s8, s8, s12
	s_addc_u32 s9, s9, 0
	s_mov_b32 m0, s85
	v_lshl_add_u64 v[42:43], s[8:9], 0, v[0:1]
	ds_read_b128 v[18:21], v192 offset:32768
	ds_read_b128 v[22:25], v193 offset:32768
	ds_read_b128 v[26:29], v192 offset:34816
	ds_read_b128 v[30:33], v193 offset:34816
	ds_read_b128 v[34:37], v192 offset:36864
	ds_read_b128 v[38:41], v193 offset:36864
	ds_read_b128 v[66:69], v192 offset:38912
	ds_read_b128 v[70:73], v193 offset:38912
	global_load_lds_dwordx4 v[42:43], off
	v_lshl_add_u64 v[42:43], v[42:43], 0, s[70:71]
	s_mov_b32 m0, s88
	s_nop 0
	global_load_lds_dwordx4 v[42:43], off
	s_waitcnt vmcnt(8)
	s_waitcnt lgkmcnt(0)
	s_setprio 1
	s_barrier
	v_mfma_scale_f32_16x16x128_f8f6f4 v[126:129], v[2:9], v[18:25], v[126:129], v208, v208 op_sel_hi:[0,0,0]
	v_mfma_scale_f32_16x16x128_f8f6f4 v[122:125], v[10:17], v[18:25], v[122:125], v208, v208 op_sel_hi:[0,0,0]
	v_mfma_scale_f32_16x16x128_f8f6f4 v[118:121], v[2:9], v[26:33], v[118:121], v208, v208 op_sel_hi:[0,0,0]
	v_mfma_scale_f32_16x16x128_f8f6f4 v[114:117], v[10:17], v[26:33], v[114:117], v208, v208 op_sel_hi:[0,0,0]
	v_mfma_scale_f32_16x16x128_f8f6f4 v[110:113], v[2:9], v[34:41], v[110:113], v208, v208 op_sel_hi:[0,0,0]
	v_mfma_scale_f32_16x16x128_f8f6f4 v[106:109], v[10:17], v[34:41], v[106:109], v208, v208 op_sel_hi:[0,0,0]
	v_mfma_scale_f32_16x16x128_f8f6f4 v[102:105], v[2:9], v[66:73], v[102:105], v208, v208 op_sel_hi:[0,0,0]
	v_mfma_scale_f32_16x16x128_f8f6f4 v[98:101], v[10:17], v[66:73], v[98:101], v208, v208 op_sel_hi:[0,0,0]
	v_mfma_scale_f32_16x16x128_f8f6f4 v[62:65], v[132:139], v[18:25], v[148:151], v208, v208 op_sel_hi:[0,0,0]
	v_mfma_scale_f32_16x16x128_f8f6f4 v[58:61], v[140:147], v[18:25], v[172:175], v208, v208 op_sel_hi:[0,0,0]
	v_mfma_scale_f32_16x16x128_f8f6f4 v[54:57], v[132:139], v[26:33], v[176:179], v208, v208 op_sel_hi:[0,0,0]
	v_mfma_scale_f32_16x16x128_f8f6f4 v[50:53], v[140:147], v[26:33], v[180:183], v208, v208 op_sel_hi:[0,0,0]
	v_mfma_scale_f32_16x16x128_f8f6f4 v[46:49], v[132:139], v[34:41], v[184:187], v208, v208 op_sel_hi:[0,0,0]
	v_mfma_scale_f32_16x16x128_f8f6f4 v[42:45], v[140:147], v[34:41], v[194:197], v208, v208 op_sel_hi:[0,0,0]
	v_mfma_scale_f32_16x16x128_f8f6f4 v[38:41], v[132:139], v[66:73], v[200:203], v208, v208 op_sel_hi:[0,0,0]
	v_mfma_scale_f32_16x16x128_f8f6f4 v[34:37], v[140:147], v[66:73], v[212:215], v208, v208 op_sel_hi:[0,0,0]
	s_barrier
	s_setprio 0
	s_mov_b32 m0, s92
	v_lshl_add_u64 v[26:27], v[152:153], 0, s[76:77]
	ds_read_b128 v[18:21], v192 offset:49152
	ds_read_b128 v[22:25], v193 offset:49152
	ds_read_b128 v[156:159], v192 offset:51200
	ds_read_b128 v[160:163], v193 offset:51200
	ds_read_b128 v[164:167], v192 offset:53248
	ds_read_b128 v[168:171], v193 offset:53248
	ds_read_b128 v[172:175], v192 offset:55296
	ds_read_b128 v[176:179], v193 offset:55296
	global_load_lds_dwordx4 v[26:27], off
	v_lshl_add_u64 v[26:27], v[152:153], 0, s[78:79]
	s_mov_b32 m0, s93
	s_nop 0
	global_load_lds_dwordx4 v[26:27], off
	v_lshl_add_u64 v[26:27], v[152:153], 0, s[44:45]
	s_mov_b32 m0, s0
	s_nop 0
	global_load_lds_dwordx4 v[26:27], off
	v_lshl_add_u64 v[26:27], v[152:153], 0, s[56:57]
	s_mov_b32 m0, s1
	s_nop 0
	global_load_lds_dwordx4 v[26:27], off
	v_lshl_add_u64 v[26:27], v[188:189], 0, s[76:77]
	s_mov_b32 m0, s94
	s_nop 0
	global_load_lds_dwordx4 v[26:27], off
	v_lshl_add_u64 v[26:27], v[188:189], 0, s[78:79]
	s_mov_b32 m0, s95
	s_nop 0
	global_load_lds_dwordx4 v[26:27], off
	s_waitcnt vmcnt(8)
	s_waitcnt lgkmcnt(0)
	s_setprio 1
	s_barrier
	v_mfma_scale_f32_16x16x128_f8f6f4 v[94:97], v[2:9], v[18:25], v[94:97], v208, v208 op_sel_hi:[0,0,0]
	v_mfma_scale_f32_16x16x128_f8f6f4 v[90:93], v[10:17], v[18:25], v[90:93], v208, v208 op_sel_hi:[0,0,0]
	v_mfma_scale_f32_16x16x128_f8f6f4 v[86:89], v[2:9], v[156:163], v[86:89], v208, v208 op_sel_hi:[0,0,0]
	v_mfma_scale_f32_16x16x128_f8f6f4 v[82:85], v[10:17], v[156:163], v[82:85], v208, v208 op_sel_hi:[0,0,0]
	v_mfma_scale_f32_16x16x128_f8f6f4 v[78:81], v[2:9], v[164:171], v[78:81], v208, v208 op_sel_hi:[0,0,0]
	v_mfma_scale_f32_16x16x128_f8f6f4 v[74:77], v[10:17], v[164:171], v[74:77], v208, v208 op_sel_hi:[0,0,0]
	v_mfma_scale_f32_16x16x128_f8f6f4 v[70:73], v[2:9], v[172:179], v[216:219], v208, v208 op_sel_hi:[0,0,0]
	v_mfma_scale_f32_16x16x128_f8f6f4 v[66:69], v[10:17], v[172:179], v[220:223], v208, v208 op_sel_hi:[0,0,0]
	v_mfma_scale_f32_16x16x128_f8f6f4 v[30:33], v[132:139], v[18:25], v[224:227], v208, v208 op_sel_hi:[0,0,0]
	v_mfma_scale_f32_16x16x128_f8f6f4 v[26:29], v[140:147], v[18:25], v[228:231], v208, v208 op_sel_hi:[0,0,0]
	v_mfma_scale_f32_16x16x128_f8f6f4 v[22:25], v[132:139], v[156:163], v[232:235], v208, v208 op_sel_hi:[0,0,0]
	v_mfma_scale_f32_16x16x128_f8f6f4 v[18:21], v[140:147], v[156:163], v[236:239], v208, v208 op_sel_hi:[0,0,0]
	v_mfma_scale_f32_16x16x128_f8f6f4 v[14:17], v[132:139], v[164:171], v[240:243], v208, v208 op_sel_hi:[0,0,0]
	v_mfma_scale_f32_16x16x128_f8f6f4 v[10:13], v[140:147], v[164:171], v[244:247], v208, v208 op_sel_hi:[0,0,0]
	v_mfma_scale_f32_16x16x128_f8f6f4 v[6:9], v[132:139], v[172:179], v[248:251], v208, v208 op_sel_hi:[0,0,0]
	v_mfma_scale_f32_16x16x128_f8f6f4 v[2:5], v[140:147], v[172:179], v[204:207], v208, v208 op_sel_hi:[0,0,0]
	s_barrier
	s_setprio 0
	s_add_i32 s46, s46, 2
	s_add_u32 s6, s6, 0x8000
	s_addc_u32 s7, s7, 0
	s_cmp_gt_u32 s46, 41
	s_cbranch_scc0 .LBB0_914
	v_readlane_b32 s4, v255, 1
	v_readlane_b32 s5, v255, 2
	s_and_b64 vcc, exec, s[4:5]
	s_cbranch_vccz .LBB0_917
	s_barrier

; #define PG8_STAGE(bufoff, gbase, unused) do { _Pragma("unroll") for (int _i = 0; _i < 2; ++_i) \
;         __builtin_amdgcn_global_load_lds((const unsigned*)((const char*)(gbase) + voff + _i * 8192), (LAS unsigned*)(lds + (bufoff) + ldsw + _i * 8192), 16, 0, 0); } while (0)
; #define PG8_LDA(dst, b, h) do { _Pragma("unroll") for (int m = 0; m < 4; ++m) _Pragma("unroll") for (int k = 0; k < 2; ++k) dst[m][k] = *(const LAS bf16x8*)(lds + PG8_SA(b, h) + aoff + m * 2048 + (FP8 ? k * 16 : k * 1024)); } while (0)
; #define PG8_LDB(dst, b, h) do { _Pragma("unroll") for (int n = 0; n < 2; ++n) _Pragma("unroll") for (int k = 0; k < 2; ++k) dst[n][k] = *(const LAS bf16x8*)(lds + PG8_SB(b, h) + boff + n * 2048 + (FP8 ? k * 16 : k * 1024)); } while (0)
; #define PG8_WAIT_V(n) asm volatile("s_waitcnt vmcnt(" #n ")" ::: "memory")
; #define PG8_WAIT_L(n) asm volatile("s_waitcnt lgkmcnt(" #n ")" ::: "memory")
; #define PG8_BAR __builtin_amdgcn_s_barrier()
; #define PG8_SCHED __builtin_amdgcn_sched_barrier(0)
; template <class Epi, class Sched, bool ALIGN_EPI, bool SP2, int MODE  >
; __device__ __forceinline__ void gemm_phase(LAS unsigned char* lds, const Gemm g, const Sched S, const Epi E, unsigned long long& probe_acc, int epi_id, int wv) {
;     ...
;                 for (int n = 0; n < 2; ++n) acc[a][b][m][n] = (f32x4){0.f, 0.f, 0.f, 0.f};
;     ...
;             PG8_LDB(B0, 0, 0); PG8_LDB(B1, 0, 1); PG8_SCHED; PG8_LDA(At, 0, 0); PG8_STAGE(PG8_SA(1, 1), a1 + hA, voffA);
;             PG8_WAIT_V(8); PG8_WAIT_L(0); PG8_BAR; PG8_MMA(0, 0, At, B0); PG8_MMA(0, 1, At, B1); PG8_BAR; PG8_SCHED;
;             PG8_LDA(At, 0, 1); PG8_STAGE(PG8_SB(0, 0), b2, voffB); PG8_STAGE(PG8_SB(0, 1), b2 + hB, voffB); PG8_STAGE(PG8_SA(0, 0), a2, voffA);
;             PG8_WAIT_V(8); PG8_WAIT_L(0); PG8_BAR; PG8_MMA(1, 0, At, B0); PG8_MMA(1, 1, At, B1); PG8_BAR; PG8_SCHED;
.LBB0_1153:
	s_add_u32 s8, s4, s40
	s_addc_u32 s9, s5, 0
	s_add_u32 s10, s6, 0x8000
	s_waitcnt vmcnt(0)
	v_lshl_add_u64 v[130:131], s[8:9], 0, v[0:1]
	s_addc_u32 s11, s7, 0
	s_mov_b32 s34, -2
	s_mov_b64 s[6:7], 0
	s_waitcnt lgkmcnt(0)
	s_mov_b64 s[42:43], 0xb0000
	v_add_u32_e32 v144, s90, v200
	v_add_u32_e32 v160, s15, v200
	s_add_u32 s8, s4, s6
	ds_read_b128 v[132:135], v144
	ds_read_b128 v[136:139], v144 offset:1024
	ds_read_b128 v[140:143], v144 offset:2048
	ds_read_b128 v[144:147], v144 offset:3072
	ds_read_b128 v[148:151], v160
	ds_read_b128 v[152:155], v160 offset:1024
	ds_read_b128 v[156:159], v160 offset:2048
	ds_read_b128 v[164:167], v160 offset:3072
	s_addc_u32 s9, s5, s7
	s_add_u32 s8, s8, 0x8000
	s_addc_u32 s9, s9, 0
	s_add_u32 s28, s10, s6
	s_addc_u32 s29, s11, s7
	s_cmp_eq_u32 s6, 0xa8000
	s_cselect_b32 s9, s67, s9
	s_cselect_b32 s8, s66, s8
	s_cselect_b32 vcc_hi, s87, s29
	s_cselect_b32 vcc_lo, s86, s28
	v_lshl_add_u64 v[160:161], v[130:131], 0, s[6:7]
	v_lshl_add_u64 v[196:197], v[160:161], 0, s[76:77]
	s_add_i32 m0, s0, 0xc000
	ds_read_b128 v[168:171], v201
	ds_read_b128 v[172:175], v201 offset:1024
	ds_read_b128 v[176:179], v201 offset:2048
	ds_read_b128 v[180:183], v201 offset:3072
	ds_read_b128 v[184:187], v201 offset:4096
	ds_read_b128 v[188:191], v201 offset:5120
	ds_read_b128 v[192:195], v201 offset:6144
	ds_read_b128 v[212:215], v201 offset:7168
	global_load_lds_dwordx4 v[196:197], off
	v_lshl_add_u64 v[160:161], v[160:161], 0, s[78:79]
	s_add_i32 m0, s0, 0xe000
	s_nop 0
	global_load_lds_dwordx4 v[160:161], off
	s_waitcnt vmcnt(8)
	s_waitcnt lgkmcnt(0)
	s_setprio 1
	s_barrier
	v_mfma_i32_16x16x64_i8 v[122:125], v[132:135], v[168:171], 0
	v_mfma_i32_16x16x64_i8 v[126:129], v[140:143], v[168:171], 0
	v_mfma_i32_16x16x64_i8 v[114:117], v[132:135], v[176:179], 0
	v_mfma_i32_16x16x64_i8 v[118:121], v[140:143], v[176:179], 0
	v_mfma_i32_16x16x64_i8 v[106:109], v[132:135], v[184:187], 0
	v_mfma_i32_16x16x64_i8 v[110:113], v[140:143], v[184:187], 0
	v_mfma_i32_16x16x64_i8 v[98:101], v[132:135], v[192:195], 0
	v_mfma_i32_16x16x64_i8 v[102:105], v[140:143], v[192:195], 0
	v_mfma_i32_16x16x64_i8 v[122:125], v[136:139], v[172:175], v[122:125]
	v_mfma_i32_16x16x64_i8 v[126:129], v[144:147], v[172:175], v[126:129]
	v_mfma_i32_16x16x64_i8 v[114:117], v[136:139], v[180:183], v[114:117]
	v_mfma_i32_16x16x64_i8 v[118:121], v[144:147], v[180:183], v[118:121]
	v_mfma_i32_16x16x64_i8 v[106:109], v[136:139], v[188:191], v[106:109]
	v_mfma_i32_16x16x64_i8 v[110:113], v[144:147], v[188:191], v[110:113]
	v_mfma_i32_16x16x64_i8 v[98:101], v[136:139], v[212:215], v[98:101]
	v_mfma_i32_16x16x64_i8 v[102:105], v[144:147], v[212:215], v[102:105]
	v_mfma_i32_16x16x64_i8 v[58:61], v[148:151], v[168:171], 0
	v_mfma_i32_16x16x64_i8 v[62:65], v[156:159], v[168:171], 0
	v_mfma_i32_16x16x64_i8 v[50:53], v[148:151], v[176:179], 0
	v_mfma_i32_16x16x64_i8 v[54:57], v[156:159], v[176:179], 0
	v_mfma_i32_16x16x64_i8 v[42:45], v[148:151], v[184:187], 0
	v_mfma_i32_16x16x64_i8 v[46:49], v[156:159], v[184:187], 0
	v_mfma_i32_16x16x64_i8 v[34:37], v[148:151], v[192:195], 0
	v_mfma_i32_16x16x64_i8 v[38:41], v[156:159], v[192:195], 0
	v_mfma_i32_16x16x64_i8 v[58:61], v[152:155], v[172:175], v[58:61]
	v_mfma_i32_16x16x64_i8 v[62:65], v[164:167], v[172:175], v[62:65]
	v_mfma_i32_16x16x64_i8 v[50:53], v[152:155], v[180:183], v[50:53]
	v_mfma_i32_16x16x64_i8 v[54:57], v[164:167], v[180:183], v[54:57]
	v_mfma_i32_16x16x64_i8 v[42:45], v[152:155], v[188:191], v[42:45]
	v_mfma_i32_16x16x64_i8 v[46:49], v[164:167], v[188:191], v[46:49]
	v_mfma_i32_16x16x64_i8 v[34:37], v[152:155], v[212:215], v[34:37]
	v_mfma_i32_16x16x64_i8 v[38:41], v[164:167], v[212:215], v[38:41]
	s_barrier
	s_setprio 0
	s_mov_b32 m0, s91
	v_lshl_add_u64 v[160:161], vcc, 0, v[0:1]
	ds_read_b128 v[168:171], v201 offset:16384
	ds_read_b128 v[172:175], v201 offset:17408
	ds_read_b128 v[176:179], v201 offset:18432
	ds_read_b128 v[180:183], v201 offset:19456
	ds_read_b128 v[184:187], v201 offset:20480
	ds_read_b128 v[188:191], v201 offset:21504
	ds_read_b128 v[192:195], v201 offset:22528
	ds_read_b128 v[212:215], v201 offset:23552
	global_load_lds_dwordx4 v[160:161], off
	v_lshl_add_u64 v[196:197], v[160:161], 0, s[70:71]
	s_mov_b32 m0, s14
	s_nop 0
	global_load_lds_dwordx4 v[196:197], off
	v_lshl_add_u64 v[196:197], v[160:161], 0, s[42:43]
	s_mov_b32 m0, s26
	s_nop 0
	global_load_lds_dwordx4 v[196:197], off
	v_lshl_add_u64 v[196:197], v[160:161], 0, s[48:49]
	s_mov_b32 m0, s27
	s_nop 0
	global_load_lds_dwordx4 v[196:197], off
	v_lshl_add_u64 v[196:197], s[8:9], 0, v[0:1]
	s_mov_b32 m0, s0
	v_lshl_add_u64 v[202:203], v[196:197], 0, s[70:71]
	global_load_lds_dwordx4 v[196:197], off
	s_mov_b32 m0, s1
	s_nop 0
	global_load_lds_dwordx4 v[202:203], off
	s_waitcnt vmcnt(8)
	s_waitcnt lgkmcnt(0)
	s_setprio 1
	s_barrier
; #define PG8_STAGE(bufoff, gbase, unused) do { _Pragma("unroll") for (int _i = 0; _i < 2; ++_i) \
;         __builtin_amdgcn_global_load_lds((const unsigned*)((const char*)(gbase) + voff + _i * 8192), (LAS unsigned*)(lds + (bufoff) + ldsw + _i * 8192), 16, 0, 0); } while (0)
; #define PG8_LDA(dst, b, h) do { _Pragma("unroll") for (int m = 0; m < 4; ++m) _Pragma("unroll") for (int k = 0; k < 2; ++k) dst[m][k] = *(const LAS bf16x8*)(lds + PG8_SA(b, h) + aoff + m * 2048 + (FP8 ? k * 16 : k * 1024)); } while (0)
; #define PG8_LDB(dst, b, h) do { _Pragma("unroll") for (int n = 0; n < 2; ++n) _Pragma("unroll") for (int k = 0; k < 2; ++k) dst[n][k] = *(const LAS bf16x8*)(lds + PG8_SB(b, h) + boff + n * 2048 + (FP8 ? k * 16 : k * 1024)); } while (0)
; #define PG8_WAIT_V(n) asm volatile("s_waitcnt vmcnt(" #n ")" ::: "memory")
; #define PG8_WAIT_L(n) asm volatile("s_waitcnt lgkmcnt(" #n ")" ::: "memory")
; #define PG8_BAR __builtin_amdgcn_s_barrier()
; #define PG8_SCHED __builtin_amdgcn_sched_barrier(0)
; template <class Epi, class Sched, bool ALIGN_EPI, bool SP2, int MODE  >
; __device__ __forceinline__ void gemm_phase(LAS unsigned char* lds, const Gemm g, const Sched S, const Epi E, unsigned long long& probe_acc, int epi_id, int wv) {
;     ...
;             PG8_WAIT_V(8); PG8_WAIT_L(0); PG8_BAR; PG8_MMA(1, 0, At, B0); PG8_MMA(1, 1, At, B1); PG8_BAR; PG8_SCHED;
;             PG8_LDB(B0, 1, 0); PG8_LDB(B1, 1, 1); PG8_SCHED; PG8_LDA(At, 1, 0); PG8_STAGE(PG8_SA(0, 1), a2 + hA, voffA);
;             PG8_WAIT_V(8); PG8_WAIT_L(0); PG8_BAR; PG8_MMA(0, 0, At, B0); PG8_MMA(0, 1, At, B1); PG8_BAR; PG8_SCHED;
	v_mfma_i32_16x16x64_i8 v[90:93], v[132:135], v[168:171], 0
	v_mfma_i32_16x16x64_i8 v[94:97], v[140:143], v[168:171], 0
	v_mfma_i32_16x16x64_i8 v[82:85], v[132:135], v[176:179], 0
	v_mfma_i32_16x16x64_i8 v[86:89], v[140:143], v[176:179], 0
	v_mfma_i32_16x16x64_i8 v[74:77], v[132:135], v[184:187], 0
	v_mfma_i32_16x16x64_i8 v[78:81], v[140:143], v[184:187], 0
	v_mfma_i32_16x16x64_i8 v[66:69], v[132:135], v[192:195], 0
	v_mfma_i32_16x16x64_i8 v[70:73], v[140:143], v[192:195], 0
	v_mfma_i32_16x16x64_i8 v[90:93], v[136:139], v[172:175], v[90:93]
	v_mfma_i32_16x16x64_i8 v[94:97], v[144:147], v[172:175], v[94:97]
	v_mfma_i32_16x16x64_i8 v[82:85], v[136:139], v[180:183], v[82:85]
	v_mfma_i32_16x16x64_i8 v[86:89], v[144:147], v[180:183], v[86:89]
	v_mfma_i32_16x16x64_i8 v[74:77], v[136:139], v[188:191], v[74:77]
	v_mfma_i32_16x16x64_i8 v[78:81], v[144:147], v[188:191], v[78:81]
	v_mfma_i32_16x16x64_i8 v[66:69], v[136:139], v[212:215], v[66:69]
	v_mfma_i32_16x16x64_i8 v[70:73], v[144:147], v[212:215], v[70:73]
	v_mfma_i32_16x16x64_i8 v[26:29], v[148:151], v[168:171], 0
	v_mfma_i32_16x16x64_i8 v[30:33], v[156:159], v[168:171], 0
	v_mfma_i32_16x16x64_i8 v[18:21], v[148:151], v[176:179], 0
	v_mfma_i32_16x16x64_i8 v[22:25], v[156:159], v[176:179], 0
	v_mfma_i32_16x16x64_i8 v[10:13], v[148:151], v[184:187], 0
	v_mfma_i32_16x16x64_i8 v[14:17], v[156:159], v[184:187], 0
	v_mfma_i32_16x16x64_i8 v[2:5], v[148:151], v[192:195], 0
	v_mfma_i32_16x16x64_i8 v[6:9], v[156:159], v[192:195], 0
	v_mfma_i32_16x16x64_i8 v[26:29], v[152:155], v[172:175], v[26:29]
	v_mfma_i32_16x16x64_i8 v[30:33], v[164:167], v[172:175], v[30:33]
	v_mfma_i32_16x16x64_i8 v[18:21], v[152:155], v[180:183], v[18:21]
	v_mfma_i32_16x16x64_i8 v[22:25], v[164:167], v[180:183], v[22:25]
	v_mfma_i32_16x16x64_i8 v[10:13], v[152:155], v[188:191], v[10:13]
	v_mfma_i32_16x16x64_i8 v[14:17], v[164:167], v[188:191], v[14:17]
	v_mfma_i32_16x16x64_i8 v[2:5], v[152:155], v[212:215], v[2:5]
	v_mfma_i32_16x16x64_i8 v[6:9], v[164:167], v[212:215], v[6:9]
	s_barrier
	s_setprio 0
	v_add_u32_e32 v144, s88, v200
	v_add_u32_e32 v162, s95, v200
	ds_read_b128 v[132:135], v144
	ds_read_b128 v[136:139], v144 offset:1024
	ds_read_b128 v[140:143], v144 offset:2048
	ds_read_b128 v[144:147], v144 offset:3072
	ds_read_b128 v[148:151], v162
	ds_read_b128 v[152:155], v162 offset:1024
	ds_read_b128 v[156:159], v162 offset:2048
	ds_read_b128 v[164:167], v162 offset:3072
	s_add_u32 s8, s8, s40
	s_addc_u32 s9, s9, 0
	s_mov_b32 m0, s36
	v_lshl_add_u64 v[202:203], s[8:9], 0, v[0:1]
	ds_read_b128 v[168:171], v201 offset:32768
	ds_read_b128 v[172:175], v201 offset:33792
	ds_read_b128 v[176:179], v201 offset:34816
	ds_read_b128 v[180:183], v201 offset:35840
	ds_read_b128 v[184:187], v201 offset:36864
	ds_read_b128 v[188:191], v201 offset:37888
	ds_read_b128 v[192:195], v201 offset:38912
	ds_read_b128 v[212:215], v201 offset:39936
	global_load_lds_dwordx4 v[202:203], off
	v_lshl_add_u64 v[202:203], v[202:203], 0, s[70:71]
	s_mov_b32 m0, s37
	s_nop 0
	global_load_lds_dwordx4 v[202:203], off
	s_waitcnt vmcnt(8)
	s_waitcnt lgkmcnt(0)
	s_setprio 1
	s_barrier
	v_mfma_i32_16x16x64_i8 v[122:125], v[132:135], v[168:171], v[122:125]
	v_mfma_i32_16x16x64_i8 v[126:129], v[140:143], v[168:171], v[126:129]
	v_mfma_i32_16x16x64_i8 v[114:117], v[132:135], v[176:179], v[114:117]
	v_mfma_i32_16x16x64_i8 v[118:121], v[140:143], v[176:179], v[118:121]
	v_mfma_i32_16x16x64_i8 v[106:109], v[132:135], v[184:187], v[106:109]
	v_mfma_i32_16x16x64_i8 v[110:113], v[140:143], v[184:187], v[110:113]
	v_mfma_i32_16x16x64_i8 v[98:101], v[132:135], v[192:195], v[98:101]
	v_mfma_i32_16x16x64_i8 v[102:105], v[140:143], v[192:195], v[102:105]
	v_mfma_i32_16x16x64_i8 v[122:125], v[136:139], v[172:175], v[122:125]
	v_mfma_i32_16x16x64_i8 v[126:129], v[144:147], v[172:175], v[126:129]
	v_mfma_i32_16x16x64_i8 v[114:117], v[136:139], v[180:183], v[114:117]
	v_mfma_i32_16x16x64_i8 v[118:121], v[144:147], v[180:183], v[118:121]
	v_mfma_i32_16x16x64_i8 v[106:109], v[136:139], v[188:191], v[106:109]
	v_mfma_i32_16x16x64_i8 v[110:113], v[144:147], v[188:191], v[110:113]
	v_mfma_i32_16x16x64_i8 v[98:101], v[136:139], v[212:215], v[98:101]
	v_mfma_i32_16x16x64_i8 v[102:105], v[144:147], v[212:215], v[102:105]
	v_mfma_i32_16x16x64_i8 v[58:61], v[148:151], v[168:171], v[58:61]
	v_mfma_i32_16x16x64_i8 v[62:65], v[156:159], v[168:171], v[62:65]
	v_mfma_i32_16x16x64_i8 v[50:53], v[148:151], v[176:179], v[50:53]
	v_mfma_i32_16x16x64_i8 v[54:57], v[156:159], v[176:179], v[54:57]
	v_mfma_i32_16x16x64_i8 v[42:45], v[148:151], v[184:187], v[42:45]
	v_mfma_i32_16x16x64_i8 v[46:49], v[156:159], v[184:187], v[46:49]
	v_mfma_i32_16x16x64_i8 v[34:37], v[148:151], v[192:195], v[34:37]
	v_mfma_i32_16x16x64_i8 v[38:41], v[156:159], v[192:195], v[38:41]
	v_mfma_i32_16x16x64_i8 v[58:61], v[152:155], v[172:175], v[58:61]
	v_mfma_i32_16x16x64_i8 v[62:65], v[164:167], v[172:175], v[62:65]
	v_mfma_i32_16x16x64_i8 v[50:53], v[152:155], v[180:183], v[50:53]
	v_mfma_i32_16x16x64_i8 v[54:57], v[164:167], v[180:183], v[54:57]
	v_mfma_i32_16x16x64_i8 v[42:45], v[152:155], v[188:191], v[42:45]
	v_mfma_i32_16x16x64_i8 v[46:49], v[164:167], v[188:191], v[46:49]
	v_mfma_i32_16x16x64_i8 v[34:37], v[152:155], v[212:215], v[34:37]
	v_mfma_i32_16x16x64_i8 v[38:41], v[164:167], v[212:215], v[38:41]
	s_barrier
; #define PG8_STAGE(bufoff, gbase, unused) do { _Pragma("unroll") for (int _i = 0; _i < 2; ++_i) \
;         __builtin_amdgcn_global_load_lds((const unsigned*)((const char*)(gbase) + voff + _i * 8192), (LAS unsigned*)(lds + (bufoff) + ldsw + _i * 8192), 16, 0, 0); } while (0)
; #define PG8_LDA(dst, b, h) do { _Pragma("unroll") for (int m = 0; m < 4; ++m) _Pragma("unroll") for (int k = 0; k < 2; ++k) dst[m][k] = *(const LAS bf16x8*)(lds + PG8_SA(b, h) + aoff + m * 2048 + (FP8 ? k * 16 : k * 1024)); } while (0)
; #define PG8_LDB(dst, b, h) do { _Pragma("unroll") for (int n = 0; n < 2; ++n) _Pragma("unroll") for (int k = 0; k < 2; ++k) dst[n][k] = *(const LAS bf16x8*)(lds + PG8_SB(b, h) + boff + n * 2048 + (FP8 ? k * 16 : k * 1024)); } while (0)
; #define PG8_WAIT_V(n) asm volatile("s_waitcnt vmcnt(" #n ")" ::: "memory")
; #define PG8_WAIT_L(n) asm volatile("s_waitcnt lgkmcnt(" #n ")" ::: "memory")
; #define PG8_BAR __builtin_amdgcn_s_barrier()
; #define PG8_SCHED __builtin_amdgcn_sched_barrier(0)
; template <class Epi, class Sched, bool ALIGN_EPI, bool SP2, int MODE  >
; __device__ __forceinline__ void gemm_phase(LAS unsigned char* lds, const Gemm g, const Sched S, const Epi E, unsigned long long& probe_acc, int epi_id, int wv) {
;     ...
;         for (int t = 0; t < nt; t += 2) {
;             const bool last = (t == nt - 2);
;             const char* a1 = cA + (size_t)(t + 1) * kstep;
;             const char* a2 = last ? nA : cA + (size_t)(t + 2) * kstep; const char* b2 = last ? nB : cB + (size_t)(t + 2) * kstep;
;             const char* a3 = a2 + kstep; const char* b3 = b2 + kstep;
;             if constexpr (SP2) {
;             PG8_LDB(B0, 0, 0); PG8_LDB(B1, 0, 1); PG8_SCHED; PG8_LDA(At, 0, 0); PG8_STAGE(PG8_SA(1, 1), a1 + hA, voffA);
;     ...
;             PG8_LDA(At, 1, 1); PG8_STAGE(PG8_SB(1, 0), b3, voffB); PG8_STAGE(PG8_SB(1, 1), b3 + hB, voffB); PG8_STAGE(PG8_SA(1, 0), a3, voffA);
;             PG8_WAIT_V(8); PG8_WAIT_L(0); PG8_BAR; PG8_MMA(1, 0, At, B0); PG8_MMA(1, 1, At, B1); PG8_BAR; PG8_SCHED;
	s_setprio 0
	s_mov_b32 m0, s89
	v_lshl_add_u64 v[202:203], v[160:161], 0, s[76:77]
	ds_read_b128 v[168:171], v201 offset:49152
	ds_read_b128 v[172:175], v201 offset:50176
	ds_read_b128 v[176:179], v201 offset:51200
	ds_read_b128 v[180:183], v201 offset:52224
	ds_read_b128 v[184:187], v201 offset:53248
	ds_read_b128 v[188:191], v201 offset:54272
	ds_read_b128 v[192:195], v201 offset:55296
	ds_read_b128 v[212:215], v201 offset:56320
	global_load_lds_dwordx4 v[202:203], off
	v_lshl_add_u64 v[202:203], v[160:161], 0, s[78:79]
	s_mov_b32 m0, s92
	s_nop 0
	global_load_lds_dwordx4 v[202:203], off
	v_lshl_add_u64 v[202:203], v[160:161], 0, s[44:45]
	s_mov_b32 m0, s84
	v_lshl_add_u64 v[160:161], v[160:161], 0, s[56:57]
	global_load_lds_dwordx4 v[202:203], off
	s_mov_b32 m0, s12
	s_nop 0
	global_load_lds_dwordx4 v[160:161], off
	v_lshl_add_u64 v[160:161], v[196:197], 0, s[76:77]
	s_mov_b32 m0, s93
	s_nop 0
	global_load_lds_dwordx4 v[160:161], off
	v_lshl_add_u64 v[160:161], v[196:197], 0, s[78:79]
	s_mov_b32 m0, s94
	s_nop 0
	global_load_lds_dwordx4 v[160:161], off
	s_waitcnt vmcnt(8)
	s_waitcnt lgkmcnt(0)
	s_setprio 1
	s_barrier
	v_mfma_i32_16x16x64_i8 v[90:93], v[132:135], v[168:171], v[90:93]
	v_mfma_i32_16x16x64_i8 v[94:97], v[140:143], v[168:171], v[94:97]
	v_mfma_i32_16x16x64_i8 v[82:85], v[132:135], v[176:179], v[82:85]
	v_mfma_i32_16x16x64_i8 v[86:89], v[140:143], v[176:179], v[86:89]
	v_mfma_i32_16x16x64_i8 v[74:77], v[132:135], v[184:187], v[74:77]
	v_mfma_i32_16x16x64_i8 v[78:81], v[140:143], v[184:187], v[78:81]
	v_mfma_i32_16x16x64_i8 v[66:69], v[132:135], v[192:195], v[66:69]
	v_mfma_i32_16x16x64_i8 v[70:73], v[140:143], v[192:195], v[70:73]
	v_mfma_i32_16x16x64_i8 v[90:93], v[136:139], v[172:175], v[90:93]
	v_mfma_i32_16x16x64_i8 v[94:97], v[144:147], v[172:175], v[94:97]
	v_mfma_i32_16x16x64_i8 v[82:85], v[136:139], v[180:183], v[82:85]
	v_mfma_i32_16x16x64_i8 v[86:89], v[144:147], v[180:183], v[86:89]
	v_mfma_i32_16x16x64_i8 v[74:77], v[136:139], v[188:191], v[74:77]
	v_mfma_i32_16x16x64_i8 v[78:81], v[144:147], v[188:191], v[78:81]
	v_mfma_i32_16x16x64_i8 v[66:69], v[136:139], v[212:215], v[66:69]
	v_mfma_i32_16x16x64_i8 v[70:73], v[144:147], v[212:215], v[70:73]
	v_mfma_i32_16x16x64_i8 v[26:29], v[148:151], v[168:171], v[26:29]
	v_mfma_i32_16x16x64_i8 v[30:33], v[156:159], v[168:171], v[30:33]
	v_mfma_i32_16x16x64_i8 v[18:21], v[148:151], v[176:179], v[18:21]
	v_mfma_i32_16x16x64_i8 v[22:25], v[156:159], v[176:179], v[22:25]
	v_mfma_i32_16x16x64_i8 v[10:13], v[148:151], v[184:187], v[10:13]
	v_mfma_i32_16x16x64_i8 v[14:17], v[156:159], v[184:187], v[14:17]
	v_mfma_i32_16x16x64_i8 v[2:5], v[148:151], v[192:195], v[2:5]
	v_mfma_i32_16x16x64_i8 v[6:9], v[156:159], v[192:195], v[6:9]
	v_mfma_i32_16x16x64_i8 v[26:29], v[152:155], v[172:175], v[26:29]
	v_mfma_i32_16x16x64_i8 v[30:33], v[164:167], v[172:175], v[30:33]
	v_mfma_i32_16x16x64_i8 v[18:21], v[152:155], v[180:183], v[18:21]
	v_mfma_i32_16x16x64_i8 v[22:25], v[164:167], v[180:183], v[22:25]
	v_mfma_i32_16x16x64_i8 v[10:13], v[152:155], v[188:191], v[10:13]
	v_mfma_i32_16x16x64_i8 v[14:17], v[164:167], v[188:191], v[14:17]
	v_mfma_i32_16x16x64_i8 v[2:5], v[152:155], v[212:215], v[2:5]
	v_mfma_i32_16x16x64_i8 v[6:9], v[164:167], v[212:215], v[6:9]
	s_barrier
	s_setprio 0
	s_add_i32 s34, s34, 2
	s_add_u32 s6, s6, 0x8000
	s_addc_u32 s7, s7, 0
	s_cmp_gt_u32 s34, 41
.LBB0_1154:
	v_add_u32_e32 v144, s90, v200
	v_add_u32_e32 v160, s15, v200
	s_add_u32 s8, s4, s6
	ds_read_b128 v[132:135], v144
	ds_read_b128 v[136:139], v144 offset:1024
	ds_read_b128 v[140:143], v144 offset:2048
	ds_read_b128 v[144:147], v144 offset:3072
	ds_read_b128 v[148:151], v160
	ds_read_b128 v[152:155], v160 offset:1024
	ds_read_b128 v[156:159], v160 offset:2048
	ds_read_b128 v[164:167], v160 offset:3072
	s_addc_u32 s9, s5, s7
	s_add_u32 s8, s8, 0x8000
	s_addc_u32 s9, s9, 0
	s_add_u32 s28, s10, s6
	s_addc_u32 s29, s11, s7
	s_cmp_eq_u32 s6, 0xa8000
	s_cselect_b32 s9, s67, s9
	s_cselect_b32 s8, s66, s8
	s_cselect_b32 vcc_hi, s87, s29
	s_cselect_b32 vcc_lo, s86, s28
	v_lshl_add_u64 v[160:161], v[130:131], 0, s[6:7]
	v_lshl_add_u64 v[196:197], v[160:161], 0, s[76:77]
	s_add_i32 m0, s0, 0xc000
	ds_read_b128 v[168:171], v201
	ds_read_b128 v[172:175], v201 offset:1024
	ds_read_b128 v[176:179], v201 offset:2048
	ds_read_b128 v[180:183], v201 offset:3072
	ds_read_b128 v[184:187], v201 offset:4096
	ds_read_b128 v[188:191], v201 offset:5120
	ds_read_b128 v[192:195], v201 offset:6144
	ds_read_b128 v[212:215], v201 offset:7168
	global_load_lds_dwordx4 v[196:197], off
	v_lshl_add_u64 v[160:161], v[160:161], 0, s[78:79]
	s_add_i32 m0, s0, 0xe000
	s_nop 0
	global_load_lds_dwordx4 v[160:161], off
	s_waitcnt vmcnt(8)
	s_waitcnt lgkmcnt(0)
	s_setprio 1
	s_barrier
; #define PG8_STAGE(bufoff, gbase, unused) do { _Pragma("unroll") for (int _i = 0; _i < 2; ++_i) \
;         __builtin_amdgcn_global_load_lds((const unsigned*)((const char*)(gbase) + voff + _i * 8192), (LAS unsigned*)(lds + (bufoff) + ldsw + _i * 8192), 16, 0, 0); } while (0)
; #define PG8_LDA(dst, b, h) do { _Pragma("unroll") for (int m = 0; m < 4; ++m) _Pragma("unroll") for (int k = 0; k < 2; ++k) dst[m][k] = *(const LAS bf16x8*)(lds + PG8_SA(b, h) + aoff + m * 2048 + (FP8 ? k * 16 : k * 1024)); } while (0)
; #define PG8_WAIT_V(n) asm volatile("s_waitcnt vmcnt(" #n ")" ::: "memory")
; #define PG8_WAIT_L(n) asm volatile("s_waitcnt lgkmcnt(" #n ")" ::: "memory")
; #define PG8_BAR __builtin_amdgcn_s_barrier()
; #define PG8_SCHED __builtin_amdgcn_sched_barrier(0)
; template <class Epi, class Sched, bool ALIGN_EPI, bool SP2, int MODE  >
; __device__ __forceinline__ void gemm_phase(LAS unsigned char* lds, const Gemm g, const Sched S, const Epi E, unsigned long long& probe_acc, int epi_id, int wv) {
;     ...
;             PG8_WAIT_V(8); PG8_WAIT_L(0); PG8_BAR; PG8_MMA(0, 0, At, B0); PG8_MMA(0, 1, At, B1); PG8_BAR; PG8_SCHED;
;             PG8_LDA(At, 0, 1); PG8_STAGE(PG8_SB(0, 0), b2, voffB); PG8_STAGE(PG8_SB(0, 1), b2 + hB, voffB); PG8_STAGE(PG8_SA(0, 0), a2, voffA);
;             PG8_WAIT_V(8); PG8_WAIT_L(0); PG8_BAR; PG8_MMA(1, 0, At, B0); PG8_MMA(1, 1, At, B1); PG8_BAR; PG8_SCHED;
	v_mfma_i32_16x16x64_i8 v[122:125], v[132:135], v[168:171], v[122:125]
	v_mfma_i32_16x16x64_i8 v[126:129], v[140:143], v[168:171], v[126:129]
	v_mfma_i32_16x16x64_i8 v[114:117], v[132:135], v[176:179], v[114:117]
	v_mfma_i32_16x16x64_i8 v[118:121], v[140:143], v[176:179], v[118:121]
	v_mfma_i32_16x16x64_i8 v[106:109], v[132:135], v[184:187], v[106:109]
	v_mfma_i32_16x16x64_i8 v[110:113], v[140:143], v[184:187], v[110:113]
	v_mfma_i32_16x16x64_i8 v[98:101], v[132:135], v[192:195], v[98:101]
	v_mfma_i32_16x16x64_i8 v[102:105], v[140:143], v[192:195], v[102:105]
	v_mfma_i32_16x16x64_i8 v[122:125], v[136:139], v[172:175], v[122:125]
	v_mfma_i32_16x16x64_i8 v[126:129], v[144:147], v[172:175], v[126:129]
	v_mfma_i32_16x16x64_i8 v[114:117], v[136:139], v[180:183], v[114:117]
	v_mfma_i32_16x16x64_i8 v[118:121], v[144:147], v[180:183], v[118:121]
	v_mfma_i32_16x16x64_i8 v[106:109], v[136:139], v[188:191], v[106:109]
	v_mfma_i32_16x16x64_i8 v[110:113], v[144:147], v[188:191], v[110:113]
	v_mfma_i32_16x16x64_i8 v[98:101], v[136:139], v[212:215], v[98:101]
	v_mfma_i32_16x16x64_i8 v[102:105], v[144:147], v[212:215], v[102:105]
	v_mfma_i32_16x16x64_i8 v[58:61], v[148:151], v[168:171], v[58:61]
	v_mfma_i32_16x16x64_i8 v[62:65], v[156:159], v[168:171], v[62:65]
	v_mfma_i32_16x16x64_i8 v[50:53], v[148:151], v[176:179], v[50:53]
	v_mfma_i32_16x16x64_i8 v[54:57], v[156:159], v[176:179], v[54:57]
	v_mfma_i32_16x16x64_i8 v[42:45], v[148:151], v[184:187], v[42:45]
	v_mfma_i32_16x16x64_i8 v[46:49], v[156:159], v[184:187], v[46:49]
	v_mfma_i32_16x16x64_i8 v[34:37], v[148:151], v[192:195], v[34:37]
	v_mfma_i32_16x16x64_i8 v[38:41], v[156:159], v[192:195], v[38:41]
	v_mfma_i32_16x16x64_i8 v[58:61], v[152:155], v[172:175], v[58:61]
	v_mfma_i32_16x16x64_i8 v[62:65], v[164:167], v[172:175], v[62:65]
	v_mfma_i32_16x16x64_i8 v[50:53], v[152:155], v[180:183], v[50:53]
	v_mfma_i32_16x16x64_i8 v[54:57], v[164:167], v[180:183], v[54:57]
	v_mfma_i32_16x16x64_i8 v[42:45], v[152:155], v[188:191], v[42:45]
	v_mfma_i32_16x16x64_i8 v[46:49], v[164:167], v[188:191], v[46:49]
	v_mfma_i32_16x16x64_i8 v[34:37], v[152:155], v[212:215], v[34:37]
	v_mfma_i32_16x16x64_i8 v[38:41], v[164:167], v[212:215], v[38:41]
	s_barrier
	s_setprio 0
	s_mov_b32 m0, s91
	v_lshl_add_u64 v[160:161], vcc, 0, v[0:1]
	ds_read_b128 v[168:171], v201 offset:16384
	ds_read_b128 v[172:175], v201 offset:17408
	ds_read_b128 v[176:179], v201 offset:18432
	ds_read_b128 v[180:183], v201 offset:19456
	ds_read_b128 v[184:187], v201 offset:20480
	ds_read_b128 v[188:191], v201 offset:21504
	ds_read_b128 v[192:195], v201 offset:22528
	ds_read_b128 v[212:215], v201 offset:23552
	global_load_lds_dwordx4 v[160:161], off
	v_lshl_add_u64 v[196:197], v[160:161], 0, s[70:71]
	s_mov_b32 m0, s14
	s_nop 0
	global_load_lds_dwordx4 v[196:197], off
	v_lshl_add_u64 v[196:197], v[160:161], 0, s[42:43]
	s_mov_b32 m0, s26
	s_nop 0
	global_load_lds_dwordx4 v[196:197], off
	v_lshl_add_u64 v[196:197], v[160:161], 0, s[48:49]
	s_mov_b32 m0, s27
	s_nop 0
	global_load_lds_dwordx4 v[196:197], off
	v_lshl_add_u64 v[196:197], s[8:9], 0, v[0:1]
	s_mov_b32 m0, s0
	v_lshl_add_u64 v[202:203], v[196:197], 0, s[70:71]
	global_load_lds_dwordx4 v[196:197], off
	s_mov_b32 m0, s1
	s_nop 0
	global_load_lds_dwordx4 v[202:203], off
	s_waitcnt vmcnt(8)
	s_waitcnt lgkmcnt(0)
	s_setprio 1
	s_barrier
	v_mfma_i32_16x16x64_i8 v[90:93], v[132:135], v[168:171], v[90:93]
	v_mfma_i32_16x16x64_i8 v[94:97], v[140:143], v[168:171], v[94:97]
	v_mfma_i32_16x16x64_i8 v[82:85], v[132:135], v[176:179], v[82:85]
	v_mfma_i32_16x16x64_i8 v[86:89], v[140:143], v[176:179], v[86:89]
	v_mfma_i32_16x16x64_i8 v[74:77], v[132:135], v[184:187], v[74:77]
	v_mfma_i32_16x16x64_i8 v[78:81], v[140:143], v[184:187], v[78:81]
	v_mfma_i32_16x16x64_i8 v[66:69], v[132:135], v[192:195], v[66:69]
	v_mfma_i32_16x16x64_i8 v[70:73], v[140:143], v[192:195], v[70:73]
	v_mfma_i32_16x16x64_i8 v[90:93], v[136:139], v[172:175], v[90:93]
	v_mfma_i32_16x16x64_i8 v[94:97], v[144:147], v[172:175], v[94:97]
	v_mfma_i32_16x16x64_i8 v[82:85], v[136:139], v[180:183], v[82:85]
	v_mfma_i32_16x16x64_i8 v[86:89], v[144:147], v[180:183], v[86:89]
	v_mfma_i32_16x16x64_i8 v[74:77], v[136:139], v[188:191], v[74:77]
	v_mfma_i32_16x16x64_i8 v[78:81], v[144:147], v[188:191], v[78:81]
	v_mfma_i32_16x16x64_i8 v[66:69], v[136:139], v[212:215], v[66:69]
	v_mfma_i32_16x16x64_i8 v[70:73], v[144:147], v[212:215], v[70:73]
	v_mfma_i32_16x16x64_i8 v[26:29], v[148:151], v[168:171], v[26:29]
	v_mfma_i32_16x16x64_i8 v[30:33], v[156:159], v[168:171], v[30:33]
	v_mfma_i32_16x16x64_i8 v[18:21], v[148:151], v[176:179], v[18:21]
	v_mfma_i32_16x16x64_i8 v[22:25], v[156:159], v[176:179], v[22:25]
	v_mfma_i32_16x16x64_i8 v[10:13], v[148:151], v[184:187], v[10:13]
	v_mfma_i32_16x16x64_i8 v[14:17], v[156:159], v[184:187], v[14:17]
	v_mfma_i32_16x16x64_i8 v[2:5], v[148:151], v[192:195], v[2:5]
	v_mfma_i32_16x16x64_i8 v[6:9], v[156:159], v[192:195], v[6:9]
	v_mfma_i32_16x16x64_i8 v[26:29], v[152:155], v[172:175], v[26:29]
	v_mfma_i32_16x16x64_i8 v[30:33], v[164:167], v[172:175], v[30:33]
	v_mfma_i32_16x16x64_i8 v[18:21], v[152:155], v[180:183], v[18:21]
	v_mfma_i32_16x16x64_i8 v[22:25], v[164:167], v[180:183], v[22:25]
	v_mfma_i32_16x16x64_i8 v[10:13], v[152:155], v[188:191], v[10:13]
	v_mfma_i32_16x16x64_i8 v[14:17], v[164:167], v[188:191], v[14:17]
	v_mfma_i32_16x16x64_i8 v[2:5], v[152:155], v[212:215], v[2:5]
	v_mfma_i32_16x16x64_i8 v[6:9], v[164:167], v[212:215], v[6:9]
	s_barrier
; #define PG8_STAGE(bufoff, gbase, unused) do { _Pragma("unroll") for (int _i = 0; _i < 2; ++_i) \
;         __builtin_amdgcn_global_load_lds((const unsigned*)((const char*)(gbase) + voff + _i * 8192), (LAS unsigned*)(lds + (bufoff) + ldsw + _i * 8192), 16, 0, 0); } while (0)
; #define PG8_LDA(dst, b, h) do { _Pragma("unroll") for (int m = 0; m < 4; ++m) _Pragma("unroll") for (int k = 0; k < 2; ++k) dst[m][k] = *(const LAS bf16x8*)(lds + PG8_SA(b, h) + aoff + m * 2048 + (FP8 ? k * 16 : k * 1024)); } while (0)
; #define PG8_LDB(dst, b, h) do { _Pragma("unroll") for (int n = 0; n < 2; ++n) _Pragma("unroll") for (int k = 0; k < 2; ++k) dst[n][k] = *(const LAS bf16x8*)(lds + PG8_SB(b, h) + boff + n * 2048 + (FP8 ? k * 16 : k * 1024)); } while (0)
; #define PG8_WAIT_V(n) asm volatile("s_waitcnt vmcnt(" #n ")" ::: "memory")
; #define PG8_WAIT_L(n) asm volatile("s_waitcnt lgkmcnt(" #n ")" ::: "memory")
; #define PG8_BAR __builtin_amdgcn_s_barrier()
; #define PG8_SCHED __builtin_amdgcn_sched_barrier(0)
; template <class Epi, class Sched, bool ALIGN_EPI, bool SP2, int MODE  >
; __device__ __forceinline__ void gemm_phase(LAS unsigned char* lds, const Gemm g, const Sched S, const Epi E, unsigned long long& probe_acc, int epi_id, int wv) {
;     ...
;             PG8_LDB(B0, 1, 0); PG8_LDB(B1, 1, 1); PG8_SCHED; PG8_LDA(At, 1, 0); PG8_STAGE(PG8_SA(0, 1), a2 + hA, voffA);
;             PG8_WAIT_V(8); PG8_WAIT_L(0); PG8_BAR; PG8_MMA(0, 0, At, B0); PG8_MMA(0, 1, At, B1); PG8_BAR; PG8_SCHED;
;             PG8_LDA(At, 1, 1); PG8_STAGE(PG8_SB(1, 0), b3, voffB); PG8_STAGE(PG8_SB(1, 1), b3 + hB, voffB); PG8_STAGE(PG8_SA(1, 0), a3, voffA);
;             PG8_WAIT_V(8); PG8_WAIT_L(0); PG8_BAR; PG8_MMA(1, 0, At, B0); PG8_MMA(1, 1, At, B1); PG8_BAR; PG8_SCHED;
;     ...
;         if constexpr (ALIGN_EPI) { if (wr == 0) PG8_BAR; }
	s_setprio 0
	v_add_u32_e32 v144, s88, v200
	v_add_u32_e32 v162, s95, v200
	ds_read_b128 v[132:135], v144
	ds_read_b128 v[136:139], v144 offset:1024
	ds_read_b128 v[140:143], v144 offset:2048
	ds_read_b128 v[144:147], v144 offset:3072
	ds_read_b128 v[148:151], v162
	ds_read_b128 v[152:155], v162 offset:1024
	ds_read_b128 v[156:159], v162 offset:2048
	ds_read_b128 v[164:167], v162 offset:3072
	s_add_u32 s8, s8, s40
	s_addc_u32 s9, s9, 0
	s_mov_b32 m0, s36
	v_lshl_add_u64 v[202:203], s[8:9], 0, v[0:1]
	ds_read_b128 v[168:171], v201 offset:32768
	ds_read_b128 v[172:175], v201 offset:33792
	ds_read_b128 v[176:179], v201 offset:34816
	ds_read_b128 v[180:183], v201 offset:35840
	ds_read_b128 v[184:187], v201 offset:36864
	ds_read_b128 v[188:191], v201 offset:37888
	ds_read_b128 v[192:195], v201 offset:38912
	ds_read_b128 v[212:215], v201 offset:39936
	global_load_lds_dwordx4 v[202:203], off
	v_lshl_add_u64 v[202:203], v[202:203], 0, s[70:71]
	s_mov_b32 m0, s37
	s_nop 0
	global_load_lds_dwordx4 v[202:203], off
	s_waitcnt vmcnt(8)
	s_waitcnt lgkmcnt(0)
	s_setprio 1
	s_barrier
	v_mfma_i32_16x16x64_i8 v[122:125], v[132:135], v[168:171], v[122:125]
	v_mfma_i32_16x16x64_i8 v[126:129], v[140:143], v[168:171], v[126:129]
	v_mfma_i32_16x16x64_i8 v[114:117], v[132:135], v[176:179], v[114:117]
	v_mfma_i32_16x16x64_i8 v[118:121], v[140:143], v[176:179], v[118:121]
	v_mfma_i32_16x16x64_i8 v[106:109], v[132:135], v[184:187], v[106:109]
	v_mfma_i32_16x16x64_i8 v[110:113], v[140:143], v[184:187], v[110:113]
	v_mfma_i32_16x16x64_i8 v[98:101], v[132:135], v[192:195], v[98:101]
	v_mfma_i32_16x16x64_i8 v[102:105], v[140:143], v[192:195], v[102:105]
	v_mfma_i32_16x16x64_i8 v[122:125], v[136:139], v[172:175], v[122:125]
	v_mfma_i32_16x16x64_i8 v[126:129], v[144:147], v[172:175], v[126:129]
	v_mfma_i32_16x16x64_i8 v[114:117], v[136:139], v[180:183], v[114:117]
	v_mfma_i32_16x16x64_i8 v[118:121], v[144:147], v[180:183], v[118:121]
	v_mfma_i32_16x16x64_i8 v[106:109], v[136:139], v[188:191], v[106:109]
	v_mfma_i32_16x16x64_i8 v[110:113], v[144:147], v[188:191], v[110:113]
	v_mfma_i32_16x16x64_i8 v[98:101], v[136:139], v[212:215], v[98:101]
	v_mfma_i32_16x16x64_i8 v[102:105], v[144:147], v[212:215], v[102:105]
	v_mfma_i32_16x16x64_i8 v[58:61], v[148:151], v[168:171], v[58:61]
	v_mfma_i32_16x16x64_i8 v[62:65], v[156:159], v[168:171], v[62:65]
	v_mfma_i32_16x16x64_i8 v[50:53], v[148:151], v[176:179], v[50:53]
	v_mfma_i32_16x16x64_i8 v[54:57], v[156:159], v[176:179], v[54:57]
	v_mfma_i32_16x16x64_i8 v[42:45], v[148:151], v[184:187], v[42:45]
	v_mfma_i32_16x16x64_i8 v[46:49], v[156:159], v[184:187], v[46:49]
	v_mfma_i32_16x16x64_i8 v[34:37], v[148:151], v[192:195], v[34:37]
	v_mfma_i32_16x16x64_i8 v[38:41], v[156:159], v[192:195], v[38:41]
	v_mfma_i32_16x16x64_i8 v[58:61], v[152:155], v[172:175], v[58:61]
	v_mfma_i32_16x16x64_i8 v[62:65], v[164:167], v[172:175], v[62:65]
	v_mfma_i32_16x16x64_i8 v[50:53], v[152:155], v[180:183], v[50:53]
	v_mfma_i32_16x16x64_i8 v[54:57], v[164:167], v[180:183], v[54:57]
	v_mfma_i32_16x16x64_i8 v[42:45], v[152:155], v[188:191], v[42:45]
	v_mfma_i32_16x16x64_i8 v[46:49], v[164:167], v[188:191], v[46:49]
	v_mfma_i32_16x16x64_i8 v[34:37], v[152:155], v[212:215], v[34:37]
	v_mfma_i32_16x16x64_i8 v[38:41], v[164:167], v[212:215], v[38:41]
	s_barrier
	s_setprio 0
	s_mov_b32 m0, s89
	v_lshl_add_u64 v[202:203], v[160:161], 0, s[76:77]
	ds_read_b128 v[168:171], v201 offset:49152
	ds_read_b128 v[172:175], v201 offset:50176
	ds_read_b128 v[176:179], v201 offset:51200
	ds_read_b128 v[180:183], v201 offset:52224
	ds_read_b128 v[184:187], v201 offset:53248
	ds_read_b128 v[188:191], v201 offset:54272
	ds_read_b128 v[192:195], v201 offset:55296
	ds_read_b128 v[212:215], v201 offset:56320
	global_load_lds_dwordx4 v[202:203], off
	v_lshl_add_u64 v[202:203], v[160:161], 0, s[78:79]
	s_mov_b32 m0, s92
	s_nop 0
	global_load_lds_dwordx4 v[202:203], off
	v_lshl_add_u64 v[202:203], v[160:161], 0, s[44:45]
	s_mov_b32 m0, s84
	v_lshl_add_u64 v[160:161], v[160:161], 0, s[56:57]
	global_load_lds_dwordx4 v[202:203], off
	s_mov_b32 m0, s12
	s_nop 0
	global_load_lds_dwordx4 v[160:161], off
	v_lshl_add_u64 v[160:161], v[196:197], 0, s[76:77]
	s_mov_b32 m0, s93
	s_nop 0
	global_load_lds_dwordx4 v[160:161], off
	v_lshl_add_u64 v[160:161], v[196:197], 0, s[78:79]
	s_mov_b32 m0, s94
	s_nop 0
	global_load_lds_dwordx4 v[160:161], off
	s_waitcnt vmcnt(8)
	s_waitcnt lgkmcnt(0)
	s_setprio 1
	s_barrier
	v_mfma_i32_16x16x64_i8 v[90:93], v[132:135], v[168:171], v[90:93]
	v_mfma_i32_16x16x64_i8 v[94:97], v[140:143], v[168:171], v[94:97]
	v_mfma_i32_16x16x64_i8 v[82:85], v[132:135], v[176:179], v[82:85]
	v_mfma_i32_16x16x64_i8 v[86:89], v[140:143], v[176:179], v[86:89]
	v_mfma_i32_16x16x64_i8 v[74:77], v[132:135], v[184:187], v[74:77]
	v_mfma_i32_16x16x64_i8 v[78:81], v[140:143], v[184:187], v[78:81]
	v_mfma_i32_16x16x64_i8 v[66:69], v[132:135], v[192:195], v[66:69]
	v_mfma_i32_16x16x64_i8 v[70:73], v[140:143], v[192:195], v[70:73]
	v_mfma_i32_16x16x64_i8 v[90:93], v[136:139], v[172:175], v[90:93]
	v_mfma_i32_16x16x64_i8 v[94:97], v[144:147], v[172:175], v[94:97]
	v_mfma_i32_16x16x64_i8 v[82:85], v[136:139], v[180:183], v[82:85]
	v_mfma_i32_16x16x64_i8 v[86:89], v[144:147], v[180:183], v[86:89]
	v_mfma_i32_16x16x64_i8 v[74:77], v[136:139], v[188:191], v[74:77]
	v_mfma_i32_16x16x64_i8 v[78:81], v[144:147], v[188:191], v[78:81]
	v_mfma_i32_16x16x64_i8 v[66:69], v[136:139], v[212:215], v[66:69]
	v_mfma_i32_16x16x64_i8 v[70:73], v[144:147], v[212:215], v[70:73]
	v_mfma_i32_16x16x64_i8 v[26:29], v[148:151], v[168:171], v[26:29]
	v_mfma_i32_16x16x64_i8 v[30:33], v[156:159], v[168:171], v[30:33]
	v_mfma_i32_16x16x64_i8 v[18:21], v[148:151], v[176:179], v[18:21]
	v_mfma_i32_16x16x64_i8 v[22:25], v[156:159], v[176:179], v[22:25]
	v_mfma_i32_16x16x64_i8 v[10:13], v[148:151], v[184:187], v[10:13]
	v_mfma_i32_16x16x64_i8 v[14:17], v[156:159], v[184:187], v[14:17]
	v_mfma_i32_16x16x64_i8 v[2:5], v[148:151], v[192:195], v[2:5]
	v_mfma_i32_16x16x64_i8 v[6:9], v[156:159], v[192:195], v[6:9]
	v_mfma_i32_16x16x64_i8 v[26:29], v[152:155], v[172:175], v[26:29]
	v_mfma_i32_16x16x64_i8 v[30:33], v[164:167], v[172:175], v[30:33]
	v_mfma_i32_16x16x64_i8 v[18:21], v[152:155], v[180:183], v[18:21]
	v_mfma_i32_16x16x64_i8 v[22:25], v[164:167], v[180:183], v[22:25]
	v_mfma_i32_16x16x64_i8 v[10:13], v[152:155], v[188:191], v[10:13]
	v_mfma_i32_16x16x64_i8 v[14:17], v[164:167], v[188:191], v[14:17]
	v_mfma_i32_16x16x64_i8 v[2:5], v[152:155], v[212:215], v[2:5]
	v_mfma_i32_16x16x64_i8 v[6:9], v[164:167], v[212:215], v[6:9]
	s_barrier
	s_setprio 0
	s_add_i32 s34, s34, 2
	s_add_u32 s6, s6, 0x8000
	s_addc_u32 s7, s7, 0
	s_cmp_gt_u32 s34, 41
	s_cbranch_scc0 .LBB0_1154
	v_readlane_b32 s4, v255, 34
	v_readlane_b32 s5, v255, 35
	s_and_b64 vcc, exec, s[4:5]
	s_cbranch_vccz .LBB0_1157
	s_barrier
